# all GEMM K-loops: s_setprio 1 moved before the barrier that opens each MFMA block (on top of HG3 og hoist and FOXIN LDS tables)
# baseline (speedup 1.0000x reference)
.LBB0_150:
	ds_read_b128 v[48:51], v214
	ds_read_b128 v[52:55], v214 offset:1024
	ds_read_b128 v[56:59], v214 offset:2048
	ds_read_b128 v[60:63], v214 offset:3072
	ds_read_b128 v[168:171], v215
	ds_read_b128 v[172:175], v215 offset:1024
	ds_read_b128 v[176:179], v215 offset:2048
	ds_read_b128 v[180:183], v215 offset:3072
	s_add_u32 s4, s2, 0xfffc0080
	s_addc_u32 s5, s3, -1
	s_cmp_eq_u32 s89, 12
	s_cselect_b32 s7, s8, s5
	s_cselect_b32 s6, s9, s4
	s_cselect_b32 s5, s79, s88
	s_cselect_b32 s4, s81, s87
	v_lshl_add_u64 v[212:213], s[2:3], 0, v[158:159]
	s_add_i32 m0, s68, 0xc000
	ds_read_b128 v[184:187], v216
	ds_read_b128 v[188:191], v216 offset:1024
	ds_read_b128 v[192:195], v216 offset:2048
	ds_read_b128 v[196:199], v216 offset:3072
	ds_read_b128 v[200:203], v216 offset:4096
	ds_read_b128 v[204:207], v216 offset:5120
	ds_read_b128 v[208:211], v216 offset:6144
	ds_read_b128 v[220:223], v216 offset:7168
	global_load_lds_dwordx4 v[212:213], off
	v_lshl_add_u64 v[212:213], s[2:3], 0, v[160:161]
	s_add_i32 m0, s68, 0xe000
	s_nop 0
	global_load_lds_dwordx4 v[212:213], off
	s_waitcnt vmcnt(8)
	s_waitcnt lgkmcnt(0)
	s_setprio 1
	s_barrier
	s_waitcnt lgkmcnt(0)
	v_mfma_f32_16x16x32_bf16 v[140:143], v[48:51], v[184:187], v[140:143]
	v_mfma_f32_16x16x32_bf16 v[136:139], v[56:59], v[184:187], v[136:139]
	v_mfma_f32_16x16x32_bf16 v[124:127], v[48:51], v[192:195], v[124:127]
	v_mfma_f32_16x16x32_bf16 v[120:123], v[56:59], v[192:195], v[120:123]
	v_mfma_f32_16x16x32_bf16 v[108:111], v[48:51], v[200:203], v[108:111]
	v_mfma_f32_16x16x32_bf16 v[104:107], v[56:59], v[200:203], v[104:107]
	v_mfma_f32_16x16x32_bf16 v[92:95], v[48:51], v[208:211], v[92:95]
	v_mfma_f32_16x16x32_bf16 v[88:91], v[56:59], v[208:211], v[88:91]
	v_mfma_f32_16x16x32_bf16 v[140:143], v[52:55], v[188:191], v[140:143]
	v_mfma_f32_16x16x32_bf16 v[136:139], v[60:63], v[188:191], v[136:139]
	v_mfma_f32_16x16x32_bf16 v[124:127], v[52:55], v[196:199], v[124:127]
	v_mfma_f32_16x16x32_bf16 v[120:123], v[60:63], v[196:199], v[120:123]
	v_mfma_f32_16x16x32_bf16 v[108:111], v[52:55], v[204:207], v[108:111]
	v_mfma_f32_16x16x32_bf16 v[104:107], v[60:63], v[204:207], v[104:107]
	v_mfma_f32_16x16x32_bf16 v[92:95], v[52:55], v[220:223], v[92:95]
	v_mfma_f32_16x16x32_bf16 v[88:91], v[60:63], v[220:223], v[88:91]
	s_setprio 0
	s_setprio 1
	v_mfma_f32_16x16x32_bf16 v[132:135], v[168:171], v[184:187], v[132:135]
	v_mfma_f32_16x16x32_bf16 v[128:131], v[176:179], v[184:187], v[128:131]
	v_mfma_f32_16x16x32_bf16 v[116:119], v[168:171], v[192:195], v[116:119]
	v_mfma_f32_16x16x32_bf16 v[112:115], v[176:179], v[192:195], v[112:115]
	v_mfma_f32_16x16x32_bf16 v[100:103], v[168:171], v[200:203], v[100:103]
	v_mfma_f32_16x16x32_bf16 v[96:99], v[176:179], v[200:203], v[96:99]
	v_mfma_f32_16x16x32_bf16 v[84:87], v[168:171], v[208:211], v[84:87]
	v_mfma_f32_16x16x32_bf16 v[80:83], v[176:179], v[208:211], v[80:83]
	v_mfma_f32_16x16x32_bf16 v[132:135], v[172:175], v[188:191], v[132:135]
	v_mfma_f32_16x16x32_bf16 v[128:131], v[180:183], v[188:191], v[128:131]
	v_mfma_f32_16x16x32_bf16 v[116:119], v[172:175], v[196:199], v[116:119]
	v_mfma_f32_16x16x32_bf16 v[112:115], v[180:183], v[196:199], v[112:115]
	v_mfma_f32_16x16x32_bf16 v[100:103], v[172:175], v[204:207], v[100:103]
	v_mfma_f32_16x16x32_bf16 v[96:99], v[180:183], v[204:207], v[96:99]
	v_mfma_f32_16x16x32_bf16 v[84:87], v[172:175], v[220:223], v[84:87]
	v_mfma_f32_16x16x32_bf16 v[80:83], v[180:183], v[220:223], v[80:83]
	s_setprio 0
	s_barrier
	s_add_i32 s90, s72, s61
	v_lshl_add_u64 v[212:213], s[4:5], 0, v[146:147]
	s_mov_b32 m0, s90
	ds_read_b128 v[184:187], v216 offset:16384
	ds_read_b128 v[188:191], v216 offset:17408
	ds_read_b128 v[192:195], v216 offset:18432
	ds_read_b128 v[196:199], v216 offset:19456
	ds_read_b128 v[200:203], v216 offset:20480
	ds_read_b128 v[204:207], v216 offset:21504
	ds_read_b128 v[208:211], v216 offset:22528
	ds_read_b128 v[220:223], v216 offset:23552
	global_load_lds_dwordx4 v[212:213], off
	s_add_i32 m0, s90, 0x2000
	s_add_u32 s90, s4, 0x40000
	v_lshl_add_u64 v[224:225], s[4:5], 0, v[150:151]
	s_addc_u32 s91, s5, 0
	s_add_i32 s93, s73, s61
	global_load_lds_dwordx4 v[224:225], off
	v_lshl_add_u64 v[226:227], s[90:91], 0, v[146:147]
	s_mov_b32 m0, s93
	v_lshl_add_u64 v[228:229], s[6:7], 0, v[148:149]
	global_load_lds_dwordx4 v[226:227], off
	v_lshl_add_u64 v[226:227], s[90:91], 0, v[150:151]
	s_add_i32 m0, s93, 0x2000
	s_nop 0
	global_load_lds_dwordx4 v[226:227], off
	v_lshl_add_u64 v[226:227], s[6:7], 0, v[144:145]
	s_mov_b32 m0, s68
	s_nop 0
	global_load_lds_dwordx4 v[226:227], off
	s_mov_b32 m0, s69
	s_nop 0
	global_load_lds_dwordx4 v[228:229], off
	s_waitcnt vmcnt(8)
	s_waitcnt lgkmcnt(0)
	s_setprio 1
	s_barrier
	s_waitcnt lgkmcnt(0)
	v_mfma_f32_16x16x32_bf16 v[76:79], v[48:51], v[184:187], v[76:79]
	v_mfma_f32_16x16x32_bf16 v[72:75], v[56:59], v[184:187], v[72:75]
	v_mfma_f32_16x16x32_bf16 v[44:47], v[48:51], v[192:195], v[44:47]
	v_mfma_f32_16x16x32_bf16 v[40:43], v[56:59], v[192:195], v[40:43]
	v_mfma_f32_16x16x32_bf16 v[28:31], v[48:51], v[200:203], v[28:31]
	v_mfma_f32_16x16x32_bf16 v[24:27], v[56:59], v[200:203], v[24:27]
	v_mfma_f32_16x16x32_bf16 v[12:15], v[48:51], v[208:211], v[12:15]
	v_mfma_f32_16x16x32_bf16 v[8:11], v[56:59], v[208:211], v[8:11]
	v_mfma_f32_16x16x32_bf16 v[76:79], v[52:55], v[188:191], v[76:79]
	v_mfma_f32_16x16x32_bf16 v[72:75], v[60:63], v[188:191], v[72:75]
	v_mfma_f32_16x16x32_bf16 v[44:47], v[52:55], v[196:199], v[44:47]
	v_mfma_f32_16x16x32_bf16 v[40:43], v[60:63], v[196:199], v[40:43]
	v_mfma_f32_16x16x32_bf16 v[28:31], v[52:55], v[204:207], v[28:31]
	v_mfma_f32_16x16x32_bf16 v[24:27], v[60:63], v[204:207], v[24:27]
	v_mfma_f32_16x16x32_bf16 v[12:15], v[52:55], v[220:223], v[12:15]
	v_mfma_f32_16x16x32_bf16 v[8:11], v[60:63], v[220:223], v[8:11]
	s_setprio 0
	s_setprio 1
	v_mfma_f32_16x16x32_bf16 v[36:39], v[168:171], v[192:195], v[36:39]
	v_mfma_f32_16x16x32_bf16 v[32:35], v[176:179], v[192:195], v[32:35]
	v_mfma_f32_16x16x32_bf16 v[20:23], v[168:171], v[200:203], v[20:23]
	v_mfma_f32_16x16x32_bf16 v[16:19], v[176:179], v[200:203], v[16:19]
	v_mfma_f32_16x16x32_bf16 v[4:7], v[168:171], v[208:211], v[4:7]
	v_mfma_f32_16x16x32_bf16 v[0:3], v[176:179], v[208:211], v[0:3]
	v_mfma_f32_16x16x32_bf16 v[48:51], v[168:171], v[184:187], v[68:71]
	v_mfma_f32_16x16x32_bf16 v[52:55], v[176:179], v[184:187], v[64:67]
	v_mfma_f32_16x16x32_bf16 v[36:39], v[172:175], v[196:199], v[36:39]
	v_mfma_f32_16x16x32_bf16 v[32:35], v[180:183], v[196:199], v[32:35]
	v_mfma_f32_16x16x32_bf16 v[20:23], v[172:175], v[204:207], v[20:23]
	v_mfma_f32_16x16x32_bf16 v[16:19], v[180:183], v[204:207], v[16:19]
	v_mfma_f32_16x16x32_bf16 v[4:7], v[172:175], v[220:223], v[4:7]
	v_mfma_f32_16x16x32_bf16 v[0:3], v[180:183], v[220:223], v[0:3]
	v_mfma_f32_16x16x32_bf16 v[48:51], v[172:175], v[188:191], v[48:51]
	v_mfma_f32_16x16x32_bf16 v[52:55], v[180:183], v[188:191], v[52:55]
	s_setprio 0
	s_barrier
	s_add_i32 s90, 0, 0x18000
	s_add_i32 s91, 0, 0x1c000
	v_add_u32_e32 v68, s90, v167
	v_add_u32_e32 v154, s91, v167
	ds_read_b128 v[56:59], v68
	ds_read_b128 v[60:63], v68 offset:1024
	ds_read_b128 v[64:67], v68 offset:2048
	ds_read_b128 v[68:71], v68 offset:3072
	ds_read_b128 v[168:171], v154
	ds_read_b128 v[172:175], v154 offset:1024
	ds_read_b128 v[176:179], v154 offset:2048
	ds_read_b128 v[180:183], v154 offset:3072
	s_add_u32 s6, s6, 0x40000
	s_addc_u32 s7, s7, 0
	s_mov_b32 m0, s70
	v_lshl_add_u64 v[230:231], s[6:7], 0, v[144:145]
	ds_read_b128 v[184:187], v216 offset:32768
	ds_read_b128 v[188:191], v216 offset:33792
	ds_read_b128 v[192:195], v216 offset:34816
	ds_read_b128 v[196:199], v216 offset:35840
	ds_read_b128 v[200:203], v216 offset:36864
	ds_read_b128 v[204:207], v216 offset:37888
	ds_read_b128 v[208:211], v216 offset:38912
	ds_read_b128 v[220:223], v216 offset:39936
	global_load_lds_dwordx4 v[230:231], off
	v_lshl_add_u64 v[230:231], s[6:7], 0, v[148:149]
	s_mov_b32 m0, s77
	s_nop 0
	global_load_lds_dwordx4 v[230:231], off
	s_waitcnt vmcnt(8)
	s_waitcnt lgkmcnt(0)
	s_setprio 1
	s_barrier
	s_waitcnt lgkmcnt(0)
	v_mfma_f32_16x16x32_bf16 v[140:143], v[56:59], v[184:187], v[140:143]
	v_mfma_f32_16x16x32_bf16 v[136:139], v[64:67], v[184:187], v[136:139]
	v_mfma_f32_16x16x32_bf16 v[124:127], v[56:59], v[192:195], v[124:127]
	v_mfma_f32_16x16x32_bf16 v[120:123], v[64:67], v[192:195], v[120:123]
	v_mfma_f32_16x16x32_bf16 v[108:111], v[56:59], v[200:203], v[108:111]
	v_mfma_f32_16x16x32_bf16 v[104:107], v[64:67], v[200:203], v[104:107]
	v_mfma_f32_16x16x32_bf16 v[92:95], v[56:59], v[208:211], v[92:95]
	v_mfma_f32_16x16x32_bf16 v[88:91], v[64:67], v[208:211], v[88:91]
	v_mfma_f32_16x16x32_bf16 v[140:143], v[60:63], v[188:191], v[140:143]
	v_mfma_f32_16x16x32_bf16 v[136:139], v[68:71], v[188:191], v[136:139]
	v_mfma_f32_16x16x32_bf16 v[124:127], v[60:63], v[196:199], v[124:127]
	v_mfma_f32_16x16x32_bf16 v[120:123], v[68:71], v[196:199], v[120:123]
	v_mfma_f32_16x16x32_bf16 v[108:111], v[60:63], v[204:207], v[108:111]
	v_mfma_f32_16x16x32_bf16 v[104:107], v[68:71], v[204:207], v[104:107]
	v_mfma_f32_16x16x32_bf16 v[92:95], v[60:63], v[220:223], v[92:95]
	v_mfma_f32_16x16x32_bf16 v[88:91], v[68:71], v[220:223], v[88:91]
	s_setprio 0
	s_setprio 1
	v_mfma_f32_16x16x32_bf16 v[132:135], v[168:171], v[184:187], v[132:135]
	v_mfma_f32_16x16x32_bf16 v[128:131], v[176:179], v[184:187], v[128:131]
	v_mfma_f32_16x16x32_bf16 v[116:119], v[168:171], v[192:195], v[116:119]
	v_mfma_f32_16x16x32_bf16 v[112:115], v[176:179], v[192:195], v[112:115]
	v_mfma_f32_16x16x32_bf16 v[100:103], v[168:171], v[200:203], v[100:103]
	v_mfma_f32_16x16x32_bf16 v[96:99], v[176:179], v[200:203], v[96:99]
	v_mfma_f32_16x16x32_bf16 v[84:87], v[168:171], v[208:211], v[84:87]
	v_mfma_f32_16x16x32_bf16 v[80:83], v[176:179], v[208:211], v[80:83]
	v_mfma_f32_16x16x32_bf16 v[132:135], v[172:175], v[188:191], v[132:135]
	v_mfma_f32_16x16x32_bf16 v[128:131], v[180:183], v[188:191], v[128:131]
	v_mfma_f32_16x16x32_bf16 v[116:119], v[172:175], v[196:199], v[116:119]
	v_mfma_f32_16x16x32_bf16 v[112:115], v[180:183], v[196:199], v[112:115]
	v_mfma_f32_16x16x32_bf16 v[100:103], v[172:175], v[204:207], v[100:103]
	v_mfma_f32_16x16x32_bf16 v[96:99], v[180:183], v[204:207], v[96:99]
	v_mfma_f32_16x16x32_bf16 v[84:87], v[172:175], v[220:223], v[84:87]
	v_mfma_f32_16x16x32_bf16 v[80:83], v[180:183], v[220:223], v[80:83]
	s_setprio 0
	s_barrier
	s_add_i32 s6, s90, s61
	v_lshl_add_u64 v[212:213], v[212:213], 0, s[56:57]
	s_mov_b32 m0, s6
	ds_read_b128 v[184:187], v216 offset:49152
	ds_read_b128 v[188:191], v216 offset:50176
	ds_read_b128 v[192:195], v216 offset:51200
	ds_read_b128 v[196:199], v216 offset:52224
	ds_read_b128 v[200:203], v216 offset:53248
	ds_read_b128 v[204:207], v216 offset:54272
	ds_read_b128 v[208:211], v216 offset:55296
	ds_read_b128 v[220:223], v216 offset:56320
	global_load_lds_dwordx4 v[212:213], off
	s_add_i32 m0, s6, 0x2000
	s_add_u32 s4, s4, 0x40080
	v_lshl_add_u64 v[212:213], v[224:225], 0, s[56:57]
	s_addc_u32 s5, s5, 0
	s_add_i32 s6, s91, s61
	global_load_lds_dwordx4 v[212:213], off
	v_lshl_add_u64 v[212:213], s[4:5], 0, v[146:147]
	s_mov_b32 m0, s6
	s_nop 0
	global_load_lds_dwordx4 v[212:213], off
	v_lshl_add_u64 v[212:213], s[4:5], 0, v[150:151]
	s_add_i32 m0, s6, 0x2000
	s_nop 0
	global_load_lds_dwordx4 v[212:213], off
	v_lshl_add_u64 v[212:213], v[226:227], 0, s[56:57]
	s_mov_b32 m0, s96
	s_nop 0
	global_load_lds_dwordx4 v[212:213], off
	v_lshl_add_u64 v[212:213], v[228:229], 0, s[56:57]
	s_mov_b32 m0, s71
	s_nop 0
	global_load_lds_dwordx4 v[212:213], off
	s_waitcnt vmcnt(8)
	s_waitcnt lgkmcnt(0)
	s_setprio 1
	s_barrier
	s_waitcnt lgkmcnt(0)
	v_mfma_f32_16x16x32_bf16 v[76:79], v[56:59], v[184:187], v[76:79]
	v_mfma_f32_16x16x32_bf16 v[72:75], v[64:67], v[184:187], v[72:75]
	v_mfma_f32_16x16x32_bf16 v[44:47], v[56:59], v[192:195], v[44:47]
	v_mfma_f32_16x16x32_bf16 v[40:43], v[64:67], v[192:195], v[40:43]
	v_mfma_f32_16x16x32_bf16 v[28:31], v[56:59], v[200:203], v[28:31]
	v_mfma_f32_16x16x32_bf16 v[24:27], v[64:67], v[200:203], v[24:27]
	v_mfma_f32_16x16x32_bf16 v[12:15], v[56:59], v[208:211], v[12:15]
	v_mfma_f32_16x16x32_bf16 v[8:11], v[64:67], v[208:211], v[8:11]
	v_mfma_f32_16x16x32_bf16 v[76:79], v[60:63], v[188:191], v[76:79]
	v_mfma_f32_16x16x32_bf16 v[72:75], v[68:71], v[188:191], v[72:75]
	v_mfma_f32_16x16x32_bf16 v[44:47], v[60:63], v[196:199], v[44:47]
	v_mfma_f32_16x16x32_bf16 v[40:43], v[68:71], v[196:199], v[40:43]
	v_mfma_f32_16x16x32_bf16 v[28:31], v[60:63], v[204:207], v[28:31]
	v_mfma_f32_16x16x32_bf16 v[24:27], v[68:71], v[204:207], v[24:27]
	v_mfma_f32_16x16x32_bf16 v[12:15], v[60:63], v[220:223], v[12:15]
	v_mfma_f32_16x16x32_bf16 v[8:11], v[68:71], v[220:223], v[8:11]
	s_setprio 0
	s_setprio 1
	v_mfma_f32_16x16x32_bf16 v[48:51], v[168:171], v[184:187], v[48:51]
	v_mfma_f32_16x16x32_bf16 v[68:71], v[172:175], v[188:191], v[48:51]
	v_mfma_f32_16x16x32_bf16 v[48:51], v[176:179], v[184:187], v[52:55]
	v_mfma_f32_16x16x32_bf16 v[36:39], v[168:171], v[192:195], v[36:39]
	v_mfma_f32_16x16x32_bf16 v[32:35], v[176:179], v[192:195], v[32:35]
	v_mfma_f32_16x16x32_bf16 v[20:23], v[168:171], v[200:203], v[20:23]
	v_mfma_f32_16x16x32_bf16 v[16:19], v[176:179], v[200:203], v[16:19]
	v_mfma_f32_16x16x32_bf16 v[4:7], v[168:171], v[208:211], v[4:7]
	v_mfma_f32_16x16x32_bf16 v[0:3], v[176:179], v[208:211], v[0:3]
	v_mfma_f32_16x16x32_bf16 v[64:67], v[180:183], v[188:191], v[48:51]
	v_mfma_f32_16x16x32_bf16 v[36:39], v[172:175], v[196:199], v[36:39]
	v_mfma_f32_16x16x32_bf16 v[32:35], v[180:183], v[196:199], v[32:35]
	v_mfma_f32_16x16x32_bf16 v[20:23], v[172:175], v[204:207], v[20:23]
	v_mfma_f32_16x16x32_bf16 v[16:19], v[180:183], v[204:207], v[16:19]
	v_mfma_f32_16x16x32_bf16 v[4:7], v[172:175], v[220:223], v[4:7]
	v_mfma_f32_16x16x32_bf16 v[0:3], v[180:183], v[220:223], v[0:3]
	s_setprio 0
	s_barrier
	s_add_i32 s89, s89, 2
	s_add_u32 s2, s2, 0x100
	s_addc_u32 s3, s3, 0
	s_add_u32 s87, s87, 0x100
	s_addc_u32 s88, s88, 0
	s_cmp_gt_u32 s89, 13
	s_cbranch_scc0 .LBB0_150
	s_and_b64 vcc, exec, s[58:59]
	s_cbranch_vccz .LBB0_153
	s_barrier

.LBB0_741:
	ds_read_b128 v[128:131], v187
	ds_read_b128 v[132:135], v187 offset:1024
	ds_read_b128 v[136:139], v187 offset:2048
	ds_read_b128 v[140:143], v187 offset:3072
	ds_read_b128 v[144:147], v188
	ds_read_b128 v[148:151], v188 offset:1024
	ds_read_b128 v[168:171], v188 offset:2048
	ds_read_b128 v[172:175], v188 offset:3072
	s_add_u32 s58, s52, 0xfffc0080
	s_addc_u32 s59, s53, -1
	s_cmp_eq_u32 s83, 12
	s_cselect_b32 s61, s6, s59
	s_cselect_b32 s60, s11, s58
	s_cselect_b32 s59, s13, s82
	s_cselect_b32 s58, s80, s81
	v_lshl_add_u64 v[216:217], s[52:53], 0, v[160:161]
	s_add_i32 m0, s62, 0xc000
	ds_read_b128 v[176:179], v189
	ds_read_b128 v[180:183], v189 offset:1024
	ds_read_b128 v[192:195], v189 offset:2048
	ds_read_b128 v[196:199], v189 offset:3072
	ds_read_b128 v[200:203], v189 offset:4096
	ds_read_b128 v[204:207], v189 offset:5120
	ds_read_b128 v[208:211], v189 offset:6144
	ds_read_b128 v[212:215], v189 offset:7168
	global_load_lds_dwordx4 v[216:217], off
	v_lshl_add_u64 v[216:217], s[52:53], 0, v[162:163]
	s_add_i32 m0, s62, 0xe000
	s_nop 0
	global_load_lds_dwordx4 v[216:217], off
	s_waitcnt vmcnt(8)
	s_waitcnt lgkmcnt(0)
	s_setprio 1
	s_barrier
	s_waitcnt lgkmcnt(0)
	v_mfma_f32_16x16x32_bf16 v[124:127], v[128:131], v[176:179], v[124:127]
	v_mfma_f32_16x16x32_bf16 v[120:123], v[136:139], v[176:179], v[120:123]
	v_mfma_f32_16x16x32_bf16 v[108:111], v[128:131], v[192:195], v[108:111]
	v_mfma_f32_16x16x32_bf16 v[104:107], v[136:139], v[192:195], v[104:107]
	v_mfma_f32_16x16x32_bf16 v[92:95], v[128:131], v[200:203], v[92:95]
	v_mfma_f32_16x16x32_bf16 v[88:91], v[136:139], v[200:203], v[88:91]
	v_mfma_f32_16x16x32_bf16 v[76:79], v[128:131], v[208:211], v[76:79]
	v_mfma_f32_16x16x32_bf16 v[72:75], v[136:139], v[208:211], v[72:75]
	v_mfma_f32_16x16x32_bf16 v[124:127], v[132:135], v[180:183], v[124:127]
	v_mfma_f32_16x16x32_bf16 v[120:123], v[140:143], v[180:183], v[120:123]
	v_mfma_f32_16x16x32_bf16 v[108:111], v[132:135], v[196:199], v[108:111]
	v_mfma_f32_16x16x32_bf16 v[104:107], v[140:143], v[196:199], v[104:107]
	v_mfma_f32_16x16x32_bf16 v[92:95], v[132:135], v[204:207], v[92:95]
	v_mfma_f32_16x16x32_bf16 v[88:91], v[140:143], v[204:207], v[88:91]
	v_mfma_f32_16x16x32_bf16 v[76:79], v[132:135], v[212:215], v[76:79]
	v_mfma_f32_16x16x32_bf16 v[72:75], v[140:143], v[212:215], v[72:75]
	s_setprio 0
	s_setprio 1
	v_mfma_f32_16x16x32_bf16 v[116:119], v[144:147], v[176:179], v[116:119]
	v_mfma_f32_16x16x32_bf16 v[112:115], v[168:171], v[176:179], v[112:115]
	v_mfma_f32_16x16x32_bf16 v[100:103], v[144:147], v[192:195], v[100:103]
	v_mfma_f32_16x16x32_bf16 v[96:99], v[168:171], v[192:195], v[96:99]
	v_mfma_f32_16x16x32_bf16 v[84:87], v[144:147], v[200:203], v[84:87]
	v_mfma_f32_16x16x32_bf16 v[80:83], v[168:171], v[200:203], v[80:83]
	v_mfma_f32_16x16x32_bf16 v[68:71], v[144:147], v[208:211], v[68:71]
	v_mfma_f32_16x16x32_bf16 v[64:67], v[168:171], v[208:211], v[64:67]
	v_mfma_f32_16x16x32_bf16 v[116:119], v[148:151], v[180:183], v[116:119]
	v_mfma_f32_16x16x32_bf16 v[112:115], v[172:175], v[180:183], v[112:115]
	v_mfma_f32_16x16x32_bf16 v[100:103], v[148:151], v[196:199], v[100:103]
	v_mfma_f32_16x16x32_bf16 v[96:99], v[172:175], v[196:199], v[96:99]
	v_mfma_f32_16x16x32_bf16 v[84:87], v[148:151], v[204:207], v[84:87]
	v_mfma_f32_16x16x32_bf16 v[80:83], v[172:175], v[204:207], v[80:83]
	v_mfma_f32_16x16x32_bf16 v[68:71], v[148:151], v[212:215], v[68:71]
	v_mfma_f32_16x16x32_bf16 v[64:67], v[172:175], v[212:215], v[64:67]
	s_setprio 0
	s_barrier
	s_add_i32 s84, s71, s57
	v_lshl_add_u64 v[216:217], s[58:59], 0, v[154:155]
	s_mov_b32 m0, s84
	ds_read_b128 v[176:179], v189 offset:16384
	ds_read_b128 v[180:183], v189 offset:17408
	ds_read_b128 v[192:195], v189 offset:18432
	ds_read_b128 v[196:199], v189 offset:19456
	ds_read_b128 v[200:203], v189 offset:20480
	ds_read_b128 v[204:207], v189 offset:21504
	ds_read_b128 v[208:211], v189 offset:22528
	ds_read_b128 v[212:215], v189 offset:23552
	global_load_lds_dwordx4 v[216:217], off
	s_add_i32 m0, s84, 0x2000
	s_add_u32 s84, s58, 0x40000
	v_lshl_add_u64 v[218:219], s[58:59], 0, v[158:159]
	s_addc_u32 s85, s59, 0
	s_add_i32 s86, s72, s57
	global_load_lds_dwordx4 v[218:219], off
	v_lshl_add_u64 v[220:221], s[84:85], 0, v[154:155]
	s_mov_b32 m0, s86
	v_lshl_add_u64 v[222:223], s[60:61], 0, v[156:157]
	global_load_lds_dwordx4 v[220:221], off
	v_lshl_add_u64 v[220:221], s[84:85], 0, v[158:159]
	s_add_i32 m0, s86, 0x2000
	s_nop 0
	global_load_lds_dwordx4 v[220:221], off
	v_lshl_add_u64 v[220:221], s[60:61], 0, v[152:153]
	s_mov_b32 m0, s62
	s_nop 0
	global_load_lds_dwordx4 v[220:221], off
	s_mov_b32 m0, s63
	s_nop 0
	global_load_lds_dwordx4 v[222:223], off
	s_waitcnt vmcnt(8)
	s_waitcnt lgkmcnt(0)
	s_setprio 1
	s_barrier
	s_waitcnt lgkmcnt(0)
	v_mfma_f32_16x16x32_bf16 v[60:63], v[128:131], v[176:179], v[60:63]
	v_mfma_f32_16x16x32_bf16 v[56:59], v[136:139], v[176:179], v[56:59]
	v_mfma_f32_16x16x32_bf16 v[44:47], v[128:131], v[192:195], v[44:47]
	v_mfma_f32_16x16x32_bf16 v[40:43], v[136:139], v[192:195], v[40:43]
	v_mfma_f32_16x16x32_bf16 v[28:31], v[128:131], v[200:203], v[28:31]
	v_mfma_f32_16x16x32_bf16 v[24:27], v[136:139], v[200:203], v[24:27]
	v_mfma_f32_16x16x32_bf16 v[12:15], v[128:131], v[208:211], v[12:15]
	v_mfma_f32_16x16x32_bf16 v[8:11], v[136:139], v[208:211], v[8:11]
	v_mfma_f32_16x16x32_bf16 v[60:63], v[132:135], v[180:183], v[60:63]
	v_mfma_f32_16x16x32_bf16 v[56:59], v[140:143], v[180:183], v[56:59]
	v_mfma_f32_16x16x32_bf16 v[44:47], v[132:135], v[196:199], v[44:47]
	v_mfma_f32_16x16x32_bf16 v[40:43], v[140:143], v[196:199], v[40:43]
	v_mfma_f32_16x16x32_bf16 v[28:31], v[132:135], v[204:207], v[28:31]
	v_mfma_f32_16x16x32_bf16 v[24:27], v[140:143], v[204:207], v[24:27]
	v_mfma_f32_16x16x32_bf16 v[12:15], v[132:135], v[212:215], v[12:15]
	v_mfma_f32_16x16x32_bf16 v[8:11], v[140:143], v[212:215], v[8:11]
	s_setprio 0
	s_setprio 1
	v_mfma_f32_16x16x32_bf16 v[52:55], v[144:147], v[176:179], v[52:55]
	v_mfma_f32_16x16x32_bf16 v[48:51], v[168:171], v[176:179], v[48:51]
	v_mfma_f32_16x16x32_bf16 v[36:39], v[144:147], v[192:195], v[36:39]
	v_mfma_f32_16x16x32_bf16 v[32:35], v[168:171], v[192:195], v[32:35]
	v_mfma_f32_16x16x32_bf16 v[20:23], v[144:147], v[200:203], v[20:23]
	v_mfma_f32_16x16x32_bf16 v[16:19], v[168:171], v[200:203], v[16:19]
	v_mfma_f32_16x16x32_bf16 v[4:7], v[144:147], v[208:211], v[4:7]
	v_mfma_f32_16x16x32_bf16 v[0:3], v[168:171], v[208:211], v[0:3]
	v_mfma_f32_16x16x32_bf16 v[52:55], v[148:151], v[180:183], v[52:55]
	v_mfma_f32_16x16x32_bf16 v[48:51], v[172:175], v[180:183], v[48:51]
	v_mfma_f32_16x16x32_bf16 v[36:39], v[148:151], v[196:199], v[36:39]
	v_mfma_f32_16x16x32_bf16 v[32:35], v[172:175], v[196:199], v[32:35]
	v_mfma_f32_16x16x32_bf16 v[20:23], v[148:151], v[204:207], v[20:23]
	v_mfma_f32_16x16x32_bf16 v[16:19], v[172:175], v[204:207], v[16:19]
	v_mfma_f32_16x16x32_bf16 v[4:7], v[148:151], v[212:215], v[4:7]
	v_mfma_f32_16x16x32_bf16 v[0:3], v[172:175], v[212:215], v[0:3]
	s_setprio 0
	s_barrier
	s_add_i32 s84, 0, 0x18000
	s_add_i32 s85, 0, 0x1c000
	v_add_u32_e32 v140, s84, v185
	v_add_u32_e32 v172, s85, v185
	ds_read_b128 v[128:131], v140
	ds_read_b128 v[132:135], v140 offset:1024
	ds_read_b128 v[136:139], v140 offset:2048
	ds_read_b128 v[140:143], v140 offset:3072
	ds_read_b128 v[144:147], v172
	ds_read_b128 v[148:151], v172 offset:1024
	ds_read_b128 v[168:171], v172 offset:2048
	ds_read_b128 v[172:175], v172 offset:3072
	s_add_u32 s60, s60, 0x40000
	s_addc_u32 s61, s61, 0
	s_mov_b32 m0, s64
	v_lshl_add_u64 v[224:225], s[60:61], 0, v[152:153]
	ds_read_b128 v[176:179], v189 offset:32768
	ds_read_b128 v[180:183], v189 offset:33792
	ds_read_b128 v[192:195], v189 offset:34816
	ds_read_b128 v[196:199], v189 offset:35840
	ds_read_b128 v[200:203], v189 offset:36864
	ds_read_b128 v[204:207], v189 offset:37888
	ds_read_b128 v[208:211], v189 offset:38912
	ds_read_b128 v[212:215], v189 offset:39936
	global_load_lds_dwordx4 v[224:225], off
	v_lshl_add_u64 v[224:225], s[60:61], 0, v[156:157]
	s_mov_b32 m0, s65
	s_nop 0
	global_load_lds_dwordx4 v[224:225], off
	s_waitcnt vmcnt(8)
	s_waitcnt lgkmcnt(0)
	s_setprio 1
	s_barrier
	s_waitcnt lgkmcnt(0)
	v_mfma_f32_16x16x32_bf16 v[124:127], v[128:131], v[176:179], v[124:127]
	v_mfma_f32_16x16x32_bf16 v[120:123], v[136:139], v[176:179], v[120:123]
	v_mfma_f32_16x16x32_bf16 v[108:111], v[128:131], v[192:195], v[108:111]
	v_mfma_f32_16x16x32_bf16 v[104:107], v[136:139], v[192:195], v[104:107]
	v_mfma_f32_16x16x32_bf16 v[92:95], v[128:131], v[200:203], v[92:95]
	v_mfma_f32_16x16x32_bf16 v[88:91], v[136:139], v[200:203], v[88:91]
	v_mfma_f32_16x16x32_bf16 v[76:79], v[128:131], v[208:211], v[76:79]
	v_mfma_f32_16x16x32_bf16 v[72:75], v[136:139], v[208:211], v[72:75]
	v_mfma_f32_16x16x32_bf16 v[124:127], v[132:135], v[180:183], v[124:127]
	v_mfma_f32_16x16x32_bf16 v[120:123], v[140:143], v[180:183], v[120:123]
	v_mfma_f32_16x16x32_bf16 v[108:111], v[132:135], v[196:199], v[108:111]
	v_mfma_f32_16x16x32_bf16 v[104:107], v[140:143], v[196:199], v[104:107]
	v_mfma_f32_16x16x32_bf16 v[92:95], v[132:135], v[204:207], v[92:95]
	v_mfma_f32_16x16x32_bf16 v[88:91], v[140:143], v[204:207], v[88:91]
	v_mfma_f32_16x16x32_bf16 v[76:79], v[132:135], v[212:215], v[76:79]
	v_mfma_f32_16x16x32_bf16 v[72:75], v[140:143], v[212:215], v[72:75]
	s_setprio 0
	s_setprio 1
	v_mfma_f32_16x16x32_bf16 v[116:119], v[144:147], v[176:179], v[116:119]
	v_mfma_f32_16x16x32_bf16 v[112:115], v[168:171], v[176:179], v[112:115]
	v_mfma_f32_16x16x32_bf16 v[100:103], v[144:147], v[192:195], v[100:103]
	v_mfma_f32_16x16x32_bf16 v[96:99], v[168:171], v[192:195], v[96:99]
	v_mfma_f32_16x16x32_bf16 v[84:87], v[144:147], v[200:203], v[84:87]
	v_mfma_f32_16x16x32_bf16 v[80:83], v[168:171], v[200:203], v[80:83]
	v_mfma_f32_16x16x32_bf16 v[68:71], v[144:147], v[208:211], v[68:71]
	v_mfma_f32_16x16x32_bf16 v[64:67], v[168:171], v[208:211], v[64:67]
	v_mfma_f32_16x16x32_bf16 v[116:119], v[148:151], v[180:183], v[116:119]
	v_mfma_f32_16x16x32_bf16 v[112:115], v[172:175], v[180:183], v[112:115]
	v_mfma_f32_16x16x32_bf16 v[100:103], v[148:151], v[196:199], v[100:103]
	v_mfma_f32_16x16x32_bf16 v[96:99], v[172:175], v[196:199], v[96:99]
	v_mfma_f32_16x16x32_bf16 v[84:87], v[148:151], v[204:207], v[84:87]
	v_mfma_f32_16x16x32_bf16 v[80:83], v[172:175], v[204:207], v[80:83]
	v_mfma_f32_16x16x32_bf16 v[68:71], v[148:151], v[212:215], v[68:71]
	v_mfma_f32_16x16x32_bf16 v[64:67], v[172:175], v[212:215], v[64:67]
	s_setprio 0
	s_barrier
	s_add_i32 s60, s84, s57
	v_lshl_add_u64 v[216:217], v[216:217], 0, s[8:9]
	s_mov_b32 m0, s60
	ds_read_b128 v[176:179], v189 offset:49152
	ds_read_b128 v[180:183], v189 offset:50176
	ds_read_b128 v[192:195], v189 offset:51200
	ds_read_b128 v[196:199], v189 offset:52224
	ds_read_b128 v[200:203], v189 offset:53248
	ds_read_b128 v[204:207], v189 offset:54272
	ds_read_b128 v[208:211], v189 offset:55296
	ds_read_b128 v[212:215], v189 offset:56320
	global_load_lds_dwordx4 v[216:217], off
	s_add_i32 m0, s60, 0x2000
	s_add_u32 s58, s58, 0x40080
	v_lshl_add_u64 v[216:217], v[218:219], 0, s[8:9]
	s_addc_u32 s59, s59, 0
	s_add_i32 s60, s85, s57
	global_load_lds_dwordx4 v[216:217], off
	v_lshl_add_u64 v[216:217], s[58:59], 0, v[154:155]
	s_mov_b32 m0, s60
	s_nop 0
	global_load_lds_dwordx4 v[216:217], off
	v_lshl_add_u64 v[216:217], s[58:59], 0, v[158:159]
	s_add_i32 m0, s60, 0x2000
	s_nop 0
	global_load_lds_dwordx4 v[216:217], off
	v_lshl_add_u64 v[216:217], v[220:221], 0, s[8:9]
	s_mov_b32 m0, s67
	s_nop 0
	global_load_lds_dwordx4 v[216:217], off
	v_lshl_add_u64 v[216:217], v[222:223], 0, s[8:9]
	s_mov_b32 m0, s68
	s_nop 0
	global_load_lds_dwordx4 v[216:217], off
	s_waitcnt vmcnt(8)
	s_waitcnt lgkmcnt(0)
	s_setprio 1
	s_barrier
	s_waitcnt lgkmcnt(0)
	v_mfma_f32_16x16x32_bf16 v[60:63], v[128:131], v[176:179], v[60:63]
	v_mfma_f32_16x16x32_bf16 v[56:59], v[136:139], v[176:179], v[56:59]
	v_mfma_f32_16x16x32_bf16 v[44:47], v[128:131], v[192:195], v[44:47]
	v_mfma_f32_16x16x32_bf16 v[40:43], v[136:139], v[192:195], v[40:43]
	v_mfma_f32_16x16x32_bf16 v[28:31], v[128:131], v[200:203], v[28:31]
	v_mfma_f32_16x16x32_bf16 v[24:27], v[136:139], v[200:203], v[24:27]
	v_mfma_f32_16x16x32_bf16 v[12:15], v[128:131], v[208:211], v[12:15]
	v_mfma_f32_16x16x32_bf16 v[8:11], v[136:139], v[208:211], v[8:11]
	v_mfma_f32_16x16x32_bf16 v[60:63], v[132:135], v[180:183], v[60:63]
	v_mfma_f32_16x16x32_bf16 v[56:59], v[140:143], v[180:183], v[56:59]
	v_mfma_f32_16x16x32_bf16 v[44:47], v[132:135], v[196:199], v[44:47]
	v_mfma_f32_16x16x32_bf16 v[40:43], v[140:143], v[196:199], v[40:43]
	v_mfma_f32_16x16x32_bf16 v[28:31], v[132:135], v[204:207], v[28:31]
	v_mfma_f32_16x16x32_bf16 v[24:27], v[140:143], v[204:207], v[24:27]
	v_mfma_f32_16x16x32_bf16 v[12:15], v[132:135], v[212:215], v[12:15]
	v_mfma_f32_16x16x32_bf16 v[8:11], v[140:143], v[212:215], v[8:11]
	s_setprio 0
	s_setprio 1
	v_mfma_f32_16x16x32_bf16 v[52:55], v[144:147], v[176:179], v[52:55]
	v_mfma_f32_16x16x32_bf16 v[48:51], v[168:171], v[176:179], v[48:51]
	v_mfma_f32_16x16x32_bf16 v[36:39], v[144:147], v[192:195], v[36:39]
	v_mfma_f32_16x16x32_bf16 v[32:35], v[168:171], v[192:195], v[32:35]
	v_mfma_f32_16x16x32_bf16 v[20:23], v[144:147], v[200:203], v[20:23]
	v_mfma_f32_16x16x32_bf16 v[16:19], v[168:171], v[200:203], v[16:19]
	v_mfma_f32_16x16x32_bf16 v[4:7], v[144:147], v[208:211], v[4:7]
	v_mfma_f32_16x16x32_bf16 v[0:3], v[168:171], v[208:211], v[0:3]
	v_mfma_f32_16x16x32_bf16 v[52:55], v[148:151], v[180:183], v[52:55]
	v_mfma_f32_16x16x32_bf16 v[48:51], v[172:175], v[180:183], v[48:51]
	v_mfma_f32_16x16x32_bf16 v[36:39], v[148:151], v[196:199], v[36:39]
	v_mfma_f32_16x16x32_bf16 v[32:35], v[172:175], v[196:199], v[32:35]
	v_mfma_f32_16x16x32_bf16 v[20:23], v[148:151], v[204:207], v[20:23]
	v_mfma_f32_16x16x32_bf16 v[16:19], v[172:175], v[204:207], v[16:19]
	v_mfma_f32_16x16x32_bf16 v[4:7], v[148:151], v[212:215], v[4:7]
	v_mfma_f32_16x16x32_bf16 v[0:3], v[172:175], v[212:215], v[0:3]
	s_setprio 0
	s_barrier
	s_add_i32 s83, s83, 2
	s_add_u32 s52, s52, 0x100
	s_addc_u32 s53, s53, 0
	s_add_u32 s81, s81, 0x100
	s_addc_u32 s82, s82, 0
	s_cmp_gt_u32 s83, 13
	s_cbranch_scc0 .LBB0_741
	v_lshl_add_u32 v168, s79, 8, v184
	v_lshl_or_b32 v128, s78, 8, v186
	v_ashrrev_i32_e32 v169, 31, v168
	v_ashrrev_i32_e32 v129, 31, v128
	v_lshlrev_b64 v[130:131], 11, v[168:169]
	v_lshl_add_u64 v[130:131], s[34:35], 0, v[130:131]
	v_lshlrev_b64 v[170:171], 1, v[128:129]
	v_lshl_add_u64 v[200:201], v[130:131], 0, v[170:171]
	global_load_dwordx4 v[192:195], v[200:201], off
	global_load_dwordx4 v[196:199], v[200:201], off offset:256
	v_or_b32_e32 v180, 16, v168
	v_or_b32_e32 v176, 32, v168
	v_or_b32_e32 v172, 48, v168
	v_ashrrev_i32_e32 v181, 31, v180
	v_ashrrev_i32_e32 v177, 31, v176
	v_ashrrev_i32_e32 v173, 31, v172
	v_lshlrev_b64 v[128:129], 11, v[180:181]
	v_lshlrev_b64 v[130:131], 11, v[176:177]
	v_lshlrev_b64 v[132:133], 11, v[172:173]
	v_lshl_add_u64 v[128:129], s[34:35], 0, v[128:129]
	v_lshl_add_u64 v[130:131], s[34:35], 0, v[130:131]
	v_lshl_add_u64 v[132:133], s[34:35], 0, v[132:133]
	v_lshl_add_u64 v[182:183], v[128:129], 0, v[170:171]
	v_lshl_add_u64 v[178:179], v[130:131], 0, v[170:171]
	v_lshl_add_u64 v[174:175], v[132:133], 0, v[170:171]
	global_load_dwordx4 v[148:151], v[182:183], off
	global_load_dwordx4 v[144:147], v[182:183], off offset:256
	global_load_dwordx4 v[140:143], v[178:179], off
	global_load_dwordx4 v[136:139], v[178:179], off offset:256
	global_load_dwordx4 v[132:135], v[174:175], off
	global_load_dwordx4 v[128:131], v[174:175], off offset:256
	v_and_b32_e32 v202, 64, v190
	v_xor_b32_e32 v191, 16, v190
	v_add_u32_e32 v202, 64, v202
	v_xor_b32_e32 v203, 32, v190
	v_cmp_lt_i32_e32 vcc, v191, v202
	s_lshl_b32 s52, s78, 2
	s_ashr_i32 s53, s52, 31
	v_cndmask_b32_e32 v191, v190, v191, vcc
	v_cmp_lt_i32_e32 vcc, v203, v202
	v_lshlrev_b32_e32 v191, 2, v191
	s_waitcnt vmcnt(0)
	v_lshlrev_b32_e32 v202, 16, v192
	v_cndmask_b32_e32 v210, v190, v203, vcc
	v_and_b32_e32 v203, 0xffff0000, v192
	v_lshlrev_b32_e32 v192, 16, v193
	v_and_b32_e32 v193, 0xffff0000, v193
	v_lshlrev_b32_e32 v204, 16, v194
	v_and_b32_e32 v205, 0xffff0000, v194
	v_lshlrev_b32_e32 v194, 16, v195
	v_and_b32_e32 v195, 0xffff0000, v195
	v_lshlrev_b32_e32 v206, 16, v196
	v_and_b32_e32 v207, 0xffff0000, v196
	v_lshlrev_b32_e32 v196, 16, v197
	v_and_b32_e32 v197, 0xffff0000, v197
	v_lshlrev_b32_e32 v208, 16, v198
	v_and_b32_e32 v209, 0xffff0000, v198
	v_lshlrev_b32_e32 v198, 16, v199
	v_and_b32_e32 v199, 0xffff0000, v199
	v_pk_add_f32 v[126:127], v[126:127], v[192:193]
	v_pk_add_f32 v[124:125], v[124:125], v[202:203]
	v_pk_add_f32 v[122:123], v[122:123], v[194:195]
	v_pk_add_f32 v[120:121], v[120:121], v[204:205]
	v_pk_add_f32 v[118:119], v[118:119], v[196:197]
	v_pk_add_f32 v[116:117], v[116:117], v[206:207]
	v_pk_add_f32 v[192:193], v[114:115], v[198:199]
	v_pk_add_f32 v[194:195], v[112:113], v[208:209]
	v_cvt_pk_bf16_f32 v112, v124, v125
	v_cvt_pk_bf16_f32 v113, v126, v127
	v_mul_f32_e32 v114, v125, v125
	v_mul_f32_e32 v115, v127, v127
	v_mul_f32_e32 v125, v121, v121
	v_mul_f32_e32 v127, v123, v123
	v_mul_f32_e32 v196, v117, v117
	v_mul_f32_e32 v197, v119, v119
	v_mul_f32_e32 v198, v195, v195
	v_mul_f32_e32 v199, v193, v193
	v_fmac_f32_e32 v114, v124, v124
	v_fmac_f32_e32 v115, v126, v126
	v_fmac_f32_e32 v125, v120, v120
	v_fmac_f32_e32 v127, v122, v122
	v_fmac_f32_e32 v196, v116, v116
	v_fmac_f32_e32 v197, v118, v118
	v_fmac_f32_e32 v198, v194, v194
	v_fmac_f32_e32 v199, v192, v192
	v_add_f32_e32 v114, v114, v115
	v_add_f32_e32 v115, v125, v127
	v_add_f32_e32 v124, v196, v197
	v_add_f32_e32 v125, v198, v199
	v_add_f32_e32 v114, v114, v115
	v_add_f32_e32 v115, v124, v125
	v_add_f32_e32 v124, v114, v115
	ds_bpermute_b32 v125, v191, v124
	v_cvt_pk_bf16_f32 v114, v120, v121
	v_cvt_pk_bf16_f32 v115, v122, v123
	global_store_dwordx4 v[200:201], v[112:115], off
	v_cvt_pk_bf16_f32 v116, v116, v117
	v_cvt_pk_bf16_f32 v117, v118, v119
	s_waitcnt lgkmcnt(0)
	v_add_f32_e32 v113, v124, v125
	v_lshlrev_b32_e32 v112, 2, v210
	ds_bpermute_b32 v114, v112, v113
	v_cvt_pk_bf16_f32 v118, v194, v195
	v_cvt_pk_bf16_f32 v119, v192, v193
	global_store_dwordx4 v[200:201], v[116:119], off offset:256
	s_and_saveexec_b64 s[58:59], s[0:1]
	s_cbranch_execz .LBB0_744
	s_waitcnt lgkmcnt(0)
	v_add_f32_e32 v113, v113, v114
	v_lshlrev_b64 v[114:115], 6, v[168:169]
	v_lshl_add_u64 v[114:115], s[74:75], 0, v[114:115]
	v_lshl_add_u64 v[114:115], s[52:53], 2, v[114:115]
	s_lshl_b32 s6, s66, 2
	v_lshl_add_u64 v[114:115], v[114:115], 0, s[6:7]
	global_store_dword v[114:115], v113, off

.LBB0_876:
	ds_read_b128 v[96:99], v182
	ds_read_b128 v[100:103], v182 offset:1024
	ds_read_b128 v[104:107], v182 offset:2048
	ds_read_b128 v[108:111], v182 offset:3072
	ds_read_b128 v[112:115], v183
	ds_read_b128 v[116:119], v183 offset:1024
	ds_read_b128 v[120:123], v183 offset:2048
	ds_read_b128 v[124:127], v183 offset:3072
	s_add_u32 s88, s86, 0xfff80080
	s_addc_u32 s89, s87, -1
	s_cmp_eq_u32 s68, 12
	s_cselect_b32 s91, s3, s5
	s_cselect_b32 s90, s61, s4
	s_cselect_b32 s89, s65, s89
	s_cselect_b32 s88, s73, s88
	v_lshl_add_u64 v[168:169], s[86:87], 0, v[142:143]
	s_add_i32 m0, s41, 0xc000
	ds_read_b128 v[128:131], v184
	ds_read_b128 v[150:153], v184 offset:1024
	ds_read_b128 v[154:157], v184 offset:2048
	ds_read_b128 v[158:161], v184 offset:3072
	ds_read_b128 v[162:165], v184 offset:4096
	ds_read_b128 v[176:179], v184 offset:5120
	ds_read_b128 v[188:191], v184 offset:6144
	ds_read_b128 v[192:195], v184 offset:7168
	global_load_lds_dwordx4 v[168:169], off
	v_lshl_add_u64 v[168:169], s[86:87], 0, v[144:145]
	s_add_i32 m0, s41, 0xe000
	s_nop 0
	global_load_lds_dwordx4 v[168:169], off
	s_waitcnt vmcnt(8)
	s_waitcnt lgkmcnt(0)
	s_setprio 1
	s_barrier
	s_waitcnt lgkmcnt(0)
	v_mfma_f32_16x16x32_bf16 v[92:95], v[96:99], v[128:131], v[92:95]
	v_mfma_f32_16x16x32_bf16 v[88:91], v[104:107], v[128:131], v[88:91]
	v_mfma_f32_16x16x32_bf16 v[84:87], v[96:99], v[154:157], v[84:87]
	v_mfma_f32_16x16x32_bf16 v[80:83], v[104:107], v[154:157], v[80:83]
	v_mfma_f32_16x16x32_bf16 v[68:71], v[96:99], v[162:165], v[68:71]
	v_mfma_f32_16x16x32_bf16 v[64:67], v[104:107], v[162:165], v[64:67]
	v_mfma_f32_16x16x32_bf16 v[52:55], v[96:99], v[188:191], v[52:55]
	v_mfma_f32_16x16x32_bf16 v[48:51], v[104:107], v[188:191], v[48:51]
	v_mfma_f32_16x16x32_bf16 v[92:95], v[100:103], v[150:153], v[92:95]
	v_mfma_f32_16x16x32_bf16 v[88:91], v[108:111], v[150:153], v[88:91]
	v_mfma_f32_16x16x32_bf16 v[84:87], v[100:103], v[158:161], v[84:87]
	v_mfma_f32_16x16x32_bf16 v[80:83], v[108:111], v[158:161], v[80:83]
	v_mfma_f32_16x16x32_bf16 v[68:71], v[100:103], v[176:179], v[68:71]
	v_mfma_f32_16x16x32_bf16 v[64:67], v[108:111], v[176:179], v[64:67]
	v_mfma_f32_16x16x32_bf16 v[52:55], v[100:103], v[192:195], v[52:55]
	v_mfma_f32_16x16x32_bf16 v[48:51], v[108:111], v[192:195], v[48:51]
	s_setprio 0
	s_setprio 1
	v_mfma_f32_16x16x32_bf16 v[76:79], v[112:115], v[128:131], v[76:79]
	v_mfma_f32_16x16x32_bf16 v[72:75], v[120:123], v[128:131], v[72:75]
	v_mfma_f32_16x16x32_bf16 v[60:63], v[112:115], v[154:157], v[60:63]
	v_mfma_f32_16x16x32_bf16 v[56:59], v[120:123], v[154:157], v[56:59]
	v_mfma_f32_16x16x32_bf16 v[44:47], v[112:115], v[162:165], v[44:47]
	v_mfma_f32_16x16x32_bf16 v[40:43], v[120:123], v[162:165], v[40:43]
	v_mfma_f32_16x16x32_bf16 v[36:39], v[112:115], v[188:191], v[36:39]
	v_mfma_f32_16x16x32_bf16 v[32:35], v[120:123], v[188:191], v[32:35]
	v_mfma_f32_16x16x32_bf16 v[76:79], v[116:119], v[150:153], v[76:79]
	v_mfma_f32_16x16x32_bf16 v[72:75], v[124:127], v[150:153], v[72:75]
	v_mfma_f32_16x16x32_bf16 v[60:63], v[116:119], v[158:161], v[60:63]
	v_mfma_f32_16x16x32_bf16 v[56:59], v[124:127], v[158:161], v[56:59]
	v_mfma_f32_16x16x32_bf16 v[44:47], v[116:119], v[176:179], v[44:47]
	v_mfma_f32_16x16x32_bf16 v[40:43], v[124:127], v[176:179], v[40:43]
	v_mfma_f32_16x16x32_bf16 v[36:39], v[116:119], v[192:195], v[36:39]
	v_mfma_f32_16x16x32_bf16 v[32:35], v[124:127], v[192:195], v[32:35]
	s_setprio 0
	s_barrier
	s_add_i32 s92, s76, s15
	v_lshl_add_u64 v[168:169], s[88:89], 0, v[134:135]
	s_mov_b32 m0, s92
	ds_read_b128 v[96:99], v185 offset:16384
	ds_read_b128 v[100:103], v185 offset:17408
	ds_read_b128 v[104:107], v185 offset:18432
	ds_read_b128 v[108:111], v185 offset:19456
	global_load_lds_dwordx4 v[168:169], off
	s_add_i32 m0, s92, 0x2000
	s_add_u32 s92, s88, 0x40000
	v_lshl_add_u64 v[172:173], s[88:89], 0, v[138:139]
	s_addc_u32 s93, s89, 0
	s_add_i32 vcc_lo, s77, s15
	global_load_lds_dwordx4 v[172:173], off
	v_lshl_add_u64 v[112:113], s[92:93], 0, v[134:135]
	s_mov_b32 m0, vcc_lo
	v_lshl_add_u64 v[180:181], s[90:91], 0, v[132:133]
	global_load_lds_dwordx4 v[112:113], off
	v_lshl_add_u64 v[112:113], s[92:93], 0, v[138:139]
	s_add_i32 m0, vcc_lo, 0x2000
	v_lshl_add_u64 v[196:197], s[90:91], 0, v[136:137]
	global_load_lds_dwordx4 v[112:113], off
	s_mov_b32 m0, s41
	s_nop 0
	global_load_lds_dwordx4 v[180:181], off
	s_mov_b32 m0, s52
	s_nop 0
	global_load_lds_dwordx4 v[196:197], off
	s_waitcnt vmcnt(8)
	s_waitcnt lgkmcnt(0)
	s_setprio 1
	s_barrier
	s_waitcnt lgkmcnt(0)
	v_mfma_f32_16x16x32_bf16 v[28:31], v[96:99], v[128:131], v[28:31]
	v_mfma_f32_16x16x32_bf16 v[24:27], v[104:107], v[128:131], v[24:27]
	v_mfma_f32_16x16x32_bf16 v[20:23], v[96:99], v[154:157], v[20:23]
	v_mfma_f32_16x16x32_bf16 v[16:19], v[104:107], v[154:157], v[16:19]
	v_mfma_f32_16x16x32_bf16 v[12:15], v[96:99], v[162:165], v[12:15]
	v_mfma_f32_16x16x32_bf16 v[8:11], v[104:107], v[162:165], v[8:11]
	v_mfma_f32_16x16x32_bf16 v[4:7], v[96:99], v[188:191], v[4:7]
	v_mfma_f32_16x16x32_bf16 v[0:3], v[104:107], v[188:191], v[0:3]
	v_mfma_f32_16x16x32_bf16 v[28:31], v[100:103], v[150:153], v[28:31]
	v_mfma_f32_16x16x32_bf16 v[24:27], v[108:111], v[150:153], v[24:27]
	v_mfma_f32_16x16x32_bf16 v[20:23], v[100:103], v[158:161], v[20:23]
	v_mfma_f32_16x16x32_bf16 v[16:19], v[108:111], v[158:161], v[16:19]
	v_mfma_f32_16x16x32_bf16 v[12:15], v[100:103], v[176:179], v[12:15]
	v_mfma_f32_16x16x32_bf16 v[8:11], v[108:111], v[176:179], v[8:11]
	v_mfma_f32_16x16x32_bf16 v[4:7], v[100:103], v[192:195], v[4:7]
	v_mfma_f32_16x16x32_bf16 v[0:3], v[108:111], v[192:195], v[0:3]
	s_setprio 0
	s_barrier
	s_add_i32 s92, 0, 0x18000
	s_add_i32 s93, 0, 0x1c000
	v_add_u32_e32 v108, s92, v171
	v_add_u32_e32 v124, s93, v171
	ds_read_b128 v[96:99], v108
	ds_read_b128 v[100:103], v108 offset:1024
	ds_read_b128 v[104:107], v108 offset:2048
	ds_read_b128 v[108:111], v108 offset:3072
	ds_read_b128 v[112:115], v124
	ds_read_b128 v[116:119], v124 offset:1024
	ds_read_b128 v[120:123], v124 offset:2048
	ds_read_b128 v[124:127], v124 offset:3072
	s_add_u32 s90, s88, 0x80000
	s_addc_u32 s91, s89, 0
	s_mov_b32 m0, s53
	v_lshl_add_u64 v[198:199], s[90:91], 0, v[134:135]
	ds_read_b128 v[128:131], v184 offset:32768
	ds_read_b128 v[150:153], v184 offset:33792
	ds_read_b128 v[154:157], v184 offset:34816
	ds_read_b128 v[158:161], v184 offset:35840
	ds_read_b128 v[162:165], v184 offset:36864
	ds_read_b128 v[176:179], v184 offset:37888
	ds_read_b128 v[188:191], v184 offset:38912
	ds_read_b128 v[192:195], v184 offset:39936
	global_load_lds_dwordx4 v[198:199], off
	v_lshl_add_u64 v[198:199], s[90:91], 0, v[138:139]
	s_mov_b32 m0, s54
	s_nop 0
	global_load_lds_dwordx4 v[198:199], off
	s_waitcnt vmcnt(8)
	s_waitcnt lgkmcnt(0)
	s_setprio 1
	s_barrier
	s_waitcnt lgkmcnt(0)
	v_mfma_f32_16x16x32_bf16 v[92:95], v[96:99], v[128:131], v[92:95]
	v_mfma_f32_16x16x32_bf16 v[88:91], v[104:107], v[128:131], v[88:91]
	v_mfma_f32_16x16x32_bf16 v[84:87], v[96:99], v[154:157], v[84:87]
	v_mfma_f32_16x16x32_bf16 v[80:83], v[104:107], v[154:157], v[80:83]
	v_mfma_f32_16x16x32_bf16 v[68:71], v[96:99], v[162:165], v[68:71]
	v_mfma_f32_16x16x32_bf16 v[64:67], v[104:107], v[162:165], v[64:67]
	v_mfma_f32_16x16x32_bf16 v[52:55], v[96:99], v[188:191], v[52:55]
	v_mfma_f32_16x16x32_bf16 v[48:51], v[104:107], v[188:191], v[48:51]
	v_mfma_f32_16x16x32_bf16 v[92:95], v[100:103], v[150:153], v[92:95]
	v_mfma_f32_16x16x32_bf16 v[88:91], v[108:111], v[150:153], v[88:91]
	v_mfma_f32_16x16x32_bf16 v[84:87], v[100:103], v[158:161], v[84:87]
	v_mfma_f32_16x16x32_bf16 v[80:83], v[108:111], v[158:161], v[80:83]
	v_mfma_f32_16x16x32_bf16 v[68:71], v[100:103], v[176:179], v[68:71]
	v_mfma_f32_16x16x32_bf16 v[64:67], v[108:111], v[176:179], v[64:67]
	v_mfma_f32_16x16x32_bf16 v[52:55], v[100:103], v[192:195], v[52:55]
	v_mfma_f32_16x16x32_bf16 v[48:51], v[108:111], v[192:195], v[48:51]
	s_setprio 0
	s_setprio 1
	v_mfma_f32_16x16x32_bf16 v[76:79], v[112:115], v[128:131], v[76:79]
	v_mfma_f32_16x16x32_bf16 v[72:75], v[120:123], v[128:131], v[72:75]
	v_mfma_f32_16x16x32_bf16 v[60:63], v[112:115], v[154:157], v[60:63]
	v_mfma_f32_16x16x32_bf16 v[56:59], v[120:123], v[154:157], v[56:59]
	v_mfma_f32_16x16x32_bf16 v[44:47], v[112:115], v[162:165], v[44:47]
	v_mfma_f32_16x16x32_bf16 v[40:43], v[120:123], v[162:165], v[40:43]
	v_mfma_f32_16x16x32_bf16 v[36:39], v[112:115], v[188:191], v[36:39]
	v_mfma_f32_16x16x32_bf16 v[32:35], v[120:123], v[188:191], v[32:35]
	v_mfma_f32_16x16x32_bf16 v[76:79], v[116:119], v[150:153], v[76:79]
	v_mfma_f32_16x16x32_bf16 v[72:75], v[124:127], v[150:153], v[72:75]
	v_mfma_f32_16x16x32_bf16 v[60:63], v[116:119], v[158:161], v[60:63]
	v_mfma_f32_16x16x32_bf16 v[56:59], v[124:127], v[158:161], v[56:59]
	v_mfma_f32_16x16x32_bf16 v[44:47], v[116:119], v[176:179], v[44:47]
	v_mfma_f32_16x16x32_bf16 v[40:43], v[124:127], v[176:179], v[40:43]
	v_mfma_f32_16x16x32_bf16 v[36:39], v[116:119], v[192:195], v[36:39]
	v_mfma_f32_16x16x32_bf16 v[32:35], v[124:127], v[192:195], v[32:35]
	s_setprio 0
	s_barrier
	s_add_i32 s90, s92, s15
	v_lshl_add_u64 v[112:113], v[168:169], 0, s[10:11]
	s_mov_b32 m0, s90
	ds_read_b128 v[96:99], v185 offset:49152
	ds_read_b128 v[100:103], v185 offset:50176
	ds_read_b128 v[104:107], v185 offset:51200
	ds_read_b128 v[108:111], v185 offset:52224
	global_load_lds_dwordx4 v[112:113], off
	s_add_i32 m0, s90, 0x2000
	s_add_u32 s88, s88, 0x40080
	v_lshl_add_u64 v[112:113], v[172:173], 0, s[10:11]
	s_addc_u32 s89, s89, 0
	s_add_i32 s90, s93, s15
	global_load_lds_dwordx4 v[112:113], off
	v_lshl_add_u64 v[112:113], s[88:89], 0, v[134:135]
	s_mov_b32 m0, s90
	s_nop 0
	global_load_lds_dwordx4 v[112:113], off
	v_lshl_add_u64 v[112:113], s[88:89], 0, v[138:139]
	s_add_i32 m0, s90, 0x2000
	s_nop 0
	global_load_lds_dwordx4 v[112:113], off
	v_lshl_add_u64 v[112:113], v[180:181], 0, s[10:11]
	s_mov_b32 m0, s55
	s_nop 0
	global_load_lds_dwordx4 v[112:113], off
	v_lshl_add_u64 v[112:113], v[196:197], 0, s[10:11]
	s_mov_b32 m0, s56
	s_nop 0
	global_load_lds_dwordx4 v[112:113], off
	s_waitcnt vmcnt(8)
	s_waitcnt lgkmcnt(0)
	s_setprio 1
	s_barrier
	s_waitcnt lgkmcnt(0)
	v_mfma_f32_16x16x32_bf16 v[28:31], v[96:99], v[128:131], v[28:31]
	v_mfma_f32_16x16x32_bf16 v[24:27], v[104:107], v[128:131], v[24:27]
	v_mfma_f32_16x16x32_bf16 v[20:23], v[96:99], v[154:157], v[20:23]
	v_mfma_f32_16x16x32_bf16 v[16:19], v[104:107], v[154:157], v[16:19]
	v_mfma_f32_16x16x32_bf16 v[12:15], v[96:99], v[162:165], v[12:15]
	v_mfma_f32_16x16x32_bf16 v[8:11], v[104:107], v[162:165], v[8:11]
	v_mfma_f32_16x16x32_bf16 v[4:7], v[96:99], v[188:191], v[4:7]
	v_mfma_f32_16x16x32_bf16 v[0:3], v[104:107], v[188:191], v[0:3]
	v_mfma_f32_16x16x32_bf16 v[28:31], v[100:103], v[150:153], v[28:31]
	v_mfma_f32_16x16x32_bf16 v[24:27], v[108:111], v[150:153], v[24:27]
	v_mfma_f32_16x16x32_bf16 v[20:23], v[100:103], v[158:161], v[20:23]
	v_mfma_f32_16x16x32_bf16 v[16:19], v[108:111], v[158:161], v[16:19]
	v_mfma_f32_16x16x32_bf16 v[12:15], v[100:103], v[176:179], v[12:15]
	v_mfma_f32_16x16x32_bf16 v[8:11], v[108:111], v[176:179], v[8:11]
	v_mfma_f32_16x16x32_bf16 v[4:7], v[100:103], v[192:195], v[4:7]
	v_mfma_f32_16x16x32_bf16 v[0:3], v[108:111], v[192:195], v[0:3]
	s_setprio 0
	s_barrier
	s_add_i32 s68, s68, 2
	s_add_u32 s4, s4, 0x100
	s_addc_u32 s5, s5, 0
	s_add_u32 s86, s86, 0x100
	s_addc_u32 s87, s87, 0
	s_cmp_gt_u32 s68, 13
	s_cbranch_scc0 .LBB0_876
	s_mov_b64 s[86:87], 0
	s_branch .LBB0_879

.LBB0_881:
	ds_read_b128 v[128:131], v182
	ds_read_b128 v[150:153], v182 offset:1024
	ds_read_b128 v[154:157], v182 offset:2048
	ds_read_b128 v[158:161], v182 offset:3072
	ds_read_b128 v[162:165], v183
	ds_read_b128 v[176:179], v183 offset:1024
	ds_read_b128 v[188:191], v183 offset:2048
	ds_read_b128 v[192:195], v183 offset:3072
	s_add_u32 s92, s84, 0xfffc0080
	s_addc_u32 s93, s85, -1
	s_cmp_eq_u32 s5, 12
	s_cselect_b64 s[90:91], -1, 0
	s_and_b64 s[88:89], s[90:91], exec
	s_cselect_b32 s89, s65, s71
	s_cselect_b32 s88, s73, s69
	s_cselect_b32 s93, s3, s93
	s_cselect_b32 s92, s61, s92
	v_lshl_add_u64 v[168:169], s[84:85], 0, v[146:147]
	s_add_i32 m0, s41, 0xc000
	ds_read_b128 v[196:199], v184
	ds_read_b128 v[200:203], v184 offset:1024
	ds_read_b128 v[204:207], v184 offset:2048
	ds_read_b128 v[208:211], v184 offset:3072
	ds_read_b128 v[212:215], v184 offset:4096
	ds_read_b128 v[216:219], v184 offset:5120
	ds_read_b128 v[220:223], v184 offset:6144
	ds_read_b128 v[224:227], v184 offset:7168
	global_load_lds_dwordx4 v[168:169], off
	v_lshl_add_u64 v[168:169], s[84:85], 0, v[136:137]
	s_add_i32 m0, s41, 0xe000
	s_nop 0
	global_load_lds_dwordx4 v[168:169], off
	s_waitcnt vmcnt(8)
	s_waitcnt lgkmcnt(0)
	s_setprio 1
	s_barrier
	s_waitcnt lgkmcnt(0)
	v_mfma_f32_16x16x32_bf16 v[92:95], v[128:131], v[196:199], v[92:95]
	v_mfma_f32_16x16x32_bf16 v[88:91], v[154:157], v[196:199], v[88:91]
	v_mfma_f32_16x16x32_bf16 v[84:87], v[128:131], v[204:207], v[84:87]
	v_mfma_f32_16x16x32_bf16 v[80:83], v[154:157], v[204:207], v[80:83]
	v_mfma_f32_16x16x32_bf16 v[68:71], v[128:131], v[212:215], v[68:71]
	v_mfma_f32_16x16x32_bf16 v[64:67], v[154:157], v[212:215], v[64:67]
	v_mfma_f32_16x16x32_bf16 v[52:55], v[128:131], v[220:223], v[52:55]
	v_mfma_f32_16x16x32_bf16 v[48:51], v[154:157], v[220:223], v[48:51]
	v_mfma_f32_16x16x32_bf16 v[92:95], v[150:153], v[200:203], v[92:95]
	v_mfma_f32_16x16x32_bf16 v[88:91], v[158:161], v[200:203], v[88:91]
	v_mfma_f32_16x16x32_bf16 v[84:87], v[150:153], v[208:211], v[84:87]
	v_mfma_f32_16x16x32_bf16 v[80:83], v[158:161], v[208:211], v[80:83]
	v_mfma_f32_16x16x32_bf16 v[68:71], v[150:153], v[216:219], v[68:71]
	v_mfma_f32_16x16x32_bf16 v[64:67], v[158:161], v[216:219], v[64:67]
	v_mfma_f32_16x16x32_bf16 v[52:55], v[150:153], v[224:227], v[52:55]
	v_mfma_f32_16x16x32_bf16 v[48:51], v[158:161], v[224:227], v[48:51]
	s_setprio 0
	s_setprio 1
	v_mfma_f32_16x16x32_bf16 v[76:79], v[162:165], v[196:199], v[76:79]
	v_mfma_f32_16x16x32_bf16 v[72:75], v[188:191], v[196:199], v[72:75]
	v_mfma_f32_16x16x32_bf16 v[60:63], v[162:165], v[204:207], v[60:63]
	v_mfma_f32_16x16x32_bf16 v[56:59], v[188:191], v[204:207], v[56:59]
	v_mfma_f32_16x16x32_bf16 v[44:47], v[162:165], v[212:215], v[44:47]
	v_mfma_f32_16x16x32_bf16 v[40:43], v[188:191], v[212:215], v[40:43]
	v_mfma_f32_16x16x32_bf16 v[36:39], v[162:165], v[220:223], v[36:39]
	v_mfma_f32_16x16x32_bf16 v[32:35], v[188:191], v[220:223], v[32:35]
	v_mfma_f32_16x16x32_bf16 v[76:79], v[176:179], v[200:203], v[76:79]
	v_mfma_f32_16x16x32_bf16 v[72:75], v[192:195], v[200:203], v[72:75]
	v_mfma_f32_16x16x32_bf16 v[60:63], v[176:179], v[208:211], v[60:63]
	v_mfma_f32_16x16x32_bf16 v[56:59], v[192:195], v[208:211], v[56:59]
	v_mfma_f32_16x16x32_bf16 v[44:47], v[176:179], v[216:219], v[44:47]
	v_mfma_f32_16x16x32_bf16 v[40:43], v[192:195], v[216:219], v[40:43]
	v_mfma_f32_16x16x32_bf16 v[36:39], v[176:179], v[224:227], v[36:39]
	v_mfma_f32_16x16x32_bf16 v[32:35], v[192:195], v[224:227], v[32:35]
	s_setprio 0
	s_barrier
	s_add_i32 vcc_lo, s76, s15
	v_lshl_add_u64 v[168:169], s[88:89], 0, v[134:135]
	s_mov_b32 m0, vcc_lo
	ds_read_b128 v[196:199], v184 offset:16384
	ds_read_b128 v[200:203], v184 offset:17408
	ds_read_b128 v[204:207], v184 offset:18432
	ds_read_b128 v[208:211], v184 offset:19456
	ds_read_b128 v[212:215], v184 offset:20480
	ds_read_b128 v[216:219], v184 offset:21504
	ds_read_b128 v[220:223], v184 offset:22528
	ds_read_b128 v[224:227], v184 offset:23552
	global_load_lds_dwordx4 v[168:169], off
	s_add_i32 m0, vcc_lo, 0x2000
	s_add_u32 vcc_lo, s88, 0x40000
	v_lshl_add_u64 v[172:173], s[88:89], 0, v[138:139]
	s_addc_u32 vcc_hi, s89, 0
	s_add_i32 s6, s77, s15
	global_load_lds_dwordx4 v[172:173], off
	v_lshl_add_u64 v[180:181], vcc, 0, v[134:135]
	s_mov_b32 m0, s6
	v_lshl_add_u64 v[228:229], s[92:93], 0, v[136:137]
	global_load_lds_dwordx4 v[180:181], off
	v_lshl_add_u64 v[180:181], vcc, 0, v[138:139]
	s_add_i32 m0, s6, 0x2000
	s_nop 0
	global_load_lds_dwordx4 v[180:181], off
	v_lshl_add_u64 v[180:181], s[92:93], 0, v[132:133]
	s_mov_b32 m0, s41
	s_nop 0
	global_load_lds_dwordx4 v[180:181], off
	s_mov_b32 m0, s52
	s_nop 0
	global_load_lds_dwordx4 v[228:229], off
	s_waitcnt vmcnt(8)
	s_waitcnt lgkmcnt(0)
	s_setprio 1
	s_barrier
	s_waitcnt lgkmcnt(0)
	v_mfma_f32_16x16x32_bf16 v[28:31], v[128:131], v[196:199], v[28:31]
	v_mfma_f32_16x16x32_bf16 v[24:27], v[154:157], v[196:199], v[24:27]
	v_mfma_f32_16x16x32_bf16 v[20:23], v[128:131], v[204:207], v[20:23]
	v_mfma_f32_16x16x32_bf16 v[16:19], v[154:157], v[204:207], v[16:19]
	v_mfma_f32_16x16x32_bf16 v[12:15], v[128:131], v[212:215], v[12:15]
	v_mfma_f32_16x16x32_bf16 v[8:11], v[154:157], v[212:215], v[8:11]
	v_mfma_f32_16x16x32_bf16 v[4:7], v[128:131], v[220:223], v[4:7]
	v_mfma_f32_16x16x32_bf16 v[0:3], v[154:157], v[220:223], v[0:3]
	v_mfma_f32_16x16x32_bf16 v[28:31], v[150:153], v[200:203], v[28:31]
	v_mfma_f32_16x16x32_bf16 v[24:27], v[158:161], v[200:203], v[24:27]
	v_mfma_f32_16x16x32_bf16 v[20:23], v[150:153], v[208:211], v[20:23]
	v_mfma_f32_16x16x32_bf16 v[16:19], v[158:161], v[208:211], v[16:19]
	v_mfma_f32_16x16x32_bf16 v[12:15], v[150:153], v[216:219], v[12:15]
	v_mfma_f32_16x16x32_bf16 v[8:11], v[158:161], v[216:219], v[8:11]
	v_mfma_f32_16x16x32_bf16 v[4:7], v[150:153], v[224:227], v[4:7]
	v_mfma_f32_16x16x32_bf16 v[0:3], v[158:161], v[224:227], v[0:3]
	s_setprio 0
	s_setprio 1
	v_mfma_f32_16x16x32_bf16 v[124:127], v[162:165], v[196:199], v[124:127]
	v_mfma_f32_16x16x32_bf16 v[120:123], v[188:191], v[196:199], v[120:123]
	v_mfma_f32_16x16x32_bf16 v[116:119], v[162:165], v[204:207], v[116:119]
	v_mfma_f32_16x16x32_bf16 v[112:115], v[188:191], v[204:207], v[112:115]
	v_mfma_f32_16x16x32_bf16 v[108:111], v[162:165], v[212:215], v[108:111]
	v_mfma_f32_16x16x32_bf16 v[104:107], v[188:191], v[212:215], v[104:107]
	v_mfma_f32_16x16x32_bf16 v[100:103], v[162:165], v[220:223], v[100:103]
	v_mfma_f32_16x16x32_bf16 v[96:99], v[188:191], v[220:223], v[96:99]
	v_mfma_f32_16x16x32_bf16 v[124:127], v[176:179], v[200:203], v[124:127]
	v_mfma_f32_16x16x32_bf16 v[120:123], v[192:195], v[200:203], v[120:123]
	v_mfma_f32_16x16x32_bf16 v[116:119], v[176:179], v[208:211], v[116:119]
	v_mfma_f32_16x16x32_bf16 v[112:115], v[192:195], v[208:211], v[112:115]
	v_mfma_f32_16x16x32_bf16 v[108:111], v[176:179], v[216:219], v[108:111]
	v_mfma_f32_16x16x32_bf16 v[104:107], v[192:195], v[216:219], v[104:107]
	v_mfma_f32_16x16x32_bf16 v[100:103], v[176:179], v[224:227], v[100:103]
	v_mfma_f32_16x16x32_bf16 v[96:99], v[192:195], v[224:227], v[96:99]
	s_setprio 0
	s_barrier
	s_add_i32 s6, 0, 0x18000
	s_add_i32 s7, 0, 0x1c000
	v_add_u32_e32 v158, s6, v171
	v_add_u32_e32 v166, s7, v171
	ds_read_b128 v[128:131], v158
	ds_read_b128 v[150:153], v158 offset:1024
	ds_read_b128 v[154:157], v158 offset:2048
	ds_read_b128 v[158:161], v158 offset:3072
	ds_read_b128 v[162:165], v166
	ds_read_b128 v[176:179], v166 offset:1024
	ds_read_b128 v[188:191], v166 offset:2048
	ds_read_b128 v[192:195], v166 offset:3072
	s_and_b64 s[90:91], s[62:63], s[90:91]
	s_and_b64 vcc, s[90:91], s[86:87]
	s_add_u32 s92, s92, 0x40000
	s_addc_u32 s93, s93, 0
	s_and_b64 s[90:91], vcc, exec
	s_mov_b32 m0, s53
	v_cndmask_b32_e32 v166, v132, v134, vcc
	s_cselect_b32 s91, s4, s93
	s_cselect_b32 s90, s68, s92
	ds_read_b128 v[196:199], v184 offset:32768
	ds_read_b128 v[200:203], v184 offset:33792
	ds_read_b128 v[204:207], v184 offset:34816
	ds_read_b128 v[208:211], v184 offset:35840
	ds_read_b128 v[212:215], v184 offset:36864
	ds_read_b128 v[216:219], v184 offset:37888
	ds_read_b128 v[220:223], v184 offset:38912
	ds_read_b128 v[224:227], v184 offset:39936
	v_cndmask_b32_e32 v170, v136, v138, vcc
	global_load_lds_dwordx4 v166, s[90:91]
	s_mov_b32 m0, s54
	s_nop 0
	global_load_lds_dwordx4 v170, s[90:91]
	s_waitcnt vmcnt(8)
	s_waitcnt lgkmcnt(0)
	s_setprio 1
	s_barrier
	s_waitcnt lgkmcnt(0)
	v_mfma_f32_16x16x32_bf16 v[92:95], v[128:131], v[196:199], v[92:95]
	v_mfma_f32_16x16x32_bf16 v[88:91], v[154:157], v[196:199], v[88:91]
	v_mfma_f32_16x16x32_bf16 v[84:87], v[128:131], v[204:207], v[84:87]
	v_mfma_f32_16x16x32_bf16 v[80:83], v[154:157], v[204:207], v[80:83]
	v_mfma_f32_16x16x32_bf16 v[68:71], v[128:131], v[212:215], v[68:71]
	v_mfma_f32_16x16x32_bf16 v[64:67], v[154:157], v[212:215], v[64:67]
	v_mfma_f32_16x16x32_bf16 v[52:55], v[128:131], v[220:223], v[52:55]
	v_mfma_f32_16x16x32_bf16 v[48:51], v[154:157], v[220:223], v[48:51]
	v_mfma_f32_16x16x32_bf16 v[92:95], v[150:153], v[200:203], v[92:95]
	v_mfma_f32_16x16x32_bf16 v[88:91], v[158:161], v[200:203], v[88:91]
	v_mfma_f32_16x16x32_bf16 v[84:87], v[150:153], v[208:211], v[84:87]
	v_mfma_f32_16x16x32_bf16 v[80:83], v[158:161], v[208:211], v[80:83]
	v_mfma_f32_16x16x32_bf16 v[68:71], v[150:153], v[216:219], v[68:71]
	v_mfma_f32_16x16x32_bf16 v[64:67], v[158:161], v[216:219], v[64:67]
	v_mfma_f32_16x16x32_bf16 v[52:55], v[150:153], v[224:227], v[52:55]
	v_mfma_f32_16x16x32_bf16 v[48:51], v[158:161], v[224:227], v[48:51]
	s_setprio 0
	s_setprio 1
	v_mfma_f32_16x16x32_bf16 v[76:79], v[162:165], v[196:199], v[76:79]
	v_mfma_f32_16x16x32_bf16 v[72:75], v[188:191], v[196:199], v[72:75]
	v_mfma_f32_16x16x32_bf16 v[60:63], v[162:165], v[204:207], v[60:63]
	v_mfma_f32_16x16x32_bf16 v[56:59], v[188:191], v[204:207], v[56:59]
	v_mfma_f32_16x16x32_bf16 v[44:47], v[162:165], v[212:215], v[44:47]
	v_mfma_f32_16x16x32_bf16 v[40:43], v[188:191], v[212:215], v[40:43]
	v_mfma_f32_16x16x32_bf16 v[36:39], v[162:165], v[220:223], v[36:39]
	v_mfma_f32_16x16x32_bf16 v[32:35], v[188:191], v[220:223], v[32:35]
	v_mfma_f32_16x16x32_bf16 v[76:79], v[176:179], v[200:203], v[76:79]
	v_mfma_f32_16x16x32_bf16 v[72:75], v[192:195], v[200:203], v[72:75]
	v_mfma_f32_16x16x32_bf16 v[60:63], v[176:179], v[208:211], v[60:63]
	v_mfma_f32_16x16x32_bf16 v[56:59], v[192:195], v[208:211], v[56:59]
	v_mfma_f32_16x16x32_bf16 v[44:47], v[176:179], v[216:219], v[44:47]
	v_mfma_f32_16x16x32_bf16 v[40:43], v[192:195], v[216:219], v[40:43]
	v_mfma_f32_16x16x32_bf16 v[36:39], v[176:179], v[224:227], v[36:39]
	v_mfma_f32_16x16x32_bf16 v[32:35], v[192:195], v[224:227], v[32:35]
	s_setprio 0
	s_barrier
	s_add_i32 s6, s6, s15
	v_lshl_add_u64 v[168:169], v[168:169], 0, s[10:11]
	s_mov_b32 m0, s6
	ds_read_b128 v[196:199], v184 offset:49152
	ds_read_b128 v[200:203], v184 offset:50176
	ds_read_b128 v[204:207], v184 offset:51200
	ds_read_b128 v[208:211], v184 offset:52224
	ds_read_b128 v[212:215], v184 offset:53248
	ds_read_b128 v[216:219], v184 offset:54272
	ds_read_b128 v[220:223], v184 offset:55296
	ds_read_b128 v[224:227], v184 offset:56320
	global_load_lds_dwordx4 v[168:169], off
	s_add_i32 m0, s6, 0x2000
	s_add_u32 s88, s88, 0x40080
	v_lshl_add_u64 v[168:169], v[172:173], 0, s[10:11]
	s_addc_u32 s89, s89, 0
	s_add_i32 s6, s7, s15
	global_load_lds_dwordx4 v[168:169], off
	v_lshl_add_u64 v[168:169], s[88:89], 0, v[134:135]
	s_mov_b32 m0, s6
	s_nop 0
	global_load_lds_dwordx4 v[168:169], off
	v_lshl_add_u64 v[168:169], s[88:89], 0, v[138:139]
	s_add_i32 m0, s6, 0x2000
	s_nop 0
	global_load_lds_dwordx4 v[168:169], off
	v_lshl_add_u64 v[168:169], v[180:181], 0, s[10:11]
	s_mov_b32 m0, s55
	s_nop 0
	global_load_lds_dwordx4 v[168:169], off
	v_lshl_add_u64 v[168:169], v[228:229], 0, s[10:11]
	s_mov_b32 m0, s56
	s_nop 0
	global_load_lds_dwordx4 v[168:169], off
	s_waitcnt vmcnt(8)
	s_waitcnt lgkmcnt(0)
	s_setprio 1
	s_barrier
	s_waitcnt lgkmcnt(0)
	v_mfma_f32_16x16x32_bf16 v[28:31], v[128:131], v[196:199], v[28:31]
	v_mfma_f32_16x16x32_bf16 v[24:27], v[154:157], v[196:199], v[24:27]
	v_mfma_f32_16x16x32_bf16 v[20:23], v[128:131], v[204:207], v[20:23]
	v_mfma_f32_16x16x32_bf16 v[16:19], v[154:157], v[204:207], v[16:19]
	v_mfma_f32_16x16x32_bf16 v[12:15], v[128:131], v[212:215], v[12:15]
	v_mfma_f32_16x16x32_bf16 v[8:11], v[154:157], v[212:215], v[8:11]
	v_mfma_f32_16x16x32_bf16 v[4:7], v[128:131], v[220:223], v[4:7]
	v_mfma_f32_16x16x32_bf16 v[0:3], v[154:157], v[220:223], v[0:3]
	v_mfma_f32_16x16x32_bf16 v[28:31], v[150:153], v[200:203], v[28:31]
	v_mfma_f32_16x16x32_bf16 v[24:27], v[158:161], v[200:203], v[24:27]
	v_mfma_f32_16x16x32_bf16 v[20:23], v[150:153], v[208:211], v[20:23]
	v_mfma_f32_16x16x32_bf16 v[16:19], v[158:161], v[208:211], v[16:19]
	v_mfma_f32_16x16x32_bf16 v[12:15], v[150:153], v[216:219], v[12:15]
	v_mfma_f32_16x16x32_bf16 v[8:11], v[158:161], v[216:219], v[8:11]
	v_mfma_f32_16x16x32_bf16 v[4:7], v[150:153], v[224:227], v[4:7]
	v_mfma_f32_16x16x32_bf16 v[0:3], v[158:161], v[224:227], v[0:3]
	s_setprio 0
	s_setprio 1
	v_mfma_f32_16x16x32_bf16 v[124:127], v[162:165], v[196:199], v[124:127]
	v_mfma_f32_16x16x32_bf16 v[120:123], v[188:191], v[196:199], v[120:123]
	v_mfma_f32_16x16x32_bf16 v[116:119], v[162:165], v[204:207], v[116:119]
	v_mfma_f32_16x16x32_bf16 v[112:115], v[188:191], v[204:207], v[112:115]
	v_mfma_f32_16x16x32_bf16 v[108:111], v[162:165], v[212:215], v[108:111]
	v_mfma_f32_16x16x32_bf16 v[104:107], v[188:191], v[212:215], v[104:107]
	v_mfma_f32_16x16x32_bf16 v[100:103], v[162:165], v[220:223], v[100:103]
	v_mfma_f32_16x16x32_bf16 v[96:99], v[188:191], v[220:223], v[96:99]
	v_mfma_f32_16x16x32_bf16 v[124:127], v[176:179], v[200:203], v[124:127]
	v_mfma_f32_16x16x32_bf16 v[120:123], v[192:195], v[200:203], v[120:123]
	v_mfma_f32_16x16x32_bf16 v[116:119], v[176:179], v[208:211], v[116:119]
	v_mfma_f32_16x16x32_bf16 v[112:115], v[192:195], v[208:211], v[112:115]
	v_mfma_f32_16x16x32_bf16 v[108:111], v[176:179], v[216:219], v[108:111]
	v_mfma_f32_16x16x32_bf16 v[104:107], v[192:195], v[216:219], v[104:107]
	v_mfma_f32_16x16x32_bf16 v[100:103], v[176:179], v[224:227], v[100:103]
	v_mfma_f32_16x16x32_bf16 v[96:99], v[192:195], v[224:227], v[96:99]
	s_setprio 0
	s_barrier
	s_add_i32 s5, s5, 2
	s_add_u32 s84, s84, 0x100
	s_addc_u32 s85, s85, 0
	s_add_u32 s69, s69, 0x100
	s_addc_u32 s71, s71, 0
	s_cmp_gt_u32 s5, 13
	s_cbranch_scc0 .LBB0_881

.LBB0_971:
	ds_read_b128 v[120:123], v237
	ds_read_b128 v[128:131], v237 offset:1024
	ds_read_b128 v[136:139], v237 offset:2048
	ds_read_b128 v[140:143], v237 offset:3072
	ds_read_b128 v[144:147], v238
	ds_read_b128 v[148:151], v238 offset:1024
	ds_read_b128 v[152:155], v238 offset:2048
	ds_read_b128 v[156:159], v238 offset:3072
	s_add_u32 s6, s4, 0xfffc0080
	s_addc_u32 s7, s5, -1
	s_cmp_eq_u32 s88, 12
	s_cselect_b32 s83, s65, s7
	s_cselect_b32 s82, s73, s6
	s_cselect_b32 s7, s67, s87
	s_cselect_b32 s6, s76, s86
	v_lshl_add_u64 v[210:211], s[4:5], 0, v[190:191]
	s_add_i32 m0, s53, 0xc000
	ds_read_b128 v[160:163], v239
	ds_read_b128 v[164:167], v239 offset:1024
	ds_read_b128 v[168:171], v239 offset:2048
	ds_read_b128 v[172:175], v239 offset:3072
	ds_read_b128 v[176:179], v239 offset:4096
	ds_read_b128 v[198:201], v239 offset:5120
	ds_read_b128 v[202:205], v239 offset:6144
	ds_read_b128 v[206:209], v239 offset:7168
	global_load_lds_dwordx4 v[210:211], off
	v_lshl_add_u64 v[210:211], s[4:5], 0, v[192:193]
	s_add_i32 m0, s53, 0xe000
	s_nop 0
	global_load_lds_dwordx4 v[210:211], off
	s_waitcnt vmcnt(8)
	s_waitcnt lgkmcnt(0)
	s_setprio 1
	s_barrier
	s_waitcnt lgkmcnt(0)
	v_mfma_f32_16x16x32_bf16 v[132:135], v[120:123], v[160:163], v[132:135]
	v_mfma_f32_16x16x32_bf16 v[124:127], v[136:139], v[160:163], v[124:127]
	v_mfma_f32_16x16x32_bf16 v[116:119], v[120:123], v[168:171], v[116:119]
	v_mfma_f32_16x16x32_bf16 v[112:115], v[136:139], v[168:171], v[112:115]
	v_mfma_f32_16x16x32_bf16 v[108:111], v[120:123], v[176:179], v[108:111]
	v_mfma_f32_16x16x32_bf16 v[104:107], v[136:139], v[176:179], v[104:107]
	v_mfma_f32_16x16x32_bf16 v[100:103], v[120:123], v[202:205], v[100:103]
	v_mfma_f32_16x16x32_bf16 v[96:99], v[136:139], v[202:205], v[96:99]
	v_mfma_f32_16x16x32_bf16 v[132:135], v[128:131], v[164:167], v[132:135]
	v_mfma_f32_16x16x32_bf16 v[124:127], v[140:143], v[164:167], v[124:127]
	v_mfma_f32_16x16x32_bf16 v[116:119], v[128:131], v[172:175], v[116:119]
	v_mfma_f32_16x16x32_bf16 v[112:115], v[140:143], v[172:175], v[112:115]
	v_mfma_f32_16x16x32_bf16 v[108:111], v[128:131], v[198:201], v[108:111]
	v_mfma_f32_16x16x32_bf16 v[104:107], v[140:143], v[198:201], v[104:107]
	v_mfma_f32_16x16x32_bf16 v[100:103], v[128:131], v[206:209], v[100:103]
	v_mfma_f32_16x16x32_bf16 v[96:99], v[140:143], v[206:209], v[96:99]
	s_setprio 0
	s_setprio 1
	v_mfma_f32_16x16x32_bf16 v[92:95], v[144:147], v[160:163], v[92:95]
	v_mfma_f32_16x16x32_bf16 v[88:91], v[152:155], v[160:163], v[88:91]
	v_mfma_f32_16x16x32_bf16 v[84:87], v[144:147], v[168:171], v[84:87]
	v_mfma_f32_16x16x32_bf16 v[80:83], v[152:155], v[168:171], v[80:83]
	v_mfma_f32_16x16x32_bf16 v[76:79], v[144:147], v[176:179], v[76:79]
	v_mfma_f32_16x16x32_bf16 v[72:75], v[152:155], v[176:179], v[72:75]
	v_mfma_f32_16x16x32_bf16 v[68:71], v[144:147], v[202:205], v[68:71]
	v_mfma_f32_16x16x32_bf16 v[64:67], v[152:155], v[202:205], v[64:67]
	v_mfma_f32_16x16x32_bf16 v[92:95], v[148:151], v[164:167], v[92:95]
	v_mfma_f32_16x16x32_bf16 v[88:91], v[156:159], v[164:167], v[88:91]
	v_mfma_f32_16x16x32_bf16 v[84:87], v[148:151], v[172:175], v[84:87]
	v_mfma_f32_16x16x32_bf16 v[80:83], v[156:159], v[172:175], v[80:83]
	v_mfma_f32_16x16x32_bf16 v[76:79], v[148:151], v[198:201], v[76:79]
	v_mfma_f32_16x16x32_bf16 v[72:75], v[156:159], v[198:201], v[72:75]
	v_mfma_f32_16x16x32_bf16 v[68:71], v[148:151], v[206:209], v[68:71]
	v_mfma_f32_16x16x32_bf16 v[64:67], v[156:159], v[206:209], v[64:67]
	s_setprio 0
	s_barrier
	s_add_i32 s89, s68, s52
	v_lshl_add_u64 v[210:211], s[6:7], 0, v[182:183]
	s_mov_b32 m0, s89
	ds_read_b128 v[160:163], v239 offset:16384
	ds_read_b128 v[164:167], v239 offset:17408
	ds_read_b128 v[168:171], v239 offset:18432
	ds_read_b128 v[172:175], v239 offset:19456
	ds_read_b128 v[176:179], v239 offset:20480
	ds_read_b128 v[198:201], v239 offset:21504
	ds_read_b128 v[202:205], v239 offset:22528
	ds_read_b128 v[206:209], v239 offset:23552
	global_load_lds_dwordx4 v[210:211], off
	s_add_i32 m0, s89, 0x2000
	s_add_u32 s90, s6, 0x40000
	v_lshl_add_u64 v[212:213], s[6:7], 0, v[186:187]
	s_addc_u32 s91, s7, 0
	s_add_i32 s89, s69, s52
	global_load_lds_dwordx4 v[212:213], off
	v_lshl_add_u64 v[214:215], s[90:91], 0, v[182:183]
	s_mov_b32 m0, s89
	v_lshl_add_u64 v[216:217], s[82:83], 0, v[184:185]
	global_load_lds_dwordx4 v[214:215], off
	v_lshl_add_u64 v[214:215], s[90:91], 0, v[186:187]
	s_add_i32 m0, s89, 0x2000
	s_nop 0
	global_load_lds_dwordx4 v[214:215], off
	v_lshl_add_u64 v[214:215], s[82:83], 0, v[180:181]
	s_mov_b32 m0, s53
	s_nop 0
	global_load_lds_dwordx4 v[214:215], off
	s_mov_b32 m0, s54
	s_nop 0
	global_load_lds_dwordx4 v[216:217], off
	s_waitcnt vmcnt(8)
	s_waitcnt lgkmcnt(0)
	s_setprio 1
	s_barrier
	s_waitcnt lgkmcnt(0)
	v_mfma_f32_16x16x32_bf16 v[60:63], v[120:123], v[160:163], v[60:63]
	v_mfma_f32_16x16x32_bf16 v[56:59], v[136:139], v[160:163], v[56:59]
	v_mfma_f32_16x16x32_bf16 v[52:55], v[120:123], v[168:171], v[52:55]
	v_mfma_f32_16x16x32_bf16 v[48:51], v[136:139], v[168:171], v[48:51]
	v_mfma_f32_16x16x32_bf16 v[44:47], v[120:123], v[176:179], v[44:47]
	v_mfma_f32_16x16x32_bf16 v[40:43], v[136:139], v[176:179], v[40:43]
	v_mfma_f32_16x16x32_bf16 v[36:39], v[120:123], v[202:205], v[36:39]
	v_mfma_f32_16x16x32_bf16 v[32:35], v[136:139], v[202:205], v[32:35]
	v_mfma_f32_16x16x32_bf16 v[60:63], v[128:131], v[164:167], v[60:63]
	v_mfma_f32_16x16x32_bf16 v[56:59], v[140:143], v[164:167], v[56:59]
	v_mfma_f32_16x16x32_bf16 v[52:55], v[128:131], v[172:175], v[52:55]
	v_mfma_f32_16x16x32_bf16 v[48:51], v[140:143], v[172:175], v[48:51]
	v_mfma_f32_16x16x32_bf16 v[44:47], v[128:131], v[198:201], v[44:47]
	v_mfma_f32_16x16x32_bf16 v[40:43], v[140:143], v[198:201], v[40:43]
	v_mfma_f32_16x16x32_bf16 v[36:39], v[128:131], v[206:209], v[36:39]
	v_mfma_f32_16x16x32_bf16 v[32:35], v[140:143], v[206:209], v[32:35]
	s_setprio 0
	s_setprio 1
	v_mfma_f32_16x16x32_bf16 v[28:31], v[144:147], v[160:163], v[28:31]
	v_mfma_f32_16x16x32_bf16 v[24:27], v[152:155], v[160:163], v[24:27]
	v_mfma_f32_16x16x32_bf16 v[20:23], v[144:147], v[168:171], v[20:23]
	v_mfma_f32_16x16x32_bf16 v[16:19], v[152:155], v[168:171], v[16:19]
	v_mfma_f32_16x16x32_bf16 v[12:15], v[144:147], v[176:179], v[12:15]
	v_mfma_f32_16x16x32_bf16 v[8:11], v[152:155], v[176:179], v[8:11]
	v_mfma_f32_16x16x32_bf16 v[4:7], v[144:147], v[202:205], v[4:7]
	v_mfma_f32_16x16x32_bf16 v[0:3], v[152:155], v[202:205], v[0:3]
	v_mfma_f32_16x16x32_bf16 v[28:31], v[148:151], v[164:167], v[28:31]
	v_mfma_f32_16x16x32_bf16 v[24:27], v[156:159], v[164:167], v[24:27]
	v_mfma_f32_16x16x32_bf16 v[20:23], v[148:151], v[172:175], v[20:23]
	v_mfma_f32_16x16x32_bf16 v[16:19], v[156:159], v[172:175], v[16:19]
	v_mfma_f32_16x16x32_bf16 v[12:15], v[148:151], v[198:201], v[12:15]
	v_mfma_f32_16x16x32_bf16 v[8:11], v[156:159], v[198:201], v[8:11]
	v_mfma_f32_16x16x32_bf16 v[4:7], v[148:151], v[206:209], v[4:7]
	v_mfma_f32_16x16x32_bf16 v[0:3], v[156:159], v[206:209], v[0:3]
	s_setprio 0
	s_barrier
	s_add_i32 s89, 0, 0x18000
	s_add_i32 s90, 0, 0x1c000
	v_add_u32_e32 v140, s89, v235
	v_add_u32_e32 v156, s90, v235
	ds_read_b128 v[120:123], v140
	ds_read_b128 v[128:131], v140 offset:1024
	ds_read_b128 v[136:139], v140 offset:2048
	ds_read_b128 v[140:143], v140 offset:3072
	ds_read_b128 v[144:147], v156
	ds_read_b128 v[148:151], v156 offset:1024
	ds_read_b128 v[152:155], v156 offset:2048
	ds_read_b128 v[156:159], v156 offset:3072
	s_add_u32 s82, s82, 0x40000
	s_addc_u32 s83, s83, 0
	s_mov_b32 m0, s55
	v_lshl_add_u64 v[218:219], s[82:83], 0, v[180:181]
	ds_read_b128 v[160:163], v239 offset:32768
	ds_read_b128 v[164:167], v239 offset:33792
	ds_read_b128 v[168:171], v239 offset:34816
	ds_read_b128 v[172:175], v239 offset:35840
	ds_read_b128 v[176:179], v239 offset:36864
	ds_read_b128 v[198:201], v239 offset:37888
	ds_read_b128 v[202:205], v239 offset:38912
	ds_read_b128 v[206:209], v239 offset:39936
	global_load_lds_dwordx4 v[218:219], off
	v_lshl_add_u64 v[218:219], s[82:83], 0, v[184:185]
	s_mov_b32 m0, s56
	s_nop 0
	global_load_lds_dwordx4 v[218:219], off
	s_waitcnt vmcnt(8)
	s_waitcnt lgkmcnt(0)
	s_setprio 1
	s_barrier
	s_waitcnt lgkmcnt(0)
	v_mfma_f32_16x16x32_bf16 v[132:135], v[120:123], v[160:163], v[132:135]
	v_mfma_f32_16x16x32_bf16 v[124:127], v[136:139], v[160:163], v[124:127]
	v_mfma_f32_16x16x32_bf16 v[116:119], v[120:123], v[168:171], v[116:119]
	v_mfma_f32_16x16x32_bf16 v[112:115], v[136:139], v[168:171], v[112:115]
	v_mfma_f32_16x16x32_bf16 v[108:111], v[120:123], v[176:179], v[108:111]
	v_mfma_f32_16x16x32_bf16 v[104:107], v[136:139], v[176:179], v[104:107]
	v_mfma_f32_16x16x32_bf16 v[100:103], v[120:123], v[202:205], v[100:103]
	v_mfma_f32_16x16x32_bf16 v[96:99], v[136:139], v[202:205], v[96:99]
	v_mfma_f32_16x16x32_bf16 v[132:135], v[128:131], v[164:167], v[132:135]
	v_mfma_f32_16x16x32_bf16 v[124:127], v[140:143], v[164:167], v[124:127]
	v_mfma_f32_16x16x32_bf16 v[116:119], v[128:131], v[172:175], v[116:119]
	v_mfma_f32_16x16x32_bf16 v[112:115], v[140:143], v[172:175], v[112:115]
	v_mfma_f32_16x16x32_bf16 v[108:111], v[128:131], v[198:201], v[108:111]
	v_mfma_f32_16x16x32_bf16 v[104:107], v[140:143], v[198:201], v[104:107]
	v_mfma_f32_16x16x32_bf16 v[100:103], v[128:131], v[206:209], v[100:103]
	v_mfma_f32_16x16x32_bf16 v[96:99], v[140:143], v[206:209], v[96:99]
	s_setprio 0
	s_setprio 1
	v_mfma_f32_16x16x32_bf16 v[92:95], v[144:147], v[160:163], v[92:95]
	v_mfma_f32_16x16x32_bf16 v[88:91], v[152:155], v[160:163], v[88:91]
	v_mfma_f32_16x16x32_bf16 v[84:87], v[144:147], v[168:171], v[84:87]
	v_mfma_f32_16x16x32_bf16 v[80:83], v[152:155], v[168:171], v[80:83]
	v_mfma_f32_16x16x32_bf16 v[76:79], v[144:147], v[176:179], v[76:79]
	v_mfma_f32_16x16x32_bf16 v[72:75], v[152:155], v[176:179], v[72:75]
	v_mfma_f32_16x16x32_bf16 v[68:71], v[144:147], v[202:205], v[68:71]
	v_mfma_f32_16x16x32_bf16 v[64:67], v[152:155], v[202:205], v[64:67]
	v_mfma_f32_16x16x32_bf16 v[92:95], v[148:151], v[164:167], v[92:95]
	v_mfma_f32_16x16x32_bf16 v[88:91], v[156:159], v[164:167], v[88:91]
	v_mfma_f32_16x16x32_bf16 v[84:87], v[148:151], v[172:175], v[84:87]
	v_mfma_f32_16x16x32_bf16 v[80:83], v[156:159], v[172:175], v[80:83]
	v_mfma_f32_16x16x32_bf16 v[76:79], v[148:151], v[198:201], v[76:79]
	v_mfma_f32_16x16x32_bf16 v[72:75], v[156:159], v[198:201], v[72:75]
	v_mfma_f32_16x16x32_bf16 v[68:71], v[148:151], v[206:209], v[68:71]
	v_mfma_f32_16x16x32_bf16 v[64:67], v[156:159], v[206:209], v[64:67]
	s_setprio 0
	s_barrier
	s_add_i32 s82, s89, s52
	v_lshl_add_u64 v[210:211], v[210:211], 0, s[18:19]
	s_mov_b32 m0, s82
	ds_read_b128 v[160:163], v239 offset:49152
	ds_read_b128 v[164:167], v239 offset:50176
	ds_read_b128 v[168:171], v239 offset:51200
	ds_read_b128 v[172:175], v239 offset:52224
	ds_read_b128 v[176:179], v239 offset:53248
	ds_read_b128 v[198:201], v239 offset:54272
	ds_read_b128 v[202:205], v239 offset:55296
	ds_read_b128 v[206:209], v239 offset:56320
	global_load_lds_dwordx4 v[210:211], off
	s_add_i32 m0, s82, 0x2000
	s_add_u32 s6, s6, 0x40080
	v_lshl_add_u64 v[210:211], v[212:213], 0, s[18:19]
	s_addc_u32 s7, s7, 0
	s_add_i32 s82, s90, s52
	global_load_lds_dwordx4 v[210:211], off
	v_lshl_add_u64 v[210:211], s[6:7], 0, v[182:183]
	s_mov_b32 m0, s82
	s_nop 0
	global_load_lds_dwordx4 v[210:211], off
	v_lshl_add_u64 v[210:211], s[6:7], 0, v[186:187]
	s_add_i32 m0, s82, 0x2000
	s_nop 0
	global_load_lds_dwordx4 v[210:211], off
	v_lshl_add_u64 v[210:211], v[214:215], 0, s[18:19]
	s_mov_b32 m0, s58
	s_nop 0
	global_load_lds_dwordx4 v[210:211], off
	v_lshl_add_u64 v[210:211], v[216:217], 0, s[18:19]
	s_mov_b32 m0, s59
	s_nop 0
	global_load_lds_dwordx4 v[210:211], off
	s_waitcnt vmcnt(8)
	s_waitcnt lgkmcnt(0)
	s_setprio 1
	s_barrier
	s_waitcnt lgkmcnt(0)
	v_mfma_f32_16x16x32_bf16 v[60:63], v[120:123], v[160:163], v[60:63]
	v_mfma_f32_16x16x32_bf16 v[56:59], v[136:139], v[160:163], v[56:59]
	v_mfma_f32_16x16x32_bf16 v[52:55], v[120:123], v[168:171], v[52:55]
	v_mfma_f32_16x16x32_bf16 v[48:51], v[136:139], v[168:171], v[48:51]
	v_mfma_f32_16x16x32_bf16 v[44:47], v[120:123], v[176:179], v[44:47]
	v_mfma_f32_16x16x32_bf16 v[40:43], v[136:139], v[176:179], v[40:43]
	v_mfma_f32_16x16x32_bf16 v[36:39], v[120:123], v[202:205], v[36:39]
	v_mfma_f32_16x16x32_bf16 v[32:35], v[136:139], v[202:205], v[32:35]
	v_mfma_f32_16x16x32_bf16 v[60:63], v[128:131], v[164:167], v[60:63]
	v_mfma_f32_16x16x32_bf16 v[56:59], v[140:143], v[164:167], v[56:59]
	v_mfma_f32_16x16x32_bf16 v[52:55], v[128:131], v[172:175], v[52:55]
	v_mfma_f32_16x16x32_bf16 v[48:51], v[140:143], v[172:175], v[48:51]
	v_mfma_f32_16x16x32_bf16 v[44:47], v[128:131], v[198:201], v[44:47]
	v_mfma_f32_16x16x32_bf16 v[40:43], v[140:143], v[198:201], v[40:43]
	v_mfma_f32_16x16x32_bf16 v[36:39], v[128:131], v[206:209], v[36:39]
	v_mfma_f32_16x16x32_bf16 v[32:35], v[140:143], v[206:209], v[32:35]
	s_setprio 0
	s_setprio 1
	v_mfma_f32_16x16x32_bf16 v[28:31], v[144:147], v[160:163], v[28:31]
	v_mfma_f32_16x16x32_bf16 v[24:27], v[152:155], v[160:163], v[24:27]
	v_mfma_f32_16x16x32_bf16 v[20:23], v[144:147], v[168:171], v[20:23]
	v_mfma_f32_16x16x32_bf16 v[16:19], v[152:155], v[168:171], v[16:19]
	v_mfma_f32_16x16x32_bf16 v[12:15], v[144:147], v[176:179], v[12:15]
	v_mfma_f32_16x16x32_bf16 v[8:11], v[152:155], v[176:179], v[8:11]
	v_mfma_f32_16x16x32_bf16 v[4:7], v[144:147], v[202:205], v[4:7]
	v_mfma_f32_16x16x32_bf16 v[0:3], v[152:155], v[202:205], v[0:3]
	v_mfma_f32_16x16x32_bf16 v[28:31], v[148:151], v[164:167], v[28:31]
	v_mfma_f32_16x16x32_bf16 v[24:27], v[156:159], v[164:167], v[24:27]
	v_mfma_f32_16x16x32_bf16 v[20:23], v[148:151], v[172:175], v[20:23]
	v_mfma_f32_16x16x32_bf16 v[16:19], v[156:159], v[172:175], v[16:19]
	v_mfma_f32_16x16x32_bf16 v[12:15], v[148:151], v[198:201], v[12:15]
	v_mfma_f32_16x16x32_bf16 v[8:11], v[156:159], v[198:201], v[8:11]
	v_mfma_f32_16x16x32_bf16 v[4:7], v[148:151], v[206:209], v[4:7]
	v_mfma_f32_16x16x32_bf16 v[0:3], v[156:159], v[206:209], v[0:3]
	s_setprio 0
	s_barrier
	s_add_i32 s88, s88, 2
	s_add_u32 s4, s4, 0x100
	s_addc_u32 s5, s5, 0
	s_add_u32 s86, s86, 0x100
	s_addc_u32 s87, s87, 0
	s_cmp_gt_u32 s88, 13
	s_cbranch_scc0 .LBB0_971
	s_and_b64 vcc, exec, s[36:37]
	s_cbranch_vccz .LBB0_974
	s_barrier

.LBB0_1080:
	ds_read_b128 v[128:131], v187
	ds_read_b128 v[132:135], v187 offset:1024
	ds_read_b128 v[136:139], v187 offset:2048
	ds_read_b128 v[140:143], v187 offset:3072
	ds_read_b128 v[144:147], v188
	ds_read_b128 v[148:151], v188 offset:1024
	ds_read_b128 v[168:171], v188 offset:2048
	ds_read_b128 v[172:175], v188 offset:3072
	s_add_u32 s38, s36, 0x100
	s_addc_u32 s39, s37, 0
	s_cmp_eq_u32 s77, 40
	s_cselect_b32 s61, s5, s39
	s_cselect_b32 s60, s4, s38
	s_cselect_b32 s45, s7, s76
	s_cselect_b32 s44, s6, s73
	v_lshl_add_u64 v[216:217], s[36:37], 0, v[160:161]
	s_add_i32 m0, s54, 0xc000
	ds_read_b128 v[176:179], v189
	ds_read_b128 v[180:183], v189 offset:1024
	ds_read_b128 v[192:195], v189 offset:2048
	ds_read_b128 v[196:199], v189 offset:3072
	ds_read_b128 v[200:203], v189 offset:4096
	ds_read_b128 v[204:207], v189 offset:5120
	ds_read_b128 v[208:211], v189 offset:6144
	ds_read_b128 v[212:215], v189 offset:7168
	global_load_lds_dwordx4 v[216:217], off
	v_lshl_add_u64 v[216:217], s[36:37], 0, v[162:163]
	s_add_i32 m0, s54, 0xe000
	s_nop 0
	global_load_lds_dwordx4 v[216:217], off
	s_waitcnt vmcnt(8)
	s_waitcnt lgkmcnt(0)
	s_setprio 1
	s_barrier
	s_waitcnt lgkmcnt(0)
	v_mfma_f32_16x16x32_bf16 v[124:127], v[128:131], v[176:179], v[124:127]
	v_mfma_f32_16x16x32_bf16 v[120:123], v[136:139], v[176:179], v[120:123]
	v_mfma_f32_16x16x32_bf16 v[108:111], v[128:131], v[192:195], v[108:111]
	v_mfma_f32_16x16x32_bf16 v[104:107], v[136:139], v[192:195], v[104:107]
	v_mfma_f32_16x16x32_bf16 v[92:95], v[128:131], v[200:203], v[92:95]
	v_mfma_f32_16x16x32_bf16 v[88:91], v[136:139], v[200:203], v[88:91]
	v_mfma_f32_16x16x32_bf16 v[76:79], v[128:131], v[208:211], v[76:79]
	v_mfma_f32_16x16x32_bf16 v[72:75], v[136:139], v[208:211], v[72:75]
	v_mfma_f32_16x16x32_bf16 v[124:127], v[132:135], v[180:183], v[124:127]
	v_mfma_f32_16x16x32_bf16 v[120:123], v[140:143], v[180:183], v[120:123]
	v_mfma_f32_16x16x32_bf16 v[108:111], v[132:135], v[196:199], v[108:111]
	v_mfma_f32_16x16x32_bf16 v[104:107], v[140:143], v[196:199], v[104:107]
	v_mfma_f32_16x16x32_bf16 v[92:95], v[132:135], v[204:207], v[92:95]
	v_mfma_f32_16x16x32_bf16 v[88:91], v[140:143], v[204:207], v[88:91]
	v_mfma_f32_16x16x32_bf16 v[76:79], v[132:135], v[212:215], v[76:79]
	v_mfma_f32_16x16x32_bf16 v[72:75], v[140:143], v[212:215], v[72:75]
	s_setprio 0
	s_setprio 1
	v_mfma_f32_16x16x32_bf16 v[116:119], v[144:147], v[176:179], v[116:119]
	v_mfma_f32_16x16x32_bf16 v[112:115], v[168:171], v[176:179], v[112:115]
	v_mfma_f32_16x16x32_bf16 v[100:103], v[144:147], v[192:195], v[100:103]
	v_mfma_f32_16x16x32_bf16 v[96:99], v[168:171], v[192:195], v[96:99]
	v_mfma_f32_16x16x32_bf16 v[84:87], v[144:147], v[200:203], v[84:87]
	v_mfma_f32_16x16x32_bf16 v[80:83], v[168:171], v[200:203], v[80:83]
	v_mfma_f32_16x16x32_bf16 v[68:71], v[144:147], v[208:211], v[68:71]
	v_mfma_f32_16x16x32_bf16 v[64:67], v[168:171], v[208:211], v[64:67]
	v_mfma_f32_16x16x32_bf16 v[116:119], v[148:151], v[180:183], v[116:119]
	v_mfma_f32_16x16x32_bf16 v[112:115], v[172:175], v[180:183], v[112:115]
	v_mfma_f32_16x16x32_bf16 v[100:103], v[148:151], v[196:199], v[100:103]
	v_mfma_f32_16x16x32_bf16 v[96:99], v[172:175], v[196:199], v[96:99]
	v_mfma_f32_16x16x32_bf16 v[84:87], v[148:151], v[204:207], v[84:87]
	v_mfma_f32_16x16x32_bf16 v[80:83], v[172:175], v[204:207], v[80:83]
	v_mfma_f32_16x16x32_bf16 v[68:71], v[148:151], v[212:215], v[68:71]
	v_mfma_f32_16x16x32_bf16 v[64:67], v[172:175], v[212:215], v[64:67]
	s_setprio 0
	s_barrier
	s_add_i32 s36, s65, s53
	v_lshl_add_u64 v[216:217], s[44:45], 0, v[154:155]
	s_mov_b32 m0, s36
	ds_read_b128 v[176:179], v189 offset:16384
	ds_read_b128 v[180:183], v189 offset:17408
	ds_read_b128 v[192:195], v189 offset:18432
	ds_read_b128 v[196:199], v189 offset:19456
	ds_read_b128 v[200:203], v189 offset:20480
	ds_read_b128 v[204:207], v189 offset:21504
	ds_read_b128 v[208:211], v189 offset:22528
	ds_read_b128 v[212:215], v189 offset:23552
	global_load_lds_dwordx4 v[216:217], off
	s_add_i32 m0, s36, 0x2000
	s_add_u32 s36, s44, 0xb0000
	v_lshl_add_u64 v[218:219], s[44:45], 0, v[158:159]
	s_addc_u32 s37, s45, 0
	s_add_i32 s78, s66, s53
	global_load_lds_dwordx4 v[218:219], off
	v_lshl_add_u64 v[220:221], s[36:37], 0, v[154:155]
	s_mov_b32 m0, s78
	v_lshl_add_u64 v[222:223], s[60:61], 0, v[156:157]
	global_load_lds_dwordx4 v[220:221], off
	v_lshl_add_u64 v[220:221], s[36:37], 0, v[158:159]
	s_add_i32 m0, s78, 0x2000
	s_nop 0
	global_load_lds_dwordx4 v[220:221], off
	v_lshl_add_u64 v[220:221], s[60:61], 0, v[152:153]
	s_mov_b32 m0, s54
	s_nop 0
	global_load_lds_dwordx4 v[220:221], off
	s_mov_b32 m0, s55
	s_nop 0
	global_load_lds_dwordx4 v[222:223], off
	s_waitcnt vmcnt(8)
	s_waitcnt lgkmcnt(0)
	s_setprio 1
	s_barrier
	s_waitcnt lgkmcnt(0)
	v_mfma_f32_16x16x32_bf16 v[60:63], v[128:131], v[176:179], v[60:63]
	v_mfma_f32_16x16x32_bf16 v[56:59], v[136:139], v[176:179], v[56:59]
	v_mfma_f32_16x16x32_bf16 v[44:47], v[128:131], v[192:195], v[44:47]
	v_mfma_f32_16x16x32_bf16 v[40:43], v[136:139], v[192:195], v[40:43]
	v_mfma_f32_16x16x32_bf16 v[28:31], v[128:131], v[200:203], v[28:31]
	v_mfma_f32_16x16x32_bf16 v[24:27], v[136:139], v[200:203], v[24:27]
	v_mfma_f32_16x16x32_bf16 v[12:15], v[128:131], v[208:211], v[12:15]
	v_mfma_f32_16x16x32_bf16 v[8:11], v[136:139], v[208:211], v[8:11]
	v_mfma_f32_16x16x32_bf16 v[60:63], v[132:135], v[180:183], v[60:63]
	v_mfma_f32_16x16x32_bf16 v[56:59], v[140:143], v[180:183], v[56:59]
	v_mfma_f32_16x16x32_bf16 v[44:47], v[132:135], v[196:199], v[44:47]
	v_mfma_f32_16x16x32_bf16 v[40:43], v[140:143], v[196:199], v[40:43]
	v_mfma_f32_16x16x32_bf16 v[28:31], v[132:135], v[204:207], v[28:31]
	v_mfma_f32_16x16x32_bf16 v[24:27], v[140:143], v[204:207], v[24:27]
	v_mfma_f32_16x16x32_bf16 v[12:15], v[132:135], v[212:215], v[12:15]
	v_mfma_f32_16x16x32_bf16 v[8:11], v[140:143], v[212:215], v[8:11]
	s_setprio 0
	s_setprio 1
	v_mfma_f32_16x16x32_bf16 v[52:55], v[144:147], v[176:179], v[52:55]
	v_mfma_f32_16x16x32_bf16 v[48:51], v[168:171], v[176:179], v[48:51]
	v_mfma_f32_16x16x32_bf16 v[36:39], v[144:147], v[192:195], v[36:39]
	v_mfma_f32_16x16x32_bf16 v[32:35], v[168:171], v[192:195], v[32:35]
	v_mfma_f32_16x16x32_bf16 v[20:23], v[144:147], v[200:203], v[20:23]
	v_mfma_f32_16x16x32_bf16 v[16:19], v[168:171], v[200:203], v[16:19]
	v_mfma_f32_16x16x32_bf16 v[4:7], v[144:147], v[208:211], v[4:7]
	v_mfma_f32_16x16x32_bf16 v[0:3], v[168:171], v[208:211], v[0:3]
	v_mfma_f32_16x16x32_bf16 v[52:55], v[148:151], v[180:183], v[52:55]
	v_mfma_f32_16x16x32_bf16 v[48:51], v[172:175], v[180:183], v[48:51]
	v_mfma_f32_16x16x32_bf16 v[36:39], v[148:151], v[196:199], v[36:39]
	v_mfma_f32_16x16x32_bf16 v[32:35], v[172:175], v[196:199], v[32:35]
	v_mfma_f32_16x16x32_bf16 v[20:23], v[148:151], v[204:207], v[20:23]
	v_mfma_f32_16x16x32_bf16 v[16:19], v[172:175], v[204:207], v[16:19]
	v_mfma_f32_16x16x32_bf16 v[4:7], v[148:151], v[212:215], v[4:7]
	v_mfma_f32_16x16x32_bf16 v[0:3], v[172:175], v[212:215], v[0:3]
	s_setprio 0
	s_barrier
	s_add_i32 s78, 0, 0x18000
	s_add_i32 s79, 0, 0x1c000
	v_add_u32_e32 v140, s78, v185
	v_add_u32_e32 v172, s79, v185
	ds_read_b128 v[128:131], v140
	ds_read_b128 v[132:135], v140 offset:1024
	ds_read_b128 v[136:139], v140 offset:2048
	ds_read_b128 v[140:143], v140 offset:3072
	ds_read_b128 v[144:147], v172
	ds_read_b128 v[148:151], v172 offset:1024
	ds_read_b128 v[168:171], v172 offset:2048
	ds_read_b128 v[172:175], v172 offset:3072
	s_add_u32 s36, s60, 0xb0000
	s_addc_u32 s37, s61, 0
	s_mov_b32 m0, s56
	v_lshl_add_u64 v[224:225], s[36:37], 0, v[152:153]
	ds_read_b128 v[176:179], v189 offset:32768
	ds_read_b128 v[180:183], v189 offset:33792
	ds_read_b128 v[192:195], v189 offset:34816
	ds_read_b128 v[196:199], v189 offset:35840
	ds_read_b128 v[200:203], v189 offset:36864
	ds_read_b128 v[204:207], v189 offset:37888
	ds_read_b128 v[208:211], v189 offset:38912
	ds_read_b128 v[212:215], v189 offset:39936
	global_load_lds_dwordx4 v[224:225], off
	v_lshl_add_u64 v[224:225], s[36:37], 0, v[156:157]
	s_mov_b32 m0, s57
	s_nop 0
	global_load_lds_dwordx4 v[224:225], off
	s_waitcnt vmcnt(8)
	s_waitcnt lgkmcnt(0)
	s_setprio 1
	s_barrier
	s_waitcnt lgkmcnt(0)
	v_mfma_f32_16x16x32_bf16 v[124:127], v[128:131], v[176:179], v[124:127]
	v_mfma_f32_16x16x32_bf16 v[120:123], v[136:139], v[176:179], v[120:123]
	v_mfma_f32_16x16x32_bf16 v[108:111], v[128:131], v[192:195], v[108:111]
	v_mfma_f32_16x16x32_bf16 v[104:107], v[136:139], v[192:195], v[104:107]
	v_mfma_f32_16x16x32_bf16 v[92:95], v[128:131], v[200:203], v[92:95]
	v_mfma_f32_16x16x32_bf16 v[88:91], v[136:139], v[200:203], v[88:91]
	v_mfma_f32_16x16x32_bf16 v[76:79], v[128:131], v[208:211], v[76:79]
	v_mfma_f32_16x16x32_bf16 v[72:75], v[136:139], v[208:211], v[72:75]
	v_mfma_f32_16x16x32_bf16 v[124:127], v[132:135], v[180:183], v[124:127]
	v_mfma_f32_16x16x32_bf16 v[120:123], v[140:143], v[180:183], v[120:123]
	v_mfma_f32_16x16x32_bf16 v[108:111], v[132:135], v[196:199], v[108:111]
	v_mfma_f32_16x16x32_bf16 v[104:107], v[140:143], v[196:199], v[104:107]
	v_mfma_f32_16x16x32_bf16 v[92:95], v[132:135], v[204:207], v[92:95]
	v_mfma_f32_16x16x32_bf16 v[88:91], v[140:143], v[204:207], v[88:91]
	v_mfma_f32_16x16x32_bf16 v[76:79], v[132:135], v[212:215], v[76:79]
	v_mfma_f32_16x16x32_bf16 v[72:75], v[140:143], v[212:215], v[72:75]
	s_setprio 0
	s_setprio 1
	v_mfma_f32_16x16x32_bf16 v[116:119], v[144:147], v[176:179], v[116:119]
	v_mfma_f32_16x16x32_bf16 v[112:115], v[168:171], v[176:179], v[112:115]
	v_mfma_f32_16x16x32_bf16 v[100:103], v[144:147], v[192:195], v[100:103]
	v_mfma_f32_16x16x32_bf16 v[96:99], v[168:171], v[192:195], v[96:99]
	v_mfma_f32_16x16x32_bf16 v[84:87], v[144:147], v[200:203], v[84:87]
	v_mfma_f32_16x16x32_bf16 v[80:83], v[168:171], v[200:203], v[80:83]
	v_mfma_f32_16x16x32_bf16 v[68:71], v[144:147], v[208:211], v[68:71]
	v_mfma_f32_16x16x32_bf16 v[64:67], v[168:171], v[208:211], v[64:67]
	v_mfma_f32_16x16x32_bf16 v[116:119], v[148:151], v[180:183], v[116:119]
	v_mfma_f32_16x16x32_bf16 v[112:115], v[172:175], v[180:183], v[112:115]
	v_mfma_f32_16x16x32_bf16 v[100:103], v[148:151], v[196:199], v[100:103]
	v_mfma_f32_16x16x32_bf16 v[96:99], v[172:175], v[196:199], v[96:99]
	v_mfma_f32_16x16x32_bf16 v[84:87], v[148:151], v[204:207], v[84:87]
	v_mfma_f32_16x16x32_bf16 v[80:83], v[172:175], v[204:207], v[80:83]
	v_mfma_f32_16x16x32_bf16 v[68:71], v[148:151], v[212:215], v[68:71]
	v_mfma_f32_16x16x32_bf16 v[64:67], v[172:175], v[212:215], v[64:67]
	s_setprio 0
	s_barrier
	s_add_i32 s36, s78, s53
	v_lshl_add_u64 v[216:217], v[216:217], 0, s[14:15]
	s_mov_b32 m0, s36
	ds_read_b128 v[176:179], v189 offset:49152
	ds_read_b128 v[180:183], v189 offset:50176
	ds_read_b128 v[192:195], v189 offset:51200
	ds_read_b128 v[196:199], v189 offset:52224
	ds_read_b128 v[200:203], v189 offset:53248
	ds_read_b128 v[204:207], v189 offset:54272
	ds_read_b128 v[208:211], v189 offset:55296
	ds_read_b128 v[212:215], v189 offset:56320
	global_load_lds_dwordx4 v[216:217], off
	s_add_i32 m0, s36, 0x2000
	s_add_u32 s36, s44, 0xb0080
	v_lshl_add_u64 v[216:217], v[218:219], 0, s[14:15]
	s_addc_u32 s37, s45, 0
	s_add_i32 s44, s79, s53
	global_load_lds_dwordx4 v[216:217], off
	v_lshl_add_u64 v[216:217], s[36:37], 0, v[154:155]
	s_mov_b32 m0, s44
	s_nop 0
	global_load_lds_dwordx4 v[216:217], off
	v_lshl_add_u64 v[216:217], s[36:37], 0, v[158:159]
	s_add_i32 m0, s44, 0x2000
	s_nop 0
	global_load_lds_dwordx4 v[216:217], off
	v_lshl_add_u64 v[216:217], v[220:221], 0, s[14:15]
	s_mov_b32 m0, s59
	s_nop 0
	global_load_lds_dwordx4 v[216:217], off
	v_lshl_add_u64 v[216:217], v[222:223], 0, s[14:15]
	s_mov_b32 m0, s62
	s_nop 0
	global_load_lds_dwordx4 v[216:217], off
	s_waitcnt vmcnt(8)
	s_waitcnt lgkmcnt(0)
	s_setprio 1
	s_barrier
	s_waitcnt lgkmcnt(0)
	v_mfma_f32_16x16x32_bf16 v[60:63], v[128:131], v[176:179], v[60:63]
	v_mfma_f32_16x16x32_bf16 v[56:59], v[136:139], v[176:179], v[56:59]
	v_mfma_f32_16x16x32_bf16 v[44:47], v[128:131], v[192:195], v[44:47]
	v_mfma_f32_16x16x32_bf16 v[40:43], v[136:139], v[192:195], v[40:43]
	v_mfma_f32_16x16x32_bf16 v[28:31], v[128:131], v[200:203], v[28:31]
	v_mfma_f32_16x16x32_bf16 v[24:27], v[136:139], v[200:203], v[24:27]
	v_mfma_f32_16x16x32_bf16 v[12:15], v[128:131], v[208:211], v[12:15]
	v_mfma_f32_16x16x32_bf16 v[8:11], v[136:139], v[208:211], v[8:11]
	v_mfma_f32_16x16x32_bf16 v[60:63], v[132:135], v[180:183], v[60:63]
	v_mfma_f32_16x16x32_bf16 v[56:59], v[140:143], v[180:183], v[56:59]
	v_mfma_f32_16x16x32_bf16 v[44:47], v[132:135], v[196:199], v[44:47]
	v_mfma_f32_16x16x32_bf16 v[40:43], v[140:143], v[196:199], v[40:43]
	v_mfma_f32_16x16x32_bf16 v[28:31], v[132:135], v[204:207], v[28:31]
	v_mfma_f32_16x16x32_bf16 v[24:27], v[140:143], v[204:207], v[24:27]
	v_mfma_f32_16x16x32_bf16 v[12:15], v[132:135], v[212:215], v[12:15]
	v_mfma_f32_16x16x32_bf16 v[8:11], v[140:143], v[212:215], v[8:11]
	s_setprio 0
	s_setprio 1
	v_mfma_f32_16x16x32_bf16 v[52:55], v[144:147], v[176:179], v[52:55]
	v_mfma_f32_16x16x32_bf16 v[48:51], v[168:171], v[176:179], v[48:51]
	v_mfma_f32_16x16x32_bf16 v[36:39], v[144:147], v[192:195], v[36:39]
	v_mfma_f32_16x16x32_bf16 v[32:35], v[168:171], v[192:195], v[32:35]
	v_mfma_f32_16x16x32_bf16 v[20:23], v[144:147], v[200:203], v[20:23]
	v_mfma_f32_16x16x32_bf16 v[16:19], v[168:171], v[200:203], v[16:19]
	v_mfma_f32_16x16x32_bf16 v[4:7], v[144:147], v[208:211], v[4:7]
	v_mfma_f32_16x16x32_bf16 v[0:3], v[168:171], v[208:211], v[0:3]
	v_mfma_f32_16x16x32_bf16 v[52:55], v[148:151], v[180:183], v[52:55]
	v_mfma_f32_16x16x32_bf16 v[48:51], v[172:175], v[180:183], v[48:51]
	v_mfma_f32_16x16x32_bf16 v[36:39], v[148:151], v[196:199], v[36:39]
	v_mfma_f32_16x16x32_bf16 v[32:35], v[172:175], v[196:199], v[32:35]
	v_mfma_f32_16x16x32_bf16 v[20:23], v[148:151], v[204:207], v[20:23]
	v_mfma_f32_16x16x32_bf16 v[16:19], v[172:175], v[204:207], v[16:19]
	v_mfma_f32_16x16x32_bf16 v[4:7], v[148:151], v[212:215], v[4:7]
	v_mfma_f32_16x16x32_bf16 v[0:3], v[172:175], v[212:215], v[0:3]
	s_setprio 0
	s_barrier
	s_add_i32 s77, s77, 2
	s_add_u32 s73, s73, 0x100
	s_addc_u32 s76, s76, 0
	s_cmp_gt_u32 s77, 41
	s_mov_b64 s[36:37], s[38:39]
	s_cbranch_scc0 .LBB0_1080
	v_lshl_add_u32 v168, s72, 8, v184
	v_lshl_or_b32 v128, s18, 8, v186
	v_ashrrev_i32_e32 v169, 31, v168
	v_ashrrev_i32_e32 v129, 31, v128
	v_lshlrev_b64 v[130:131], 11, v[168:169]
	v_lshl_add_u64 v[130:131], s[34:35], 0, v[130:131]
	v_lshlrev_b64 v[170:171], 1, v[128:129]
	v_lshl_add_u64 v[200:201], v[130:131], 0, v[170:171]
	global_load_dwordx4 v[192:195], v[200:201], off
	global_load_dwordx4 v[196:199], v[200:201], off offset:256
	v_or_b32_e32 v180, 16, v168
	v_or_b32_e32 v176, 32, v168
	v_or_b32_e32 v172, 48, v168
	v_ashrrev_i32_e32 v181, 31, v180
	v_ashrrev_i32_e32 v177, 31, v176
	v_ashrrev_i32_e32 v173, 31, v172
	v_lshlrev_b64 v[128:129], 11, v[180:181]
	v_lshlrev_b64 v[130:131], 11, v[176:177]
	v_lshlrev_b64 v[132:133], 11, v[172:173]
	v_lshl_add_u64 v[128:129], s[34:35], 0, v[128:129]
	v_lshl_add_u64 v[130:131], s[34:35], 0, v[130:131]
	v_lshl_add_u64 v[132:133], s[34:35], 0, v[132:133]
	v_lshl_add_u64 v[182:183], v[128:129], 0, v[170:171]
	v_lshl_add_u64 v[178:179], v[130:131], 0, v[170:171]
	v_lshl_add_u64 v[174:175], v[132:133], 0, v[170:171]
	global_load_dwordx4 v[148:151], v[182:183], off
	global_load_dwordx4 v[144:147], v[182:183], off offset:256
	global_load_dwordx4 v[140:143], v[178:179], off
	global_load_dwordx4 v[136:139], v[178:179], off offset:256
	global_load_dwordx4 v[132:135], v[174:175], off
	global_load_dwordx4 v[128:131], v[174:175], off offset:256
	v_and_b32_e32 v202, 64, v190
	v_xor_b32_e32 v191, 16, v190
	v_add_u32_e32 v202, 64, v202
	v_xor_b32_e32 v203, 32, v190
	v_cmp_lt_i32_e32 vcc, v191, v202
	s_lshl_b32 s36, s18, 2
	s_ashr_i32 s37, s36, 31
	v_cndmask_b32_e32 v191, v190, v191, vcc
	v_cmp_lt_i32_e32 vcc, v203, v202
	v_lshlrev_b32_e32 v191, 2, v191
	s_waitcnt vmcnt(0)
	v_lshlrev_b32_e32 v202, 16, v192
	v_cndmask_b32_e32 v210, v190, v203, vcc
	v_and_b32_e32 v203, 0xffff0000, v192
	v_lshlrev_b32_e32 v192, 16, v193
	v_and_b32_e32 v193, 0xffff0000, v193
	v_lshlrev_b32_e32 v204, 16, v194
	v_and_b32_e32 v205, 0xffff0000, v194
	v_lshlrev_b32_e32 v194, 16, v195
	v_and_b32_e32 v195, 0xffff0000, v195
	v_lshlrev_b32_e32 v206, 16, v196
	v_and_b32_e32 v207, 0xffff0000, v196
	v_lshlrev_b32_e32 v196, 16, v197
	v_and_b32_e32 v197, 0xffff0000, v197
	v_lshlrev_b32_e32 v208, 16, v198
	v_and_b32_e32 v209, 0xffff0000, v198
	v_lshlrev_b32_e32 v198, 16, v199
	v_and_b32_e32 v199, 0xffff0000, v199
	v_pk_add_f32 v[126:127], v[126:127], v[192:193]
	v_pk_add_f32 v[124:125], v[124:125], v[202:203]
	v_pk_add_f32 v[122:123], v[122:123], v[194:195]
	v_pk_add_f32 v[120:121], v[120:121], v[204:205]
	v_pk_add_f32 v[118:119], v[118:119], v[196:197]
	v_pk_add_f32 v[116:117], v[116:117], v[206:207]
	v_pk_add_f32 v[192:193], v[114:115], v[198:199]
	v_pk_add_f32 v[194:195], v[112:113], v[208:209]
	v_cvt_pk_bf16_f32 v112, v124, v125
	v_cvt_pk_bf16_f32 v113, v126, v127
	v_mul_f32_e32 v114, v125, v125
	v_mul_f32_e32 v115, v127, v127
	v_mul_f32_e32 v125, v121, v121
	v_mul_f32_e32 v127, v123, v123
	v_mul_f32_e32 v196, v117, v117
	v_mul_f32_e32 v197, v119, v119
	v_mul_f32_e32 v198, v195, v195
	v_mul_f32_e32 v199, v193, v193
	v_fmac_f32_e32 v114, v124, v124
	v_fmac_f32_e32 v115, v126, v126
	v_fmac_f32_e32 v125, v120, v120
	v_fmac_f32_e32 v127, v122, v122
	v_fmac_f32_e32 v196, v116, v116
	v_fmac_f32_e32 v197, v118, v118
	v_fmac_f32_e32 v198, v194, v194
	v_fmac_f32_e32 v199, v192, v192
	v_add_f32_e32 v114, v114, v115
	v_add_f32_e32 v115, v125, v127
	v_add_f32_e32 v124, v196, v197
	v_add_f32_e32 v125, v198, v199
	v_add_f32_e32 v114, v114, v115
	v_add_f32_e32 v115, v124, v125
	v_add_f32_e32 v124, v114, v115
	ds_bpermute_b32 v125, v191, v124
	v_cvt_pk_bf16_f32 v114, v120, v121
	v_cvt_pk_bf16_f32 v115, v122, v123
	global_store_dwordx4 v[200:201], v[112:115], off
	v_cvt_pk_bf16_f32 v116, v116, v117
	v_cvt_pk_bf16_f32 v117, v118, v119
	s_waitcnt lgkmcnt(0)
	v_add_f32_e32 v113, v124, v125
	v_lshlrev_b32_e32 v112, 2, v210
	ds_bpermute_b32 v114, v112, v113
	v_cvt_pk_bf16_f32 v118, v194, v195
	v_cvt_pk_bf16_f32 v119, v192, v193
	global_store_dwordx4 v[200:201], v[116:119], off offset:256
	s_and_saveexec_b64 s[38:39], s[0:1]
	s_cbranch_execz .LBB0_1083
	s_waitcnt lgkmcnt(0)
	v_add_f32_e32 v113, v113, v114
	v_lshlrev_b64 v[114:115], 6, v[168:169]
	v_lshl_add_u64 v[114:115], s[74:75], 0, v[114:115]
	v_lshl_add_u64 v[114:115], s[36:37], 2, v[114:115]
	s_lshl_b32 s18, s58, 2
	v_lshl_add_u64 v[114:115], v[114:115], 0, s[18:19]
	global_store_dword v[114:115], v113, off

.LBB0_1181:
	ds_read_b128 v[128:131], v175
	ds_read_b128 v[152:155], v175 offset:1024
	ds_read_b128 v[156:159], v175 offset:2048
	ds_read_b128 v[160:163], v175 offset:3072
	ds_read_b128 v[164:167], v176
	ds_read_b128 v[168:171], v176 offset:1024
	ds_read_b128 v[180:183], v176 offset:2048
	ds_read_b128 v[184:187], v176 offset:3072
	s_add_u32 s57, s2, 0xfffc0080
	s_addc_u32 s58, s3, -1
	s_cmp_eq_u32 s56, 12
	s_cselect_b32 s65, s37, s58
	s_cselect_b32 s64, s52, s57
	s_cselect_b32 s63, s39, s55
	s_cselect_b32 s62, s53, s54
	v_lshl_add_u64 v[220:221], s[2:3], 0, v[144:145]
	s_add_i32 m0, s79, 0xc000
	ds_read_b128 v[188:191], v177
	ds_read_b128 v[192:195], v177 offset:1024
	ds_read_b128 v[196:199], v177 offset:2048
	ds_read_b128 v[200:203], v177 offset:3072
	ds_read_b128 v[204:207], v177 offset:4096
	ds_read_b128 v[208:211], v177 offset:5120
	ds_read_b128 v[212:215], v177 offset:6144
	ds_read_b128 v[216:219], v177 offset:7168
	global_load_lds_dwordx4 v[220:221], off
	v_lshl_add_u64 v[220:221], s[2:3], 0, v[146:147]
	s_add_i32 m0, s79, 0xe000
	s_nop 0
	global_load_lds_dwordx4 v[220:221], off
	s_waitcnt vmcnt(8)
	s_waitcnt lgkmcnt(0)
	s_setprio 1
	s_barrier
	s_waitcnt lgkmcnt(0)
	v_mfma_f32_16x16x32_bf16 v[124:127], v[128:131], v[188:191], v[124:127]
	v_mfma_f32_16x16x32_bf16 v[120:123], v[156:159], v[188:191], v[120:123]
	v_mfma_f32_16x16x32_bf16 v[116:119], v[128:131], v[196:199], v[116:119]
	v_mfma_f32_16x16x32_bf16 v[112:115], v[156:159], v[196:199], v[112:115]
	v_mfma_f32_16x16x32_bf16 v[100:103], v[128:131], v[204:207], v[100:103]
	v_mfma_f32_16x16x32_bf16 v[96:99], v[156:159], v[204:207], v[96:99]
	v_mfma_f32_16x16x32_bf16 v[80:83], v[128:131], v[212:215], v[80:83]
	v_mfma_f32_16x16x32_bf16 v[76:79], v[156:159], v[212:215], v[76:79]
	v_mfma_f32_16x16x32_bf16 v[124:127], v[152:155], v[192:195], v[124:127]
	v_mfma_f32_16x16x32_bf16 v[120:123], v[160:163], v[192:195], v[120:123]
	v_mfma_f32_16x16x32_bf16 v[116:119], v[152:155], v[200:203], v[116:119]
	v_mfma_f32_16x16x32_bf16 v[112:115], v[160:163], v[200:203], v[112:115]
	v_mfma_f32_16x16x32_bf16 v[100:103], v[152:155], v[208:211], v[100:103]
	v_mfma_f32_16x16x32_bf16 v[96:99], v[160:163], v[208:211], v[96:99]
	v_mfma_f32_16x16x32_bf16 v[80:83], v[152:155], v[216:219], v[80:83]
	v_mfma_f32_16x16x32_bf16 v[76:79], v[160:163], v[216:219], v[76:79]
	s_setprio 0
	s_setprio 1
	v_mfma_f32_16x16x32_bf16 v[108:111], v[164:167], v[188:191], v[108:111]
	v_mfma_f32_16x16x32_bf16 v[104:107], v[180:183], v[188:191], v[104:107]
	v_mfma_f32_16x16x32_bf16 v[92:95], v[164:167], v[196:199], v[92:95]
	v_mfma_f32_16x16x32_bf16 v[88:91], v[180:183], v[196:199], v[88:91]
	v_mfma_f32_16x16x32_bf16 v[84:87], v[164:167], v[204:207], v[84:87]
	v_mfma_f32_16x16x32_bf16 v[72:75], v[180:183], v[204:207], v[72:75]
	v_mfma_f32_16x16x32_bf16 v[68:71], v[164:167], v[212:215], v[68:71]
	v_mfma_f32_16x16x32_bf16 v[32:35], v[180:183], v[212:215], v[32:35]
	v_mfma_f32_16x16x32_bf16 v[108:111], v[168:171], v[192:195], v[108:111]
	v_mfma_f32_16x16x32_bf16 v[104:107], v[184:187], v[192:195], v[104:107]
	v_mfma_f32_16x16x32_bf16 v[92:95], v[168:171], v[200:203], v[92:95]
	v_mfma_f32_16x16x32_bf16 v[88:91], v[184:187], v[200:203], v[88:91]
	v_mfma_f32_16x16x32_bf16 v[84:87], v[168:171], v[208:211], v[84:87]
	v_mfma_f32_16x16x32_bf16 v[72:75], v[184:187], v[208:211], v[72:75]
	v_mfma_f32_16x16x32_bf16 v[68:71], v[168:171], v[216:219], v[68:71]
	v_mfma_f32_16x16x32_bf16 v[32:35], v[184:187], v[216:219], v[32:35]
	s_setprio 0
	s_barrier
	s_add_i32 s57, s89, s66
	v_lshl_add_u64 v[220:221], s[62:63], 0, v[134:135]
	s_mov_b32 m0, s57
	ds_read_b128 v[188:191], v177 offset:16384
	ds_read_b128 v[192:195], v177 offset:17408
	ds_read_b128 v[196:199], v177 offset:18432
	ds_read_b128 v[200:203], v177 offset:19456
	ds_read_b128 v[204:207], v177 offset:20480
	ds_read_b128 v[208:211], v177 offset:21504
	ds_read_b128 v[212:215], v177 offset:22528
	ds_read_b128 v[216:219], v177 offset:23552
	global_load_lds_dwordx4 v[220:221], off
	s_add_i32 m0, s57, 0x2000
	s_add_u32 s58, s62, 0x40000
	v_lshl_add_u64 v[222:223], s[62:63], 0, v[138:139]
	s_addc_u32 s59, s63, 0
	s_add_i32 s57, s90, s66
	global_load_lds_dwordx4 v[222:223], off
	v_lshl_add_u64 v[224:225], s[58:59], 0, v[134:135]
	s_mov_b32 m0, s57
	v_lshl_add_u64 v[226:227], s[64:65], 0, v[136:137]
	global_load_lds_dwordx4 v[224:225], off
	v_lshl_add_u64 v[224:225], s[58:59], 0, v[138:139]
	s_add_i32 m0, s57, 0x2000
	s_nop 0
	global_load_lds_dwordx4 v[224:225], off
	v_lshl_add_u64 v[224:225], s[64:65], 0, v[132:133]
	s_mov_b32 m0, s79
	s_nop 0
	global_load_lds_dwordx4 v[224:225], off
	s_mov_b32 m0, s80
	s_nop 0
	global_load_lds_dwordx4 v[226:227], off
	s_waitcnt vmcnt(8)
	s_waitcnt lgkmcnt(0)
	s_setprio 1
	s_barrier
	s_waitcnt lgkmcnt(0)
	v_mfma_f32_16x16x32_bf16 v[64:67], v[128:131], v[188:191], v[64:67]
	v_mfma_f32_16x16x32_bf16 v[60:63], v[156:159], v[188:191], v[60:63]
	v_mfma_f32_16x16x32_bf16 v[56:59], v[128:131], v[196:199], v[56:59]
	v_mfma_f32_16x16x32_bf16 v[52:55], v[156:159], v[196:199], v[52:55]
	v_mfma_f32_16x16x32_bf16 v[48:51], v[128:131], v[204:207], v[48:51]
	v_mfma_f32_16x16x32_bf16 v[44:47], v[156:159], v[204:207], v[44:47]
	v_mfma_f32_16x16x32_bf16 v[40:43], v[128:131], v[212:215], v[40:43]
	v_mfma_f32_16x16x32_bf16 v[36:39], v[156:159], v[212:215], v[36:39]
	v_mfma_f32_16x16x32_bf16 v[64:67], v[152:155], v[192:195], v[64:67]
	v_mfma_f32_16x16x32_bf16 v[60:63], v[160:163], v[192:195], v[60:63]
	v_mfma_f32_16x16x32_bf16 v[56:59], v[152:155], v[200:203], v[56:59]
	v_mfma_f32_16x16x32_bf16 v[52:55], v[160:163], v[200:203], v[52:55]
	v_mfma_f32_16x16x32_bf16 v[48:51], v[152:155], v[208:211], v[48:51]
	v_mfma_f32_16x16x32_bf16 v[44:47], v[160:163], v[208:211], v[44:47]
	v_mfma_f32_16x16x32_bf16 v[40:43], v[152:155], v[216:219], v[40:43]
	v_mfma_f32_16x16x32_bf16 v[36:39], v[160:163], v[216:219], v[36:39]
	s_setprio 0
	s_setprio 1
	v_mfma_f32_16x16x32_bf16 v[28:31], v[164:167], v[188:191], v[28:31]
	v_mfma_f32_16x16x32_bf16 v[24:27], v[180:183], v[188:191], v[24:27]
	v_mfma_f32_16x16x32_bf16 v[20:23], v[164:167], v[196:199], v[20:23]
	v_mfma_f32_16x16x32_bf16 v[16:19], v[180:183], v[196:199], v[16:19]
	v_mfma_f32_16x16x32_bf16 v[12:15], v[164:167], v[204:207], v[12:15]
	v_mfma_f32_16x16x32_bf16 v[8:11], v[180:183], v[204:207], v[8:11]
	v_mfma_f32_16x16x32_bf16 v[4:7], v[164:167], v[212:215], v[4:7]
	v_mfma_f32_16x16x32_bf16 v[0:3], v[180:183], v[212:215], v[0:3]
	v_mfma_f32_16x16x32_bf16 v[28:31], v[168:171], v[192:195], v[28:31]
	v_mfma_f32_16x16x32_bf16 v[24:27], v[184:187], v[192:195], v[24:27]
	v_mfma_f32_16x16x32_bf16 v[20:23], v[168:171], v[200:203], v[20:23]
	v_mfma_f32_16x16x32_bf16 v[16:19], v[184:187], v[200:203], v[16:19]
	v_mfma_f32_16x16x32_bf16 v[12:15], v[168:171], v[208:211], v[12:15]
	v_mfma_f32_16x16x32_bf16 v[8:11], v[184:187], v[208:211], v[8:11]
	v_mfma_f32_16x16x32_bf16 v[4:7], v[168:171], v[216:219], v[4:7]
	v_mfma_f32_16x16x32_bf16 v[0:3], v[184:187], v[216:219], v[0:3]
	s_setprio 0
	s_barrier
	s_add_i32 s57, 0, 0x18000
	v_add_u32_e32 v140, s57, v173
	s_add_i32 s68, 0, 0x1c000
	ds_read_b128 v[128:131], v140
	ds_read_b128 v[152:155], v140 offset:1024
	ds_read_b128 v[156:159], v140 offset:2048
	ds_read_b128 v[160:163], v140 offset:3072
	v_add_u32_e32 v140, s68, v173
	ds_read_b128 v[164:167], v140
	ds_read_b128 v[168:171], v140 offset:1024
	ds_read_b128 v[180:183], v140 offset:2048
	ds_read_b128 v[184:187], v140 offset:3072
	s_add_u32 s58, s64, 0x40000
	s_addc_u32 s59, s65, 0
	s_mov_b32 m0, s81
	v_lshl_add_u64 v[228:229], s[58:59], 0, v[132:133]
	ds_read_b128 v[188:191], v177 offset:32768
	ds_read_b128 v[192:195], v177 offset:33792
	ds_read_b128 v[196:199], v177 offset:34816
	ds_read_b128 v[200:203], v177 offset:35840
	ds_read_b128 v[204:207], v177 offset:36864
	ds_read_b128 v[208:211], v177 offset:37888
	ds_read_b128 v[212:215], v177 offset:38912
	ds_read_b128 v[216:219], v177 offset:39936
	global_load_lds_dwordx4 v[228:229], off
	v_lshl_add_u64 v[228:229], s[58:59], 0, v[136:137]
	s_mov_b32 m0, s82
	s_nop 0
	global_load_lds_dwordx4 v[228:229], off
	s_waitcnt vmcnt(8)
	s_waitcnt lgkmcnt(0)
	s_setprio 1
	s_barrier
	s_waitcnt lgkmcnt(0)
	v_mfma_f32_16x16x32_bf16 v[124:127], v[128:131], v[188:191], v[124:127]
	v_mfma_f32_16x16x32_bf16 v[120:123], v[156:159], v[188:191], v[120:123]
	v_mfma_f32_16x16x32_bf16 v[116:119], v[128:131], v[196:199], v[116:119]
	v_mfma_f32_16x16x32_bf16 v[112:115], v[156:159], v[196:199], v[112:115]
	v_mfma_f32_16x16x32_bf16 v[100:103], v[128:131], v[204:207], v[100:103]
	v_mfma_f32_16x16x32_bf16 v[96:99], v[156:159], v[204:207], v[96:99]
	v_mfma_f32_16x16x32_bf16 v[80:83], v[128:131], v[212:215], v[80:83]
	v_mfma_f32_16x16x32_bf16 v[76:79], v[156:159], v[212:215], v[76:79]
	v_mfma_f32_16x16x32_bf16 v[124:127], v[152:155], v[192:195], v[124:127]
	v_mfma_f32_16x16x32_bf16 v[120:123], v[160:163], v[192:195], v[120:123]
	v_mfma_f32_16x16x32_bf16 v[116:119], v[152:155], v[200:203], v[116:119]
	v_mfma_f32_16x16x32_bf16 v[112:115], v[160:163], v[200:203], v[112:115]
	v_mfma_f32_16x16x32_bf16 v[100:103], v[152:155], v[208:211], v[100:103]
	v_mfma_f32_16x16x32_bf16 v[96:99], v[160:163], v[208:211], v[96:99]
	v_mfma_f32_16x16x32_bf16 v[80:83], v[152:155], v[216:219], v[80:83]
	v_mfma_f32_16x16x32_bf16 v[76:79], v[160:163], v[216:219], v[76:79]
	s_setprio 0
	s_setprio 1
	v_mfma_f32_16x16x32_bf16 v[108:111], v[164:167], v[188:191], v[108:111]
	v_mfma_f32_16x16x32_bf16 v[104:107], v[180:183], v[188:191], v[104:107]
	v_mfma_f32_16x16x32_bf16 v[92:95], v[164:167], v[196:199], v[92:95]
	v_mfma_f32_16x16x32_bf16 v[88:91], v[180:183], v[196:199], v[88:91]
	v_mfma_f32_16x16x32_bf16 v[84:87], v[164:167], v[204:207], v[84:87]
	v_mfma_f32_16x16x32_bf16 v[72:75], v[180:183], v[204:207], v[72:75]
	v_mfma_f32_16x16x32_bf16 v[68:71], v[164:167], v[212:215], v[68:71]
	v_mfma_f32_16x16x32_bf16 v[32:35], v[180:183], v[212:215], v[32:35]
	v_mfma_f32_16x16x32_bf16 v[108:111], v[168:171], v[192:195], v[108:111]
	v_mfma_f32_16x16x32_bf16 v[104:107], v[184:187], v[192:195], v[104:107]
	v_mfma_f32_16x16x32_bf16 v[92:95], v[168:171], v[200:203], v[92:95]
	v_mfma_f32_16x16x32_bf16 v[88:91], v[184:187], v[200:203], v[88:91]
	v_mfma_f32_16x16x32_bf16 v[84:87], v[168:171], v[208:211], v[84:87]
	v_mfma_f32_16x16x32_bf16 v[72:75], v[184:187], v[208:211], v[72:75]
	v_mfma_f32_16x16x32_bf16 v[68:71], v[168:171], v[216:219], v[68:71]
	v_mfma_f32_16x16x32_bf16 v[32:35], v[184:187], v[216:219], v[32:35]
	s_setprio 0
	s_barrier
	s_add_i32 s57, s57, s66
	v_lshl_add_u64 v[220:221], v[220:221], 0, s[12:13]
	s_mov_b32 m0, s57
	ds_read_b128 v[188:191], v177 offset:49152
	ds_read_b128 v[192:195], v177 offset:50176
	ds_read_b128 v[196:199], v177 offset:51200
	ds_read_b128 v[200:203], v177 offset:52224
	ds_read_b128 v[204:207], v177 offset:53248
	ds_read_b128 v[208:211], v177 offset:54272
	ds_read_b128 v[212:215], v177 offset:55296
	ds_read_b128 v[216:219], v177 offset:56320
	global_load_lds_dwordx4 v[220:221], off
	s_add_i32 m0, s57, 0x2000
	s_add_u32 s58, s62, 0x40080
	v_lshl_add_u64 v[220:221], v[222:223], 0, s[12:13]
	s_addc_u32 s59, s63, 0
	s_add_i32 s57, s68, s66
	global_load_lds_dwordx4 v[220:221], off
	v_lshl_add_u64 v[220:221], s[58:59], 0, v[134:135]
	s_mov_b32 m0, s57
	s_nop 0
	global_load_lds_dwordx4 v[220:221], off
	v_lshl_add_u64 v[220:221], s[58:59], 0, v[138:139]
	s_add_i32 m0, s57, 0x2000
	s_nop 0
	global_load_lds_dwordx4 v[220:221], off
	v_lshl_add_u64 v[220:221], v[224:225], 0, s[12:13]
	s_mov_b32 m0, s86
	s_nop 0
	global_load_lds_dwordx4 v[220:221], off
	v_lshl_add_u64 v[220:221], v[226:227], 0, s[12:13]
	s_mov_b32 m0, s87
	s_nop 0
	global_load_lds_dwordx4 v[220:221], off
	s_waitcnt vmcnt(8)
	s_waitcnt lgkmcnt(0)
	s_setprio 1
	s_barrier
	s_waitcnt lgkmcnt(0)
	v_mfma_f32_16x16x32_bf16 v[64:67], v[128:131], v[188:191], v[64:67]
	v_mfma_f32_16x16x32_bf16 v[60:63], v[156:159], v[188:191], v[60:63]
	v_mfma_f32_16x16x32_bf16 v[56:59], v[128:131], v[196:199], v[56:59]
	v_mfma_f32_16x16x32_bf16 v[52:55], v[156:159], v[196:199], v[52:55]
	v_mfma_f32_16x16x32_bf16 v[48:51], v[128:131], v[204:207], v[48:51]
	v_mfma_f32_16x16x32_bf16 v[44:47], v[156:159], v[204:207], v[44:47]
	v_mfma_f32_16x16x32_bf16 v[40:43], v[128:131], v[212:215], v[40:43]
	v_mfma_f32_16x16x32_bf16 v[36:39], v[156:159], v[212:215], v[36:39]
	v_mfma_f32_16x16x32_bf16 v[64:67], v[152:155], v[192:195], v[64:67]
	v_mfma_f32_16x16x32_bf16 v[60:63], v[160:163], v[192:195], v[60:63]
	v_mfma_f32_16x16x32_bf16 v[56:59], v[152:155], v[200:203], v[56:59]
	v_mfma_f32_16x16x32_bf16 v[52:55], v[160:163], v[200:203], v[52:55]
	v_mfma_f32_16x16x32_bf16 v[48:51], v[152:155], v[208:211], v[48:51]
	v_mfma_f32_16x16x32_bf16 v[44:47], v[160:163], v[208:211], v[44:47]
	v_mfma_f32_16x16x32_bf16 v[40:43], v[152:155], v[216:219], v[40:43]
	v_mfma_f32_16x16x32_bf16 v[36:39], v[160:163], v[216:219], v[36:39]
	s_setprio 0
	s_setprio 1
	v_mfma_f32_16x16x32_bf16 v[28:31], v[164:167], v[188:191], v[28:31]
	v_mfma_f32_16x16x32_bf16 v[24:27], v[180:183], v[188:191], v[24:27]
	v_mfma_f32_16x16x32_bf16 v[20:23], v[164:167], v[196:199], v[20:23]
	v_mfma_f32_16x16x32_bf16 v[16:19], v[180:183], v[196:199], v[16:19]
	v_mfma_f32_16x16x32_bf16 v[12:15], v[164:167], v[204:207], v[12:15]
	v_mfma_f32_16x16x32_bf16 v[8:11], v[180:183], v[204:207], v[8:11]
	v_mfma_f32_16x16x32_bf16 v[4:7], v[164:167], v[212:215], v[4:7]
	v_mfma_f32_16x16x32_bf16 v[0:3], v[180:183], v[212:215], v[0:3]
	v_mfma_f32_16x16x32_bf16 v[28:31], v[168:171], v[192:195], v[28:31]
	v_mfma_f32_16x16x32_bf16 v[24:27], v[184:187], v[192:195], v[24:27]
	v_mfma_f32_16x16x32_bf16 v[20:23], v[168:171], v[200:203], v[20:23]
	v_mfma_f32_16x16x32_bf16 v[16:19], v[184:187], v[200:203], v[16:19]
	v_mfma_f32_16x16x32_bf16 v[12:15], v[168:171], v[208:211], v[12:15]
	v_mfma_f32_16x16x32_bf16 v[8:11], v[184:187], v[208:211], v[8:11]
	v_mfma_f32_16x16x32_bf16 v[4:7], v[168:171], v[216:219], v[4:7]
	v_mfma_f32_16x16x32_bf16 v[0:3], v[184:187], v[216:219], v[0:3]
	s_setprio 0
	s_barrier
	s_add_i32 s56, s56, 2
	s_add_u32 s2, s2, 0x100
	s_addc_u32 s3, s3, 0
	s_add_u32 s54, s54, 0x100
	s_addc_u32 s55, s55, 0
	s_cmp_gt_u32 s56, 13
	s_cbranch_scc0 .LBB0_1181
	s_and_b64 vcc, exec, s[14:15]
	s_cbranch_vccz .LBB0_1184
	s_barrier

.LBB0_1530:
	ds_read_b128 v[128:131], v187
	ds_read_b128 v[132:135], v187 offset:1024
	ds_read_b128 v[136:139], v187 offset:2048
	ds_read_b128 v[140:143], v187 offset:3072
	ds_read_b128 v[144:147], v188
	ds_read_b128 v[148:151], v188 offset:1024
	ds_read_b128 v[168:171], v188 offset:2048
	ds_read_b128 v[172:175], v188 offset:3072
	s_add_u32 s36, s24, 0xfffc0080
	s_addc_u32 s37, s25, -1
	s_cmp_eq_u32 s65, 12
	s_cselect_b32 s39, s11, s37
	s_cselect_b32 s38, s61, s36
	s_cselect_b32 s37, s13, s64
	s_cselect_b32 s36, s62, s63
	v_lshl_add_u64 v[216:217], s[24:25], 0, v[160:161]
	s_add_i32 m0, s46, 0xc000
	ds_read_b128 v[176:179], v189
	ds_read_b128 v[180:183], v189 offset:1024
	ds_read_b128 v[192:195], v189 offset:2048
	ds_read_b128 v[196:199], v189 offset:3072
	ds_read_b128 v[200:203], v189 offset:4096
	ds_read_b128 v[204:207], v189 offset:5120
	ds_read_b128 v[208:211], v189 offset:6144
	ds_read_b128 v[212:215], v189 offset:7168
	global_load_lds_dwordx4 v[216:217], off
	v_lshl_add_u64 v[216:217], s[24:25], 0, v[162:163]
	s_add_i32 m0, s46, 0xe000
	s_nop 0
	global_load_lds_dwordx4 v[216:217], off
	s_waitcnt vmcnt(8)
	s_waitcnt lgkmcnt(0)
	s_setprio 1
	s_barrier
	s_waitcnt lgkmcnt(0)
	v_mfma_f32_16x16x32_bf16 v[124:127], v[128:131], v[176:179], v[124:127]
	v_mfma_f32_16x16x32_bf16 v[120:123], v[136:139], v[176:179], v[120:123]
	v_mfma_f32_16x16x32_bf16 v[108:111], v[128:131], v[192:195], v[108:111]
	v_mfma_f32_16x16x32_bf16 v[104:107], v[136:139], v[192:195], v[104:107]
	v_mfma_f32_16x16x32_bf16 v[92:95], v[128:131], v[200:203], v[92:95]
	v_mfma_f32_16x16x32_bf16 v[88:91], v[136:139], v[200:203], v[88:91]
	v_mfma_f32_16x16x32_bf16 v[76:79], v[128:131], v[208:211], v[76:79]
	v_mfma_f32_16x16x32_bf16 v[72:75], v[136:139], v[208:211], v[72:75]
	v_mfma_f32_16x16x32_bf16 v[124:127], v[132:135], v[180:183], v[124:127]
	v_mfma_f32_16x16x32_bf16 v[120:123], v[140:143], v[180:183], v[120:123]
	v_mfma_f32_16x16x32_bf16 v[108:111], v[132:135], v[196:199], v[108:111]
	v_mfma_f32_16x16x32_bf16 v[104:107], v[140:143], v[196:199], v[104:107]
	v_mfma_f32_16x16x32_bf16 v[92:95], v[132:135], v[204:207], v[92:95]
	v_mfma_f32_16x16x32_bf16 v[88:91], v[140:143], v[204:207], v[88:91]
	v_mfma_f32_16x16x32_bf16 v[76:79], v[132:135], v[212:215], v[76:79]
	v_mfma_f32_16x16x32_bf16 v[72:75], v[140:143], v[212:215], v[72:75]
	s_setprio 0
	s_setprio 1
	v_mfma_f32_16x16x32_bf16 v[116:119], v[144:147], v[176:179], v[116:119]
	v_mfma_f32_16x16x32_bf16 v[112:115], v[168:171], v[176:179], v[112:115]
	v_mfma_f32_16x16x32_bf16 v[100:103], v[144:147], v[192:195], v[100:103]
	v_mfma_f32_16x16x32_bf16 v[96:99], v[168:171], v[192:195], v[96:99]
	v_mfma_f32_16x16x32_bf16 v[84:87], v[144:147], v[200:203], v[84:87]
	v_mfma_f32_16x16x32_bf16 v[80:83], v[168:171], v[200:203], v[80:83]
	v_mfma_f32_16x16x32_bf16 v[68:71], v[144:147], v[208:211], v[68:71]
	v_mfma_f32_16x16x32_bf16 v[64:67], v[168:171], v[208:211], v[64:67]
	v_mfma_f32_16x16x32_bf16 v[116:119], v[148:151], v[180:183], v[116:119]
	v_mfma_f32_16x16x32_bf16 v[112:115], v[172:175], v[180:183], v[112:115]
	v_mfma_f32_16x16x32_bf16 v[100:103], v[148:151], v[196:199], v[100:103]
	v_mfma_f32_16x16x32_bf16 v[96:99], v[172:175], v[196:199], v[96:99]
	v_mfma_f32_16x16x32_bf16 v[84:87], v[148:151], v[204:207], v[84:87]
	v_mfma_f32_16x16x32_bf16 v[80:83], v[172:175], v[204:207], v[80:83]
	v_mfma_f32_16x16x32_bf16 v[68:71], v[148:151], v[212:215], v[68:71]
	v_mfma_f32_16x16x32_bf16 v[64:67], v[172:175], v[212:215], v[64:67]
	s_setprio 0
	s_barrier
	s_add_i32 s66, s55, s45
	v_lshl_add_u64 v[216:217], s[36:37], 0, v[154:155]
	s_mov_b32 m0, s66
	ds_read_b128 v[176:179], v189 offset:16384
	ds_read_b128 v[180:183], v189 offset:17408
	ds_read_b128 v[192:195], v189 offset:18432
	ds_read_b128 v[196:199], v189 offset:19456
	ds_read_b128 v[200:203], v189 offset:20480
	ds_read_b128 v[204:207], v189 offset:21504
	ds_read_b128 v[208:211], v189 offset:22528
	ds_read_b128 v[212:215], v189 offset:23552
	global_load_lds_dwordx4 v[216:217], off
	s_add_i32 m0, s66, 0x2000
	s_add_u32 s66, s36, 0x40000
	v_lshl_add_u64 v[218:219], s[36:37], 0, v[158:159]
	s_addc_u32 s67, s37, 0
	s_add_i32 s68, s56, s45
	global_load_lds_dwordx4 v[218:219], off
	v_lshl_add_u64 v[220:221], s[66:67], 0, v[154:155]
	s_mov_b32 m0, s68
	v_lshl_add_u64 v[222:223], s[38:39], 0, v[156:157]
	global_load_lds_dwordx4 v[220:221], off
	v_lshl_add_u64 v[220:221], s[66:67], 0, v[158:159]
	s_add_i32 m0, s68, 0x2000
	s_nop 0
	global_load_lds_dwordx4 v[220:221], off
	v_lshl_add_u64 v[220:221], s[38:39], 0, v[152:153]
	s_mov_b32 m0, s46
	s_nop 0
	global_load_lds_dwordx4 v[220:221], off
	s_mov_b32 m0, s47
	s_nop 0
	global_load_lds_dwordx4 v[222:223], off
	s_waitcnt vmcnt(8)
	s_waitcnt lgkmcnt(0)
	s_setprio 1
	s_barrier
	s_waitcnt lgkmcnt(0)
	v_mfma_f32_16x16x32_bf16 v[60:63], v[128:131], v[176:179], v[60:63]
	v_mfma_f32_16x16x32_bf16 v[56:59], v[136:139], v[176:179], v[56:59]
	v_mfma_f32_16x16x32_bf16 v[44:47], v[128:131], v[192:195], v[44:47]
	v_mfma_f32_16x16x32_bf16 v[40:43], v[136:139], v[192:195], v[40:43]
	v_mfma_f32_16x16x32_bf16 v[28:31], v[128:131], v[200:203], v[28:31]
	v_mfma_f32_16x16x32_bf16 v[24:27], v[136:139], v[200:203], v[24:27]
	v_mfma_f32_16x16x32_bf16 v[12:15], v[128:131], v[208:211], v[12:15]
	v_mfma_f32_16x16x32_bf16 v[8:11], v[136:139], v[208:211], v[8:11]
	v_mfma_f32_16x16x32_bf16 v[60:63], v[132:135], v[180:183], v[60:63]
	v_mfma_f32_16x16x32_bf16 v[56:59], v[140:143], v[180:183], v[56:59]
	v_mfma_f32_16x16x32_bf16 v[44:47], v[132:135], v[196:199], v[44:47]
	v_mfma_f32_16x16x32_bf16 v[40:43], v[140:143], v[196:199], v[40:43]
	v_mfma_f32_16x16x32_bf16 v[28:31], v[132:135], v[204:207], v[28:31]
	v_mfma_f32_16x16x32_bf16 v[24:27], v[140:143], v[204:207], v[24:27]
	v_mfma_f32_16x16x32_bf16 v[12:15], v[132:135], v[212:215], v[12:15]
	v_mfma_f32_16x16x32_bf16 v[8:11], v[140:143], v[212:215], v[8:11]
	s_setprio 0
	s_setprio 1
	v_mfma_f32_16x16x32_bf16 v[52:55], v[144:147], v[176:179], v[52:55]
	v_mfma_f32_16x16x32_bf16 v[48:51], v[168:171], v[176:179], v[48:51]
	v_mfma_f32_16x16x32_bf16 v[36:39], v[144:147], v[192:195], v[36:39]
	v_mfma_f32_16x16x32_bf16 v[32:35], v[168:171], v[192:195], v[32:35]
	v_mfma_f32_16x16x32_bf16 v[20:23], v[144:147], v[200:203], v[20:23]
	v_mfma_f32_16x16x32_bf16 v[16:19], v[168:171], v[200:203], v[16:19]
	v_mfma_f32_16x16x32_bf16 v[4:7], v[144:147], v[208:211], v[4:7]
	v_mfma_f32_16x16x32_bf16 v[0:3], v[168:171], v[208:211], v[0:3]
	v_mfma_f32_16x16x32_bf16 v[52:55], v[148:151], v[180:183], v[52:55]
	v_mfma_f32_16x16x32_bf16 v[48:51], v[172:175], v[180:183], v[48:51]
	v_mfma_f32_16x16x32_bf16 v[36:39], v[148:151], v[196:199], v[36:39]
	v_mfma_f32_16x16x32_bf16 v[32:35], v[172:175], v[196:199], v[32:35]
	v_mfma_f32_16x16x32_bf16 v[20:23], v[148:151], v[204:207], v[20:23]
	v_mfma_f32_16x16x32_bf16 v[16:19], v[172:175], v[204:207], v[16:19]
	v_mfma_f32_16x16x32_bf16 v[4:7], v[148:151], v[212:215], v[4:7]
	v_mfma_f32_16x16x32_bf16 v[0:3], v[172:175], v[212:215], v[0:3]
	s_setprio 0
	s_barrier
	s_add_i32 s66, 0, 0x18000
	s_add_i32 s67, 0, 0x1c000
	v_add_u32_e32 v140, s66, v185
	v_add_u32_e32 v172, s67, v185
	ds_read_b128 v[128:131], v140
	ds_read_b128 v[132:135], v140 offset:1024
	ds_read_b128 v[136:139], v140 offset:2048
	ds_read_b128 v[140:143], v140 offset:3072
	ds_read_b128 v[144:147], v172
	ds_read_b128 v[148:151], v172 offset:1024
	ds_read_b128 v[168:171], v172 offset:2048
	ds_read_b128 v[172:175], v172 offset:3072
	s_add_u32 s38, s38, 0x40000
	s_addc_u32 s39, s39, 0
	s_mov_b32 m0, s48
	v_lshl_add_u64 v[224:225], s[38:39], 0, v[152:153]
	ds_read_b128 v[176:179], v189 offset:32768
	ds_read_b128 v[180:183], v189 offset:33792
	ds_read_b128 v[192:195], v189 offset:34816
	ds_read_b128 v[196:199], v189 offset:35840
	ds_read_b128 v[200:203], v189 offset:36864
	ds_read_b128 v[204:207], v189 offset:37888
	ds_read_b128 v[208:211], v189 offset:38912
	ds_read_b128 v[212:215], v189 offset:39936
	global_load_lds_dwordx4 v[224:225], off
	v_lshl_add_u64 v[224:225], s[38:39], 0, v[156:157]
	s_mov_b32 m0, s49
	s_nop 0
	global_load_lds_dwordx4 v[224:225], off
	s_waitcnt vmcnt(8)
	s_waitcnt lgkmcnt(0)
	s_setprio 1
	s_barrier
	s_waitcnt lgkmcnt(0)
	v_mfma_f32_16x16x32_bf16 v[124:127], v[128:131], v[176:179], v[124:127]
	v_mfma_f32_16x16x32_bf16 v[120:123], v[136:139], v[176:179], v[120:123]
	v_mfma_f32_16x16x32_bf16 v[108:111], v[128:131], v[192:195], v[108:111]
	v_mfma_f32_16x16x32_bf16 v[104:107], v[136:139], v[192:195], v[104:107]
	v_mfma_f32_16x16x32_bf16 v[92:95], v[128:131], v[200:203], v[92:95]
	v_mfma_f32_16x16x32_bf16 v[88:91], v[136:139], v[200:203], v[88:91]
	v_mfma_f32_16x16x32_bf16 v[76:79], v[128:131], v[208:211], v[76:79]
	v_mfma_f32_16x16x32_bf16 v[72:75], v[136:139], v[208:211], v[72:75]
	v_mfma_f32_16x16x32_bf16 v[124:127], v[132:135], v[180:183], v[124:127]
	v_mfma_f32_16x16x32_bf16 v[120:123], v[140:143], v[180:183], v[120:123]
	v_mfma_f32_16x16x32_bf16 v[108:111], v[132:135], v[196:199], v[108:111]
	v_mfma_f32_16x16x32_bf16 v[104:107], v[140:143], v[196:199], v[104:107]
	v_mfma_f32_16x16x32_bf16 v[92:95], v[132:135], v[204:207], v[92:95]
	v_mfma_f32_16x16x32_bf16 v[88:91], v[140:143], v[204:207], v[88:91]
	v_mfma_f32_16x16x32_bf16 v[76:79], v[132:135], v[212:215], v[76:79]
	v_mfma_f32_16x16x32_bf16 v[72:75], v[140:143], v[212:215], v[72:75]
	s_setprio 0
	s_setprio 1
	v_mfma_f32_16x16x32_bf16 v[116:119], v[144:147], v[176:179], v[116:119]
	v_mfma_f32_16x16x32_bf16 v[112:115], v[168:171], v[176:179], v[112:115]
	v_mfma_f32_16x16x32_bf16 v[100:103], v[144:147], v[192:195], v[100:103]
	v_mfma_f32_16x16x32_bf16 v[96:99], v[168:171], v[192:195], v[96:99]
	v_mfma_f32_16x16x32_bf16 v[84:87], v[144:147], v[200:203], v[84:87]
	v_mfma_f32_16x16x32_bf16 v[80:83], v[168:171], v[200:203], v[80:83]
	v_mfma_f32_16x16x32_bf16 v[68:71], v[144:147], v[208:211], v[68:71]
	v_mfma_f32_16x16x32_bf16 v[64:67], v[168:171], v[208:211], v[64:67]
	v_mfma_f32_16x16x32_bf16 v[116:119], v[148:151], v[180:183], v[116:119]
	v_mfma_f32_16x16x32_bf16 v[112:115], v[172:175], v[180:183], v[112:115]
	v_mfma_f32_16x16x32_bf16 v[100:103], v[148:151], v[196:199], v[100:103]
	v_mfma_f32_16x16x32_bf16 v[96:99], v[172:175], v[196:199], v[96:99]
	v_mfma_f32_16x16x32_bf16 v[84:87], v[148:151], v[204:207], v[84:87]
	v_mfma_f32_16x16x32_bf16 v[80:83], v[172:175], v[204:207], v[80:83]
	v_mfma_f32_16x16x32_bf16 v[68:71], v[148:151], v[212:215], v[68:71]
	v_mfma_f32_16x16x32_bf16 v[64:67], v[172:175], v[212:215], v[64:67]
	s_setprio 0
	s_barrier
	s_add_i32 s38, s66, s45
	v_lshl_add_u64 v[216:217], v[216:217], 0, s[6:7]
	s_mov_b32 m0, s38
	ds_read_b128 v[176:179], v189 offset:49152
	ds_read_b128 v[180:183], v189 offset:50176
	ds_read_b128 v[192:195], v189 offset:51200
	ds_read_b128 v[196:199], v189 offset:52224
	ds_read_b128 v[200:203], v189 offset:53248
	ds_read_b128 v[204:207], v189 offset:54272
	ds_read_b128 v[208:211], v189 offset:55296
	ds_read_b128 v[212:215], v189 offset:56320
	global_load_lds_dwordx4 v[216:217], off
	s_add_i32 m0, s38, 0x2000
	s_add_u32 s36, s36, 0x40080
	v_lshl_add_u64 v[216:217], v[218:219], 0, s[6:7]
	s_addc_u32 s37, s37, 0
	s_add_i32 s38, s67, s45
	global_load_lds_dwordx4 v[216:217], off
	v_lshl_add_u64 v[216:217], s[36:37], 0, v[154:155]
	s_mov_b32 m0, s38
	s_nop 0
	global_load_lds_dwordx4 v[216:217], off
	v_lshl_add_u64 v[216:217], s[36:37], 0, v[158:159]
	s_add_i32 m0, s38, 0x2000
	s_nop 0
	global_load_lds_dwordx4 v[216:217], off
	v_lshl_add_u64 v[216:217], v[220:221], 0, s[6:7]
	s_mov_b32 m0, s51
	s_nop 0
	global_load_lds_dwordx4 v[216:217], off
	v_lshl_add_u64 v[216:217], v[222:223], 0, s[6:7]
	s_mov_b32 m0, s52
	s_nop 0
	global_load_lds_dwordx4 v[216:217], off
	s_waitcnt vmcnt(8)
	s_waitcnt lgkmcnt(0)
	s_setprio 1
	s_barrier
	s_waitcnt lgkmcnt(0)
	v_mfma_f32_16x16x32_bf16 v[60:63], v[128:131], v[176:179], v[60:63]
	v_mfma_f32_16x16x32_bf16 v[56:59], v[136:139], v[176:179], v[56:59]
	v_mfma_f32_16x16x32_bf16 v[44:47], v[128:131], v[192:195], v[44:47]
	v_mfma_f32_16x16x32_bf16 v[40:43], v[136:139], v[192:195], v[40:43]
	v_mfma_f32_16x16x32_bf16 v[28:31], v[128:131], v[200:203], v[28:31]
	v_mfma_f32_16x16x32_bf16 v[24:27], v[136:139], v[200:203], v[24:27]
	v_mfma_f32_16x16x32_bf16 v[12:15], v[128:131], v[208:211], v[12:15]
	v_mfma_f32_16x16x32_bf16 v[8:11], v[136:139], v[208:211], v[8:11]
	v_mfma_f32_16x16x32_bf16 v[60:63], v[132:135], v[180:183], v[60:63]
	v_mfma_f32_16x16x32_bf16 v[56:59], v[140:143], v[180:183], v[56:59]
	v_mfma_f32_16x16x32_bf16 v[44:47], v[132:135], v[196:199], v[44:47]
	v_mfma_f32_16x16x32_bf16 v[40:43], v[140:143], v[196:199], v[40:43]
	v_mfma_f32_16x16x32_bf16 v[28:31], v[132:135], v[204:207], v[28:31]
	v_mfma_f32_16x16x32_bf16 v[24:27], v[140:143], v[204:207], v[24:27]
	v_mfma_f32_16x16x32_bf16 v[12:15], v[132:135], v[212:215], v[12:15]
	v_mfma_f32_16x16x32_bf16 v[8:11], v[140:143], v[212:215], v[8:11]
	s_setprio 0
	s_setprio 1
	v_mfma_f32_16x16x32_bf16 v[52:55], v[144:147], v[176:179], v[52:55]
	v_mfma_f32_16x16x32_bf16 v[48:51], v[168:171], v[176:179], v[48:51]
	v_mfma_f32_16x16x32_bf16 v[36:39], v[144:147], v[192:195], v[36:39]
	v_mfma_f32_16x16x32_bf16 v[32:35], v[168:171], v[192:195], v[32:35]
	v_mfma_f32_16x16x32_bf16 v[20:23], v[144:147], v[200:203], v[20:23]
	v_mfma_f32_16x16x32_bf16 v[16:19], v[168:171], v[200:203], v[16:19]
	v_mfma_f32_16x16x32_bf16 v[4:7], v[144:147], v[208:211], v[4:7]
	v_mfma_f32_16x16x32_bf16 v[0:3], v[168:171], v[208:211], v[0:3]
	v_mfma_f32_16x16x32_bf16 v[52:55], v[148:151], v[180:183], v[52:55]
	v_mfma_f32_16x16x32_bf16 v[48:51], v[172:175], v[180:183], v[48:51]
	v_mfma_f32_16x16x32_bf16 v[36:39], v[148:151], v[196:199], v[36:39]
	v_mfma_f32_16x16x32_bf16 v[32:35], v[172:175], v[196:199], v[32:35]
	v_mfma_f32_16x16x32_bf16 v[20:23], v[148:151], v[204:207], v[20:23]
	v_mfma_f32_16x16x32_bf16 v[16:19], v[172:175], v[204:207], v[16:19]
	v_mfma_f32_16x16x32_bf16 v[4:7], v[148:151], v[212:215], v[4:7]
	v_mfma_f32_16x16x32_bf16 v[0:3], v[172:175], v[212:215], v[0:3]
	s_setprio 0
	s_barrier
	s_add_i32 s65, s65, 2
	s_add_u32 s24, s24, 0x100
	s_addc_u32 s25, s25, 0
	s_add_u32 s63, s63, 0x100
	s_addc_u32 s64, s64, 0
	s_cmp_gt_u32 s65, 13
	s_cbranch_scc0 .LBB0_1530
	v_lshl_add_u32 v168, s60, 8, v184
	v_lshl_or_b32 v128, s8, 8, v186
	v_ashrrev_i32_e32 v169, 31, v168
	v_ashrrev_i32_e32 v129, 31, v128
	v_lshlrev_b64 v[130:131], 11, v[168:169]
	v_lshl_add_u64 v[130:131], s[34:35], 0, v[130:131]
	v_lshlrev_b64 v[170:171], 1, v[128:129]
	v_lshl_add_u64 v[200:201], v[130:131], 0, v[170:171]
	global_load_dwordx4 v[192:195], v[200:201], off
	global_load_dwordx4 v[196:199], v[200:201], off offset:256
	v_or_b32_e32 v180, 16, v168
	v_or_b32_e32 v176, 32, v168
	v_or_b32_e32 v172, 48, v168
	v_ashrrev_i32_e32 v181, 31, v180
	v_ashrrev_i32_e32 v177, 31, v176
	v_ashrrev_i32_e32 v173, 31, v172
	v_lshlrev_b64 v[128:129], 11, v[180:181]
	v_lshlrev_b64 v[130:131], 11, v[176:177]
	v_lshlrev_b64 v[132:133], 11, v[172:173]
	v_lshl_add_u64 v[128:129], s[34:35], 0, v[128:129]
	v_lshl_add_u64 v[130:131], s[34:35], 0, v[130:131]
	v_lshl_add_u64 v[132:133], s[34:35], 0, v[132:133]
	v_lshl_add_u64 v[182:183], v[128:129], 0, v[170:171]
	v_lshl_add_u64 v[178:179], v[130:131], 0, v[170:171]
	v_lshl_add_u64 v[174:175], v[132:133], 0, v[170:171]
	global_load_dwordx4 v[148:151], v[182:183], off
	global_load_dwordx4 v[144:147], v[182:183], off offset:256
	global_load_dwordx4 v[140:143], v[178:179], off
	global_load_dwordx4 v[136:139], v[178:179], off offset:256
	global_load_dwordx4 v[132:135], v[174:175], off
	global_load_dwordx4 v[128:131], v[174:175], off offset:256
	v_and_b32_e32 v202, 64, v190
	v_xor_b32_e32 v191, 16, v190
	v_add_u32_e32 v202, 64, v202
	v_xor_b32_e32 v203, 32, v190
	v_cmp_lt_i32_e32 vcc, v191, v202
	s_lshl_b32 s24, s8, 2
	s_ashr_i32 s25, s24, 31
	v_cndmask_b32_e32 v191, v190, v191, vcc
	v_cmp_lt_i32_e32 vcc, v203, v202
	v_lshlrev_b32_e32 v191, 2, v191
	s_waitcnt vmcnt(0)
	v_lshlrev_b32_e32 v202, 16, v192
	v_cndmask_b32_e32 v210, v190, v203, vcc
	v_and_b32_e32 v203, 0xffff0000, v192
	v_lshlrev_b32_e32 v192, 16, v193
	v_and_b32_e32 v193, 0xffff0000, v193
	v_lshlrev_b32_e32 v204, 16, v194
	v_and_b32_e32 v205, 0xffff0000, v194
	v_lshlrev_b32_e32 v194, 16, v195
	v_and_b32_e32 v195, 0xffff0000, v195
	v_lshlrev_b32_e32 v206, 16, v196
	v_and_b32_e32 v207, 0xffff0000, v196
	v_lshlrev_b32_e32 v196, 16, v197
	v_and_b32_e32 v197, 0xffff0000, v197
	v_lshlrev_b32_e32 v208, 16, v198
	v_and_b32_e32 v209, 0xffff0000, v198
	v_lshlrev_b32_e32 v198, 16, v199
	v_and_b32_e32 v199, 0xffff0000, v199
	v_pk_add_f32 v[126:127], v[126:127], v[192:193]
	v_pk_add_f32 v[124:125], v[124:125], v[202:203]
	v_pk_add_f32 v[122:123], v[122:123], v[194:195]
	v_pk_add_f32 v[120:121], v[120:121], v[204:205]
	v_pk_add_f32 v[118:119], v[118:119], v[196:197]
	v_pk_add_f32 v[116:117], v[116:117], v[206:207]
	v_pk_add_f32 v[192:193], v[114:115], v[198:199]
	v_pk_add_f32 v[194:195], v[112:113], v[208:209]
	v_cvt_pk_bf16_f32 v112, v124, v125
	v_cvt_pk_bf16_f32 v113, v126, v127
	v_mul_f32_e32 v114, v125, v125
	v_mul_f32_e32 v115, v127, v127
	v_mul_f32_e32 v125, v121, v121
	v_mul_f32_e32 v127, v123, v123
	v_mul_f32_e32 v196, v117, v117
	v_mul_f32_e32 v197, v119, v119
	v_mul_f32_e32 v198, v195, v195
	v_mul_f32_e32 v199, v193, v193
	v_fmac_f32_e32 v114, v124, v124
	v_fmac_f32_e32 v115, v126, v126
	v_fmac_f32_e32 v125, v120, v120
	v_fmac_f32_e32 v127, v122, v122
	v_fmac_f32_e32 v196, v116, v116
	v_fmac_f32_e32 v197, v118, v118
	v_fmac_f32_e32 v198, v194, v194
	v_fmac_f32_e32 v199, v192, v192
	v_add_f32_e32 v114, v114, v115
	v_add_f32_e32 v115, v125, v127
	v_add_f32_e32 v124, v196, v197
	v_add_f32_e32 v125, v198, v199
	v_add_f32_e32 v114, v114, v115
	v_add_f32_e32 v115, v124, v125
	v_add_f32_e32 v124, v114, v115
	ds_bpermute_b32 v125, v191, v124
	v_cvt_pk_bf16_f32 v114, v120, v121
	v_cvt_pk_bf16_f32 v115, v122, v123
	global_store_dwordx4 v[200:201], v[112:115], off
	v_cvt_pk_bf16_f32 v116, v116, v117
	v_cvt_pk_bf16_f32 v117, v118, v119
	s_waitcnt lgkmcnt(0)
	v_add_f32_e32 v113, v124, v125
	v_lshlrev_b32_e32 v112, 2, v210
	ds_bpermute_b32 v114, v112, v113
	v_cvt_pk_bf16_f32 v118, v194, v195
	v_cvt_pk_bf16_f32 v119, v192, v193
	global_store_dwordx4 v[200:201], v[116:119], off offset:256
	s_and_saveexec_b64 s[36:37], s[0:1]
	s_cbranch_execz .LBB0_1533
	s_waitcnt lgkmcnt(0)
	v_add_f32_e32 v113, v113, v114
	v_lshlrev_b64 v[114:115], 6, v[168:169]
	v_lshl_add_u64 v[114:115], s[74:75], 0, v[114:115]
	v_lshl_add_u64 v[114:115], s[24:25], 2, v[114:115]
	s_lshl_b32 s8, s50, 2
	v_lshl_add_u64 v[114:115], v[114:115], 0, s[8:9]
	global_store_dword v[114:115], v113, off

.LBB0_1658:
	ds_read_b128 v[96:99], v169
	ds_read_b128 v[100:103], v169 offset:1024
	ds_read_b128 v[104:107], v169 offset:2048
	ds_read_b128 v[108:111], v169 offset:3072
	ds_read_b128 v[112:115], v170
	ds_read_b128 v[116:119], v170 offset:1024
	ds_read_b128 v[120:123], v170 offset:2048
	ds_read_b128 v[124:127], v170 offset:3072
	s_add_u32 s54, s50, 0xfff80080
	s_addc_u32 s55, s51, -1
	s_cmp_eq_u32 s58, 12
	s_cselect_b32 s89, s3, s57
	s_cselect_b32 s88, s5, s56
	s_cselect_b32 s55, s39, s55
	s_cselect_b32 s54, s43, s54
	v_lshl_add_u64 v[164:165], s[50:51], 0, v[138:139]
	s_add_i32 m0, s53, 0xc000
	ds_read_b128 v[146:149], v171
	ds_read_b128 v[150:153], v171 offset:1024
	ds_read_b128 v[154:157], v171 offset:2048
	ds_read_b128 v[158:161], v171 offset:3072
	ds_read_b128 v[174:177], v171 offset:4096
	ds_read_b128 v[178:181], v171 offset:5120
	ds_read_b128 v[182:185], v171 offset:6144
	ds_read_b128 v[186:189], v171 offset:7168
	global_load_lds_dwordx4 v[164:165], off
	v_lshl_add_u64 v[164:165], s[50:51], 0, v[140:141]
	s_add_i32 m0, s53, 0xe000
	s_nop 0
	global_load_lds_dwordx4 v[164:165], off
	s_waitcnt vmcnt(8)
	s_waitcnt lgkmcnt(0)
	s_setprio 1
	s_barrier
	s_waitcnt lgkmcnt(0)
	v_mfma_f32_16x16x32_bf16 v[92:95], v[96:99], v[146:149], v[92:95]
	v_mfma_f32_16x16x32_bf16 v[88:91], v[104:107], v[146:149], v[88:91]
	v_mfma_f32_16x16x32_bf16 v[84:87], v[96:99], v[154:157], v[84:87]
	v_mfma_f32_16x16x32_bf16 v[80:83], v[104:107], v[154:157], v[80:83]
	v_mfma_f32_16x16x32_bf16 v[68:71], v[96:99], v[174:177], v[68:71]
	v_mfma_f32_16x16x32_bf16 v[64:67], v[104:107], v[174:177], v[64:67]
	v_mfma_f32_16x16x32_bf16 v[52:55], v[96:99], v[182:185], v[52:55]
	v_mfma_f32_16x16x32_bf16 v[48:51], v[104:107], v[182:185], v[48:51]
	v_mfma_f32_16x16x32_bf16 v[92:95], v[100:103], v[150:153], v[92:95]
	v_mfma_f32_16x16x32_bf16 v[88:91], v[108:111], v[150:153], v[88:91]
	v_mfma_f32_16x16x32_bf16 v[84:87], v[100:103], v[158:161], v[84:87]
	v_mfma_f32_16x16x32_bf16 v[80:83], v[108:111], v[158:161], v[80:83]
	v_mfma_f32_16x16x32_bf16 v[68:71], v[100:103], v[178:181], v[68:71]
	v_mfma_f32_16x16x32_bf16 v[64:67], v[108:111], v[178:181], v[64:67]
	v_mfma_f32_16x16x32_bf16 v[52:55], v[100:103], v[186:189], v[52:55]
	v_mfma_f32_16x16x32_bf16 v[48:51], v[108:111], v[186:189], v[48:51]
	s_setprio 0
	s_setprio 1
	v_mfma_f32_16x16x32_bf16 v[76:79], v[112:115], v[146:149], v[76:79]
	v_mfma_f32_16x16x32_bf16 v[72:75], v[120:123], v[146:149], v[72:75]
	v_mfma_f32_16x16x32_bf16 v[60:63], v[112:115], v[154:157], v[60:63]
	v_mfma_f32_16x16x32_bf16 v[56:59], v[120:123], v[154:157], v[56:59]
	v_mfma_f32_16x16x32_bf16 v[44:47], v[112:115], v[174:177], v[44:47]
	v_mfma_f32_16x16x32_bf16 v[40:43], v[120:123], v[174:177], v[40:43]
	v_mfma_f32_16x16x32_bf16 v[36:39], v[112:115], v[182:185], v[36:39]
	v_mfma_f32_16x16x32_bf16 v[32:35], v[120:123], v[182:185], v[32:35]
	v_mfma_f32_16x16x32_bf16 v[76:79], v[116:119], v[150:153], v[76:79]
	v_mfma_f32_16x16x32_bf16 v[72:75], v[124:127], v[150:153], v[72:75]
	v_mfma_f32_16x16x32_bf16 v[60:63], v[116:119], v[158:161], v[60:63]
	v_mfma_f32_16x16x32_bf16 v[56:59], v[124:127], v[158:161], v[56:59]
	v_mfma_f32_16x16x32_bf16 v[44:47], v[116:119], v[178:181], v[44:47]
	v_mfma_f32_16x16x32_bf16 v[40:43], v[124:127], v[178:181], v[40:43]
	v_mfma_f32_16x16x32_bf16 v[36:39], v[116:119], v[186:189], v[36:39]
	v_mfma_f32_16x16x32_bf16 v[32:35], v[124:127], v[186:189], v[32:35]
	s_setprio 0
	s_barrier
	s_add_i32 s59, s73, s25
	v_lshl_add_u64 v[164:165], s[54:55], 0, v[130:131]
	s_mov_b32 m0, s59
	ds_read_b128 v[96:99], v172 offset:16384
	ds_read_b128 v[100:103], v172 offset:17408
	ds_read_b128 v[104:107], v172 offset:18432
	ds_read_b128 v[108:111], v172 offset:19456
	global_load_lds_dwordx4 v[164:165], off
	s_add_i32 m0, s59, 0x2000
	s_add_u32 s90, s54, 0x40000
	v_lshl_add_u64 v[190:191], s[54:55], 0, v[134:135]
	s_addc_u32 s91, s55, 0
	s_add_i32 s59, s76, s25
	global_load_lds_dwordx4 v[190:191], off
	v_lshl_add_u64 v[112:113], s[90:91], 0, v[130:131]
	s_mov_b32 m0, s59
	v_lshl_add_u64 v[192:193], s[88:89], 0, v[128:129]
	global_load_lds_dwordx4 v[112:113], off
	v_lshl_add_u64 v[112:113], s[90:91], 0, v[134:135]
	s_add_i32 m0, s59, 0x2000
	v_lshl_add_u64 v[194:195], s[88:89], 0, v[132:133]
	global_load_lds_dwordx4 v[112:113], off
	s_mov_b32 m0, s53
	s_nop 0
	global_load_lds_dwordx4 v[192:193], off
	s_mov_b32 m0, s60
	s_nop 0
	global_load_lds_dwordx4 v[194:195], off
	s_waitcnt vmcnt(8)
	s_waitcnt lgkmcnt(0)
	s_setprio 1
	s_barrier
	s_waitcnt lgkmcnt(0)
	v_mfma_f32_16x16x32_bf16 v[28:31], v[96:99], v[146:149], v[28:31]
	v_mfma_f32_16x16x32_bf16 v[24:27], v[104:107], v[146:149], v[24:27]
	v_mfma_f32_16x16x32_bf16 v[20:23], v[96:99], v[154:157], v[20:23]
	v_mfma_f32_16x16x32_bf16 v[16:19], v[104:107], v[154:157], v[16:19]
	v_mfma_f32_16x16x32_bf16 v[12:15], v[96:99], v[174:177], v[12:15]
	v_mfma_f32_16x16x32_bf16 v[8:11], v[104:107], v[174:177], v[8:11]
	v_mfma_f32_16x16x32_bf16 v[4:7], v[96:99], v[182:185], v[4:7]
	v_mfma_f32_16x16x32_bf16 v[0:3], v[104:107], v[182:185], v[0:3]
	v_mfma_f32_16x16x32_bf16 v[28:31], v[100:103], v[150:153], v[28:31]
	v_mfma_f32_16x16x32_bf16 v[24:27], v[108:111], v[150:153], v[24:27]
	v_mfma_f32_16x16x32_bf16 v[20:23], v[100:103], v[158:161], v[20:23]
	v_mfma_f32_16x16x32_bf16 v[16:19], v[108:111], v[158:161], v[16:19]
	v_mfma_f32_16x16x32_bf16 v[12:15], v[100:103], v[178:181], v[12:15]
	v_mfma_f32_16x16x32_bf16 v[8:11], v[108:111], v[178:181], v[8:11]
	v_mfma_f32_16x16x32_bf16 v[4:7], v[100:103], v[186:189], v[4:7]
	v_mfma_f32_16x16x32_bf16 v[0:3], v[108:111], v[186:189], v[0:3]
	s_setprio 0
	s_barrier
	s_add_i32 s59, 0, 0x18000
	s_add_i32 s87, 0, 0x1c000
	v_add_u32_e32 v108, s59, v167
	v_add_u32_e32 v124, s87, v167
	ds_read_b128 v[96:99], v108
	ds_read_b128 v[100:103], v108 offset:1024
	ds_read_b128 v[104:107], v108 offset:2048
	ds_read_b128 v[108:111], v108 offset:3072
	ds_read_b128 v[112:115], v124
	ds_read_b128 v[116:119], v124 offset:1024
	ds_read_b128 v[120:123], v124 offset:2048
	ds_read_b128 v[124:127], v124 offset:3072
	s_add_u32 s88, s54, 0x80000
	s_addc_u32 s89, s55, 0
	s_mov_b32 m0, s61
	v_lshl_add_u64 v[196:197], s[88:89], 0, v[130:131]
	ds_read_b128 v[146:149], v171 offset:32768
	ds_read_b128 v[150:153], v171 offset:33792
	ds_read_b128 v[154:157], v171 offset:34816
	ds_read_b128 v[158:161], v171 offset:35840
	ds_read_b128 v[174:177], v171 offset:36864
	ds_read_b128 v[178:181], v171 offset:37888
	ds_read_b128 v[182:185], v171 offset:38912
	ds_read_b128 v[186:189], v171 offset:39936
	global_load_lds_dwordx4 v[196:197], off
	v_lshl_add_u64 v[196:197], s[88:89], 0, v[134:135]
	s_mov_b32 m0, s62
	s_nop 0
	global_load_lds_dwordx4 v[196:197], off
	s_waitcnt vmcnt(8)
	s_waitcnt lgkmcnt(0)
	s_setprio 1
	s_barrier
	s_waitcnt lgkmcnt(0)
	v_mfma_f32_16x16x32_bf16 v[92:95], v[96:99], v[146:149], v[92:95]
	v_mfma_f32_16x16x32_bf16 v[88:91], v[104:107], v[146:149], v[88:91]
	v_mfma_f32_16x16x32_bf16 v[84:87], v[96:99], v[154:157], v[84:87]
	v_mfma_f32_16x16x32_bf16 v[80:83], v[104:107], v[154:157], v[80:83]
	v_mfma_f32_16x16x32_bf16 v[68:71], v[96:99], v[174:177], v[68:71]
	v_mfma_f32_16x16x32_bf16 v[64:67], v[104:107], v[174:177], v[64:67]
	v_mfma_f32_16x16x32_bf16 v[52:55], v[96:99], v[182:185], v[52:55]
	v_mfma_f32_16x16x32_bf16 v[48:51], v[104:107], v[182:185], v[48:51]
	v_mfma_f32_16x16x32_bf16 v[92:95], v[100:103], v[150:153], v[92:95]
	v_mfma_f32_16x16x32_bf16 v[88:91], v[108:111], v[150:153], v[88:91]
	v_mfma_f32_16x16x32_bf16 v[84:87], v[100:103], v[158:161], v[84:87]
	v_mfma_f32_16x16x32_bf16 v[80:83], v[108:111], v[158:161], v[80:83]
	v_mfma_f32_16x16x32_bf16 v[68:71], v[100:103], v[178:181], v[68:71]
	v_mfma_f32_16x16x32_bf16 v[64:67], v[108:111], v[178:181], v[64:67]
	v_mfma_f32_16x16x32_bf16 v[52:55], v[100:103], v[186:189], v[52:55]
	v_mfma_f32_16x16x32_bf16 v[48:51], v[108:111], v[186:189], v[48:51]
	s_setprio 0
	s_setprio 1
	v_mfma_f32_16x16x32_bf16 v[76:79], v[112:115], v[146:149], v[76:79]
	v_mfma_f32_16x16x32_bf16 v[72:75], v[120:123], v[146:149], v[72:75]
	v_mfma_f32_16x16x32_bf16 v[60:63], v[112:115], v[154:157], v[60:63]
	v_mfma_f32_16x16x32_bf16 v[56:59], v[120:123], v[154:157], v[56:59]
	v_mfma_f32_16x16x32_bf16 v[44:47], v[112:115], v[174:177], v[44:47]
	v_mfma_f32_16x16x32_bf16 v[40:43], v[120:123], v[174:177], v[40:43]
	v_mfma_f32_16x16x32_bf16 v[36:39], v[112:115], v[182:185], v[36:39]
	v_mfma_f32_16x16x32_bf16 v[32:35], v[120:123], v[182:185], v[32:35]
	v_mfma_f32_16x16x32_bf16 v[76:79], v[116:119], v[150:153], v[76:79]
	v_mfma_f32_16x16x32_bf16 v[72:75], v[124:127], v[150:153], v[72:75]
	v_mfma_f32_16x16x32_bf16 v[60:63], v[116:119], v[158:161], v[60:63]
	v_mfma_f32_16x16x32_bf16 v[56:59], v[124:127], v[158:161], v[56:59]
	v_mfma_f32_16x16x32_bf16 v[44:47], v[116:119], v[178:181], v[44:47]
	v_mfma_f32_16x16x32_bf16 v[40:43], v[124:127], v[178:181], v[40:43]
	v_mfma_f32_16x16x32_bf16 v[36:39], v[116:119], v[186:189], v[36:39]
	v_mfma_f32_16x16x32_bf16 v[32:35], v[124:127], v[186:189], v[32:35]
	s_setprio 0
	s_barrier
	s_add_i32 s59, s59, s25
	v_lshl_add_u64 v[112:113], v[164:165], 0, s[14:15]
	s_mov_b32 m0, s59
	ds_read_b128 v[96:99], v172 offset:49152
	ds_read_b128 v[100:103], v172 offset:50176
	ds_read_b128 v[104:107], v172 offset:51200
	ds_read_b128 v[108:111], v172 offset:52224
	global_load_lds_dwordx4 v[112:113], off
	s_add_i32 m0, s59, 0x2000
	s_add_u32 s54, s54, 0x40080
	v_lshl_add_u64 v[112:113], v[190:191], 0, s[14:15]
	s_addc_u32 s55, s55, 0
	s_add_i32 s59, s87, s25
	global_load_lds_dwordx4 v[112:113], off
	v_lshl_add_u64 v[112:113], s[54:55], 0, v[130:131]
	s_mov_b32 m0, s59
	s_nop 0
	global_load_lds_dwordx4 v[112:113], off
	v_lshl_add_u64 v[112:113], s[54:55], 0, v[134:135]
	s_add_i32 m0, s59, 0x2000
	s_nop 0
	global_load_lds_dwordx4 v[112:113], off
	v_lshl_add_u64 v[112:113], v[192:193], 0, s[14:15]
	s_mov_b32 m0, s63
	s_nop 0
	global_load_lds_dwordx4 v[112:113], off
	v_lshl_add_u64 v[112:113], v[194:195], 0, s[14:15]
	s_mov_b32 m0, s64
	s_nop 0
	global_load_lds_dwordx4 v[112:113], off
	s_waitcnt vmcnt(8)
	s_waitcnt lgkmcnt(0)
	s_setprio 1
	s_barrier
	s_waitcnt lgkmcnt(0)
	v_mfma_f32_16x16x32_bf16 v[28:31], v[96:99], v[146:149], v[28:31]
	v_mfma_f32_16x16x32_bf16 v[24:27], v[104:107], v[146:149], v[24:27]
	v_mfma_f32_16x16x32_bf16 v[20:23], v[96:99], v[154:157], v[20:23]
	v_mfma_f32_16x16x32_bf16 v[16:19], v[104:107], v[154:157], v[16:19]
	v_mfma_f32_16x16x32_bf16 v[12:15], v[96:99], v[174:177], v[12:15]
	v_mfma_f32_16x16x32_bf16 v[8:11], v[104:107], v[174:177], v[8:11]
	v_mfma_f32_16x16x32_bf16 v[4:7], v[96:99], v[182:185], v[4:7]
	v_mfma_f32_16x16x32_bf16 v[0:3], v[104:107], v[182:185], v[0:3]
	v_mfma_f32_16x16x32_bf16 v[28:31], v[100:103], v[150:153], v[28:31]
	v_mfma_f32_16x16x32_bf16 v[24:27], v[108:111], v[150:153], v[24:27]
	v_mfma_f32_16x16x32_bf16 v[20:23], v[100:103], v[158:161], v[20:23]
	v_mfma_f32_16x16x32_bf16 v[16:19], v[108:111], v[158:161], v[16:19]
	v_mfma_f32_16x16x32_bf16 v[12:15], v[100:103], v[178:181], v[12:15]
	v_mfma_f32_16x16x32_bf16 v[8:11], v[108:111], v[178:181], v[8:11]
	v_mfma_f32_16x16x32_bf16 v[4:7], v[100:103], v[186:189], v[4:7]
	v_mfma_f32_16x16x32_bf16 v[0:3], v[108:111], v[186:189], v[0:3]
	s_setprio 0
	s_barrier
	s_add_i32 s58, s58, 2
	s_add_u32 s56, s56, 0x100
	s_addc_u32 s57, s57, 0
	s_add_u32 s50, s50, 0x100
	s_addc_u32 s51, s51, 0
	s_cmp_gt_u32 s58, 13
	s_cbranch_scc0 .LBB0_1658
	s_mov_b64 s[50:51], 0
	s_branch .LBB0_1661

.LBB0_1663:
	ds_read_b128 v[146:149], v169
	ds_read_b128 v[150:153], v169 offset:1024
	ds_read_b128 v[154:157], v169 offset:2048
	ds_read_b128 v[158:161], v169 offset:3072
	ds_read_b128 v[174:177], v170
	ds_read_b128 v[178:181], v170 offset:1024
	ds_read_b128 v[182:185], v170 offset:2048
	ds_read_b128 v[186:189], v170 offset:3072
	s_add_u32 s58, s48, 0xfffc0080
	s_addc_u32 s59, s49, -1
	s_cmp_eq_u32 s89, 12
	s_cselect_b64 s[56:57], -1, 0
	s_and_b64 s[54:55], s[56:57], exec
	s_cselect_b32 s55, s39, s86
	s_cselect_b32 s54, s43, s85
	s_cselect_b32 s59, s3, s59
	s_cselect_b32 s58, s5, s58
	v_lshl_add_u64 v[164:165], s[48:49], 0, v[142:143]
	s_add_i32 m0, s53, 0xc000
	ds_read_b128 v[190:193], v171
	ds_read_b128 v[194:197], v171 offset:1024
	ds_read_b128 v[198:201], v171 offset:2048
	ds_read_b128 v[202:205], v171 offset:3072
	ds_read_b128 v[206:209], v171 offset:4096
	ds_read_b128 v[210:213], v171 offset:5120
	ds_read_b128 v[214:217], v171 offset:6144
	ds_read_b128 v[218:221], v171 offset:7168
	global_load_lds_dwordx4 v[164:165], off
	v_lshl_add_u64 v[164:165], s[48:49], 0, v[132:133]
	s_add_i32 m0, s53, 0xe000
	s_nop 0
	global_load_lds_dwordx4 v[164:165], off
	s_waitcnt vmcnt(8)
	s_waitcnt lgkmcnt(0)
	s_setprio 1
	s_barrier
	s_waitcnt lgkmcnt(0)
	v_mfma_f32_16x16x32_bf16 v[92:95], v[146:149], v[190:193], v[92:95]
	v_mfma_f32_16x16x32_bf16 v[88:91], v[154:157], v[190:193], v[88:91]
	v_mfma_f32_16x16x32_bf16 v[84:87], v[146:149], v[198:201], v[84:87]
	v_mfma_f32_16x16x32_bf16 v[80:83], v[154:157], v[198:201], v[80:83]
	v_mfma_f32_16x16x32_bf16 v[68:71], v[146:149], v[206:209], v[68:71]
	v_mfma_f32_16x16x32_bf16 v[64:67], v[154:157], v[206:209], v[64:67]
	v_mfma_f32_16x16x32_bf16 v[52:55], v[146:149], v[214:217], v[52:55]
	v_mfma_f32_16x16x32_bf16 v[48:51], v[154:157], v[214:217], v[48:51]
	v_mfma_f32_16x16x32_bf16 v[92:95], v[150:153], v[194:197], v[92:95]
	v_mfma_f32_16x16x32_bf16 v[88:91], v[158:161], v[194:197], v[88:91]
	v_mfma_f32_16x16x32_bf16 v[84:87], v[150:153], v[202:205], v[84:87]
	v_mfma_f32_16x16x32_bf16 v[80:83], v[158:161], v[202:205], v[80:83]
	v_mfma_f32_16x16x32_bf16 v[68:71], v[150:153], v[210:213], v[68:71]
	v_mfma_f32_16x16x32_bf16 v[64:67], v[158:161], v[210:213], v[64:67]
	v_mfma_f32_16x16x32_bf16 v[52:55], v[150:153], v[218:221], v[52:55]
	v_mfma_f32_16x16x32_bf16 v[48:51], v[158:161], v[218:221], v[48:51]
	s_setprio 0
	s_setprio 1
	v_mfma_f32_16x16x32_bf16 v[76:79], v[174:177], v[190:193], v[76:79]
	v_mfma_f32_16x16x32_bf16 v[72:75], v[182:185], v[190:193], v[72:75]
	v_mfma_f32_16x16x32_bf16 v[60:63], v[174:177], v[198:201], v[60:63]
	v_mfma_f32_16x16x32_bf16 v[56:59], v[182:185], v[198:201], v[56:59]
	v_mfma_f32_16x16x32_bf16 v[44:47], v[174:177], v[206:209], v[44:47]
	v_mfma_f32_16x16x32_bf16 v[40:43], v[182:185], v[206:209], v[40:43]
	v_mfma_f32_16x16x32_bf16 v[36:39], v[174:177], v[214:217], v[36:39]
	v_mfma_f32_16x16x32_bf16 v[32:35], v[182:185], v[214:217], v[32:35]
	v_mfma_f32_16x16x32_bf16 v[76:79], v[178:181], v[194:197], v[76:79]
	v_mfma_f32_16x16x32_bf16 v[72:75], v[186:189], v[194:197], v[72:75]
	v_mfma_f32_16x16x32_bf16 v[60:63], v[178:181], v[202:205], v[60:63]
	v_mfma_f32_16x16x32_bf16 v[56:59], v[186:189], v[202:205], v[56:59]
	v_mfma_f32_16x16x32_bf16 v[44:47], v[178:181], v[210:213], v[44:47]
	v_mfma_f32_16x16x32_bf16 v[40:43], v[186:189], v[210:213], v[40:43]
	v_mfma_f32_16x16x32_bf16 v[36:39], v[178:181], v[218:221], v[36:39]
	v_mfma_f32_16x16x32_bf16 v[32:35], v[186:189], v[218:221], v[32:35]
	s_setprio 0
	s_barrier
	s_add_i32 s90, s73, s25
	v_lshl_add_u64 v[164:165], s[54:55], 0, v[130:131]
	s_mov_b32 m0, s90
	ds_read_b128 v[190:193], v171 offset:16384
	ds_read_b128 v[194:197], v171 offset:17408
	ds_read_b128 v[198:201], v171 offset:18432
	ds_read_b128 v[202:205], v171 offset:19456
	ds_read_b128 v[206:209], v171 offset:20480
	ds_read_b128 v[210:213], v171 offset:21504
	ds_read_b128 v[214:217], v171 offset:22528
	ds_read_b128 v[218:221], v171 offset:23552
	global_load_lds_dwordx4 v[164:165], off
	s_add_i32 m0, s90, 0x2000
	s_add_u32 s90, s54, 0x40000
	v_lshl_add_u64 v[222:223], s[54:55], 0, v[134:135]
	s_addc_u32 s91, s55, 0
	s_add_i32 s92, s76, s25
	global_load_lds_dwordx4 v[222:223], off
	v_lshl_add_u64 v[224:225], s[90:91], 0, v[130:131]
	s_mov_b32 m0, s92
	v_lshl_add_u64 v[226:227], s[58:59], 0, v[132:133]
	global_load_lds_dwordx4 v[224:225], off
	v_lshl_add_u64 v[224:225], s[90:91], 0, v[134:135]
	s_add_i32 m0, s92, 0x2000
	s_nop 0
	global_load_lds_dwordx4 v[224:225], off
	v_lshl_add_u64 v[224:225], s[58:59], 0, v[128:129]
	s_mov_b32 m0, s53
	s_nop 0
	global_load_lds_dwordx4 v[224:225], off
	s_mov_b32 m0, s60
	s_nop 0
	global_load_lds_dwordx4 v[226:227], off
	s_waitcnt vmcnt(8)
	s_waitcnt lgkmcnt(0)
	s_setprio 1
	s_barrier
	s_waitcnt lgkmcnt(0)
	v_mfma_f32_16x16x32_bf16 v[28:31], v[146:149], v[190:193], v[28:31]
	v_mfma_f32_16x16x32_bf16 v[24:27], v[154:157], v[190:193], v[24:27]
	v_mfma_f32_16x16x32_bf16 v[20:23], v[146:149], v[198:201], v[20:23]
	v_mfma_f32_16x16x32_bf16 v[16:19], v[154:157], v[198:201], v[16:19]
	v_mfma_f32_16x16x32_bf16 v[12:15], v[146:149], v[206:209], v[12:15]
	v_mfma_f32_16x16x32_bf16 v[8:11], v[154:157], v[206:209], v[8:11]
	v_mfma_f32_16x16x32_bf16 v[4:7], v[146:149], v[214:217], v[4:7]
	v_mfma_f32_16x16x32_bf16 v[0:3], v[154:157], v[214:217], v[0:3]
	v_mfma_f32_16x16x32_bf16 v[28:31], v[150:153], v[194:197], v[28:31]
	v_mfma_f32_16x16x32_bf16 v[24:27], v[158:161], v[194:197], v[24:27]
	v_mfma_f32_16x16x32_bf16 v[20:23], v[150:153], v[202:205], v[20:23]
	v_mfma_f32_16x16x32_bf16 v[16:19], v[158:161], v[202:205], v[16:19]
	v_mfma_f32_16x16x32_bf16 v[12:15], v[150:153], v[210:213], v[12:15]
	v_mfma_f32_16x16x32_bf16 v[8:11], v[158:161], v[210:213], v[8:11]
	v_mfma_f32_16x16x32_bf16 v[4:7], v[150:153], v[218:221], v[4:7]
	v_mfma_f32_16x16x32_bf16 v[0:3], v[158:161], v[218:221], v[0:3]
	s_setprio 0
	s_setprio 1
	v_mfma_f32_16x16x32_bf16 v[124:127], v[174:177], v[190:193], v[124:127]
	v_mfma_f32_16x16x32_bf16 v[120:123], v[182:185], v[190:193], v[120:123]
	v_mfma_f32_16x16x32_bf16 v[116:119], v[174:177], v[198:201], v[116:119]
	v_mfma_f32_16x16x32_bf16 v[112:115], v[182:185], v[198:201], v[112:115]
	v_mfma_f32_16x16x32_bf16 v[108:111], v[174:177], v[206:209], v[108:111]
	v_mfma_f32_16x16x32_bf16 v[104:107], v[182:185], v[206:209], v[104:107]
	v_mfma_f32_16x16x32_bf16 v[100:103], v[174:177], v[214:217], v[100:103]
	v_mfma_f32_16x16x32_bf16 v[96:99], v[182:185], v[214:217], v[96:99]
	v_mfma_f32_16x16x32_bf16 v[124:127], v[178:181], v[194:197], v[124:127]
	v_mfma_f32_16x16x32_bf16 v[120:123], v[186:189], v[194:197], v[120:123]
	v_mfma_f32_16x16x32_bf16 v[116:119], v[178:181], v[202:205], v[116:119]
	v_mfma_f32_16x16x32_bf16 v[112:115], v[186:189], v[202:205], v[112:115]
	v_mfma_f32_16x16x32_bf16 v[108:111], v[178:181], v[210:213], v[108:111]
	v_mfma_f32_16x16x32_bf16 v[104:107], v[186:189], v[210:213], v[104:107]
	v_mfma_f32_16x16x32_bf16 v[100:103], v[178:181], v[218:221], v[100:103]
	v_mfma_f32_16x16x32_bf16 v[96:99], v[186:189], v[218:221], v[96:99]
	s_setprio 0
	s_barrier
	s_add_i32 s90, 0, 0x18000
	s_add_i32 s91, 0, 0x1c000
	v_add_u32_e32 v158, s90, v167
	v_add_u32_e32 v162, s91, v167
	ds_read_b128 v[146:149], v158
	ds_read_b128 v[150:153], v158 offset:1024
	ds_read_b128 v[154:157], v158 offset:2048
	ds_read_b128 v[158:161], v158 offset:3072
	ds_read_b128 v[174:177], v162
	ds_read_b128 v[178:181], v162 offset:1024
	ds_read_b128 v[182:185], v162 offset:2048
	ds_read_b128 v[186:189], v162 offset:3072
	s_and_b64 s[56:57], s[40:41], s[56:57]
	s_and_b64 vcc, s[56:57], s[50:51]
	s_add_u32 s58, s58, 0x40000
	s_addc_u32 s59, s59, 0
	s_and_b64 s[56:57], vcc, exec
	s_mov_b32 m0, s61
	v_cndmask_b32_e32 v162, v128, v130, vcc
	s_cselect_b32 s57, s88, s59
	s_cselect_b32 s56, s87, s58
	ds_read_b128 v[190:193], v171 offset:32768
	ds_read_b128 v[194:197], v171 offset:33792
	ds_read_b128 v[198:201], v171 offset:34816
	ds_read_b128 v[202:205], v171 offset:35840
	ds_read_b128 v[206:209], v171 offset:36864
	ds_read_b128 v[210:213], v171 offset:37888
	ds_read_b128 v[214:217], v171 offset:38912
	ds_read_b128 v[218:221], v171 offset:39936
	v_cndmask_b32_e32 v166, v132, v134, vcc
	global_load_lds_dwordx4 v162, s[56:57]
	s_mov_b32 m0, s62
	s_nop 0
	global_load_lds_dwordx4 v166, s[56:57]
	s_waitcnt vmcnt(8)
	s_waitcnt lgkmcnt(0)
	s_setprio 1
	s_barrier
	s_waitcnt lgkmcnt(0)
	v_mfma_f32_16x16x32_bf16 v[92:95], v[146:149], v[190:193], v[92:95]
	v_mfma_f32_16x16x32_bf16 v[88:91], v[154:157], v[190:193], v[88:91]
	v_mfma_f32_16x16x32_bf16 v[84:87], v[146:149], v[198:201], v[84:87]
	v_mfma_f32_16x16x32_bf16 v[80:83], v[154:157], v[198:201], v[80:83]
	v_mfma_f32_16x16x32_bf16 v[68:71], v[146:149], v[206:209], v[68:71]
	v_mfma_f32_16x16x32_bf16 v[64:67], v[154:157], v[206:209], v[64:67]
	v_mfma_f32_16x16x32_bf16 v[52:55], v[146:149], v[214:217], v[52:55]
	v_mfma_f32_16x16x32_bf16 v[48:51], v[154:157], v[214:217], v[48:51]
	v_mfma_f32_16x16x32_bf16 v[92:95], v[150:153], v[194:197], v[92:95]
	v_mfma_f32_16x16x32_bf16 v[88:91], v[158:161], v[194:197], v[88:91]
	v_mfma_f32_16x16x32_bf16 v[84:87], v[150:153], v[202:205], v[84:87]
	v_mfma_f32_16x16x32_bf16 v[80:83], v[158:161], v[202:205], v[80:83]
	v_mfma_f32_16x16x32_bf16 v[68:71], v[150:153], v[210:213], v[68:71]
	v_mfma_f32_16x16x32_bf16 v[64:67], v[158:161], v[210:213], v[64:67]
	v_mfma_f32_16x16x32_bf16 v[52:55], v[150:153], v[218:221], v[52:55]
	v_mfma_f32_16x16x32_bf16 v[48:51], v[158:161], v[218:221], v[48:51]
	s_setprio 0
	s_setprio 1
	v_mfma_f32_16x16x32_bf16 v[76:79], v[174:177], v[190:193], v[76:79]
	v_mfma_f32_16x16x32_bf16 v[72:75], v[182:185], v[190:193], v[72:75]
	v_mfma_f32_16x16x32_bf16 v[60:63], v[174:177], v[198:201], v[60:63]
	v_mfma_f32_16x16x32_bf16 v[56:59], v[182:185], v[198:201], v[56:59]
	v_mfma_f32_16x16x32_bf16 v[44:47], v[174:177], v[206:209], v[44:47]
	v_mfma_f32_16x16x32_bf16 v[40:43], v[182:185], v[206:209], v[40:43]
	v_mfma_f32_16x16x32_bf16 v[36:39], v[174:177], v[214:217], v[36:39]
	v_mfma_f32_16x16x32_bf16 v[32:35], v[182:185], v[214:217], v[32:35]
	v_mfma_f32_16x16x32_bf16 v[76:79], v[178:181], v[194:197], v[76:79]
	v_mfma_f32_16x16x32_bf16 v[72:75], v[186:189], v[194:197], v[72:75]
	v_mfma_f32_16x16x32_bf16 v[60:63], v[178:181], v[202:205], v[60:63]
	v_mfma_f32_16x16x32_bf16 v[56:59], v[186:189], v[202:205], v[56:59]
	v_mfma_f32_16x16x32_bf16 v[44:47], v[178:181], v[210:213], v[44:47]
	v_mfma_f32_16x16x32_bf16 v[40:43], v[186:189], v[210:213], v[40:43]
	v_mfma_f32_16x16x32_bf16 v[36:39], v[178:181], v[218:221], v[36:39]
	v_mfma_f32_16x16x32_bf16 v[32:35], v[186:189], v[218:221], v[32:35]
	s_setprio 0
	s_barrier
	s_add_i32 s56, s90, s25
	v_lshl_add_u64 v[164:165], v[164:165], 0, s[14:15]
	s_mov_b32 m0, s56
	ds_read_b128 v[190:193], v171 offset:49152
	ds_read_b128 v[194:197], v171 offset:50176
	ds_read_b128 v[198:201], v171 offset:51200
	ds_read_b128 v[202:205], v171 offset:52224
	ds_read_b128 v[206:209], v171 offset:53248
	ds_read_b128 v[210:213], v171 offset:54272
	ds_read_b128 v[214:217], v171 offset:55296
	ds_read_b128 v[218:221], v171 offset:56320
	global_load_lds_dwordx4 v[164:165], off
	s_add_i32 m0, s56, 0x2000
	s_add_u32 s54, s54, 0x40080
	v_lshl_add_u64 v[164:165], v[222:223], 0, s[14:15]
	s_addc_u32 s55, s55, 0
	s_add_i32 s56, s91, s25
	global_load_lds_dwordx4 v[164:165], off
	v_lshl_add_u64 v[164:165], s[54:55], 0, v[130:131]
	s_mov_b32 m0, s56
	s_nop 0
	global_load_lds_dwordx4 v[164:165], off
	v_lshl_add_u64 v[164:165], s[54:55], 0, v[134:135]
	s_add_i32 m0, s56, 0x2000
	s_nop 0
	global_load_lds_dwordx4 v[164:165], off
	v_lshl_add_u64 v[164:165], v[224:225], 0, s[14:15]
	s_mov_b32 m0, s63
	s_nop 0
	global_load_lds_dwordx4 v[164:165], off
	v_lshl_add_u64 v[164:165], v[226:227], 0, s[14:15]
	s_mov_b32 m0, s64
	s_nop 0
	global_load_lds_dwordx4 v[164:165], off
	s_waitcnt vmcnt(8)
	s_waitcnt lgkmcnt(0)
	s_setprio 1
	s_barrier
	s_waitcnt lgkmcnt(0)
	v_mfma_f32_16x16x32_bf16 v[28:31], v[146:149], v[190:193], v[28:31]
	v_mfma_f32_16x16x32_bf16 v[24:27], v[154:157], v[190:193], v[24:27]
	v_mfma_f32_16x16x32_bf16 v[20:23], v[146:149], v[198:201], v[20:23]
	v_mfma_f32_16x16x32_bf16 v[16:19], v[154:157], v[198:201], v[16:19]
	v_mfma_f32_16x16x32_bf16 v[12:15], v[146:149], v[206:209], v[12:15]
	v_mfma_f32_16x16x32_bf16 v[8:11], v[154:157], v[206:209], v[8:11]
	v_mfma_f32_16x16x32_bf16 v[4:7], v[146:149], v[214:217], v[4:7]
	v_mfma_f32_16x16x32_bf16 v[0:3], v[154:157], v[214:217], v[0:3]
	v_mfma_f32_16x16x32_bf16 v[28:31], v[150:153], v[194:197], v[28:31]
	v_mfma_f32_16x16x32_bf16 v[24:27], v[158:161], v[194:197], v[24:27]
	v_mfma_f32_16x16x32_bf16 v[20:23], v[150:153], v[202:205], v[20:23]
	v_mfma_f32_16x16x32_bf16 v[16:19], v[158:161], v[202:205], v[16:19]
	v_mfma_f32_16x16x32_bf16 v[12:15], v[150:153], v[210:213], v[12:15]
	v_mfma_f32_16x16x32_bf16 v[8:11], v[158:161], v[210:213], v[8:11]
	v_mfma_f32_16x16x32_bf16 v[4:7], v[150:153], v[218:221], v[4:7]
	v_mfma_f32_16x16x32_bf16 v[0:3], v[158:161], v[218:221], v[0:3]
	s_setprio 0
	s_setprio 1
	v_mfma_f32_16x16x32_bf16 v[124:127], v[174:177], v[190:193], v[124:127]
	v_mfma_f32_16x16x32_bf16 v[120:123], v[182:185], v[190:193], v[120:123]
	v_mfma_f32_16x16x32_bf16 v[116:119], v[174:177], v[198:201], v[116:119]
	v_mfma_f32_16x16x32_bf16 v[112:115], v[182:185], v[198:201], v[112:115]
	v_mfma_f32_16x16x32_bf16 v[108:111], v[174:177], v[206:209], v[108:111]
	v_mfma_f32_16x16x32_bf16 v[104:107], v[182:185], v[206:209], v[104:107]
	v_mfma_f32_16x16x32_bf16 v[100:103], v[174:177], v[214:217], v[100:103]
	v_mfma_f32_16x16x32_bf16 v[96:99], v[182:185], v[214:217], v[96:99]
	v_mfma_f32_16x16x32_bf16 v[124:127], v[178:181], v[194:197], v[124:127]
	v_mfma_f32_16x16x32_bf16 v[120:123], v[186:189], v[194:197], v[120:123]
	v_mfma_f32_16x16x32_bf16 v[116:119], v[178:181], v[202:205], v[116:119]
	v_mfma_f32_16x16x32_bf16 v[112:115], v[186:189], v[202:205], v[112:115]
	v_mfma_f32_16x16x32_bf16 v[108:111], v[178:181], v[210:213], v[108:111]
	v_mfma_f32_16x16x32_bf16 v[104:107], v[186:189], v[210:213], v[104:107]
	v_mfma_f32_16x16x32_bf16 v[100:103], v[178:181], v[218:221], v[100:103]
	v_mfma_f32_16x16x32_bf16 v[96:99], v[186:189], v[218:221], v[96:99]
	s_setprio 0
	s_barrier
	s_add_i32 s89, s89, 2
	s_add_u32 s48, s48, 0x100
	s_addc_u32 s49, s49, 0
	s_add_u32 s85, s85, 0x100
	s_addc_u32 s86, s86, 0
	s_cmp_gt_u32 s89, 13
	s_cbranch_scc0 .LBB0_1663

.LBB0_1749:
	ds_read_b128 v[2:5], v243
	ds_read_b128 v[6:9], v243 offset:1024
	ds_read_b128 v[10:13], v243 offset:2048
	ds_read_b128 v[18:21], v243 offset:3072
	ds_read_b128 v[26:29], v244
	ds_read_b128 v[30:33], v244 offset:1024
	ds_read_b128 v[38:41], v244 offset:2048
	ds_read_b128 v[46:49], v244 offset:3072
	s_add_u32 s62, s60, 0xfff80080
	s_addc_u32 s63, s61, -1
	s_cmp_eq_u32 s66, 12
	s_cselect_b32 s69, s3, s65
	s_cselect_b32 s68, s5, s64
	s_cselect_b32 s63, s49, s63
	s_cselect_b32 s62, s52, s62
	v_lshl_add_u64 v[162:163], s[60:61], 0, v[192:193]
	s_add_i32 m0, s71, 0xc000
	ds_read_b128 v[130:133], v245
	ds_read_b128 v[134:137], v245 offset:1024
	ds_read_b128 v[138:141], v245 offset:2048
	ds_read_b128 v[142:145], v245 offset:3072
	ds_read_b128 v[146:149], v245 offset:4096
	ds_read_b128 v[150:153], v245 offset:5120
	ds_read_b128 v[154:157], v245 offset:6144
	ds_read_b128 v[158:161], v245 offset:7168
	global_load_lds_dwordx4 v[162:163], off
	v_lshl_add_u64 v[162:163], s[60:61], 0, v[194:195]
	s_add_i32 m0, s71, 0xe000
	s_nop 0
	global_load_lds_dwordx4 v[162:163], off
	s_waitcnt vmcnt(8)
	s_waitcnt lgkmcnt(0)
	s_setprio 1
	s_barrier
	s_waitcnt lgkmcnt(0)
	v_mfma_f32_16x16x32_bf16 v[126:129], v[2:5], v[130:133], v[126:129]
	v_mfma_f32_16x16x32_bf16 v[122:125], v[10:13], v[130:133], v[122:125]
	v_mfma_f32_16x16x32_bf16 v[118:121], v[2:5], v[138:141], v[118:121]
	v_mfma_f32_16x16x32_bf16 v[114:117], v[10:13], v[138:141], v[114:117]
	v_mfma_f32_16x16x32_bf16 v[110:113], v[2:5], v[146:149], v[110:113]
	v_mfma_f32_16x16x32_bf16 v[106:109], v[10:13], v[146:149], v[106:109]
	v_mfma_f32_16x16x32_bf16 v[2:5], v[2:5], v[154:157], v[102:105]
	v_mfma_f32_16x16x32_bf16 v[126:129], v[6:9], v[134:137], v[126:129]
	v_mfma_f32_16x16x32_bf16 v[122:125], v[18:21], v[134:137], v[122:125]
	v_mfma_f32_16x16x32_bf16 v[118:121], v[6:9], v[142:145], v[118:121]
	v_mfma_f32_16x16x32_bf16 v[114:117], v[18:21], v[142:145], v[114:117]
	v_mfma_f32_16x16x32_bf16 v[110:113], v[6:9], v[150:153], v[110:113]
	v_mfma_f32_16x16x32_bf16 v[106:109], v[18:21], v[150:153], v[106:109]
	v_mfma_f32_16x16x32_bf16 v[2:5], v[6:9], v[158:161], v[2:5]
	v_mfma_f32_16x16x32_bf16 v[6:9], v[10:13], v[154:157], v[98:101]
	v_mfma_f32_16x16x32_bf16 v[6:9], v[18:21], v[158:161], v[6:9]
	s_setprio 0
	s_setprio 1
	v_mfma_f32_16x16x32_bf16 v[10:13], v[26:29], v[130:133], v[94:97]
	v_mfma_f32_16x16x32_bf16 v[86:89], v[26:29], v[138:141], v[86:89]
	v_mfma_f32_16x16x32_bf16 v[82:85], v[38:41], v[138:141], v[82:85]
	v_mfma_f32_16x16x32_bf16 v[78:81], v[26:29], v[146:149], v[78:81]
	v_mfma_f32_16x16x32_bf16 v[74:77], v[38:41], v[146:149], v[74:77]
	v_mfma_f32_16x16x32_bf16 v[26:29], v[26:29], v[154:157], v[70:73]
	v_mfma_f32_16x16x32_bf16 v[10:13], v[30:33], v[134:137], v[10:13]
	v_mfma_f32_16x16x32_bf16 v[18:21], v[38:41], v[130:133], v[90:93]
	v_mfma_f32_16x16x32_bf16 v[86:89], v[30:33], v[142:145], v[86:89]
	v_mfma_f32_16x16x32_bf16 v[82:85], v[46:49], v[142:145], v[82:85]
	v_mfma_f32_16x16x32_bf16 v[78:81], v[30:33], v[150:153], v[78:81]
	v_mfma_f32_16x16x32_bf16 v[74:77], v[46:49], v[150:153], v[74:77]
	v_mfma_f32_16x16x32_bf16 v[26:29], v[30:33], v[158:161], v[26:29]
	v_mfma_f32_16x16x32_bf16 v[30:33], v[38:41], v[154:157], v[66:69]
	v_mfma_f32_16x16x32_bf16 v[18:21], v[46:49], v[134:137], v[18:21]
	v_mfma_f32_16x16x32_bf16 v[30:33], v[46:49], v[158:161], v[30:33]
	s_setprio 0
	s_barrier
	s_add_i32 s67, s74, s70
	v_lshl_add_u64 v[178:179], s[62:63], 0, v[184:185]
	s_mov_b32 m0, s67
	ds_read_b128 v[38:41], v246 offset:16384
	ds_read_b128 v[46:49], v246 offset:17408
	ds_read_b128 v[66:69], v246 offset:18432
	ds_read_b128 v[70:73], v246 offset:19456
	global_load_lds_dwordx4 v[178:179], off
	s_add_i32 m0, s67, 0x2000
	s_add_u32 s72, s62, 0x40000
	v_lshl_add_u64 v[180:181], s[62:63], 0, v[188:189]
	s_addc_u32 s73, s63, 0
	s_add_i32 s67, s75, s70
	global_load_lds_dwordx4 v[180:181], off
	v_lshl_add_u64 v[90:91], s[72:73], 0, v[184:185]
	s_mov_b32 m0, s67
	v_lshl_add_u64 v[198:199], s[68:69], 0, v[182:183]
	global_load_lds_dwordx4 v[90:91], off
	v_lshl_add_u64 v[90:91], s[72:73], 0, v[188:189]
	s_add_i32 m0, s67, 0x2000
	v_lshl_add_u64 v[200:201], s[68:69], 0, v[186:187]
	global_load_lds_dwordx4 v[90:91], off
	s_mov_b32 m0, s71
	s_nop 0
	global_load_lds_dwordx4 v[198:199], off
	s_mov_b32 m0, s76
	s_nop 0
	global_load_lds_dwordx4 v[200:201], off
	s_waitcnt vmcnt(8)
	s_waitcnt lgkmcnt(0)
	s_setprio 1
	s_barrier
	s_waitcnt lgkmcnt(0)
	v_mfma_f32_16x16x32_bf16 v[62:65], v[38:41], v[130:133], v[62:65]
	v_mfma_f32_16x16x32_bf16 v[58:61], v[66:69], v[130:133], v[58:61]
	v_mfma_f32_16x16x32_bf16 v[54:57], v[38:41], v[138:141], v[54:57]
	v_mfma_f32_16x16x32_bf16 v[50:53], v[66:69], v[138:141], v[50:53]
	v_mfma_f32_16x16x32_bf16 v[42:45], v[38:41], v[146:149], v[42:45]
	v_mfma_f32_16x16x32_bf16 v[34:37], v[66:69], v[146:149], v[34:37]
	v_mfma_f32_16x16x32_bf16 v[22:25], v[38:41], v[154:157], v[22:25]
	v_mfma_f32_16x16x32_bf16 v[14:17], v[66:69], v[154:157], v[14:17]
	v_mfma_f32_16x16x32_bf16 v[62:65], v[46:49], v[134:137], v[62:65]
	v_mfma_f32_16x16x32_bf16 v[58:61], v[70:73], v[134:137], v[58:61]
	v_mfma_f32_16x16x32_bf16 v[54:57], v[46:49], v[142:145], v[54:57]
	v_mfma_f32_16x16x32_bf16 v[50:53], v[70:73], v[142:145], v[50:53]
	v_mfma_f32_16x16x32_bf16 v[42:45], v[46:49], v[150:153], v[42:45]
	v_mfma_f32_16x16x32_bf16 v[34:37], v[70:73], v[150:153], v[34:37]
	v_mfma_f32_16x16x32_bf16 v[22:25], v[46:49], v[158:161], v[22:25]
	v_mfma_f32_16x16x32_bf16 v[14:17], v[70:73], v[158:161], v[14:17]
	s_setprio 0
	s_barrier
	s_add_i32 s67, 0, 0x18000
	v_add_u32_e32 v1, s67, v241
	s_add_i32 s72, 0, 0x1c000
	ds_read_b128 v[38:41], v1
	ds_read_b128 v[46:49], v1 offset:1024
	ds_read_b128 v[66:69], v1 offset:2048
	ds_read_b128 v[70:73], v1 offset:3072
	v_add_u32_e32 v1, s72, v241
	ds_read_b128 v[130:133], v1
	ds_read_b128 v[134:137], v1 offset:1024
	ds_read_b128 v[138:141], v1 offset:2048
	ds_read_b128 v[142:145], v1 offset:3072
	s_add_u32 s68, s62, 0x80000
	s_addc_u32 s69, s63, 0
	s_mov_b32 m0, s77
	v_lshl_add_u64 v[90:91], s[68:69], 0, v[184:185]
	ds_read_b128 v[146:149], v245 offset:32768
	ds_read_b128 v[150:153], v245 offset:33792
	ds_read_b128 v[154:157], v245 offset:34816
	ds_read_b128 v[158:161], v245 offset:35840
	ds_read_b128 v[162:165], v245 offset:36864
	ds_read_b128 v[166:169], v245 offset:37888
	ds_read_b128 v[170:173], v245 offset:38912
	ds_read_b128 v[174:177], v245 offset:39936
	global_load_lds_dwordx4 v[90:91], off
	v_lshl_add_u64 v[90:91], s[68:69], 0, v[188:189]
	s_mov_b32 m0, s78
	s_nop 0
	global_load_lds_dwordx4 v[90:91], off
	s_waitcnt vmcnt(8)
	s_waitcnt lgkmcnt(0)
	s_setprio 1
	s_barrier
	s_waitcnt lgkmcnt(0)
	v_mfma_f32_16x16x32_bf16 v[90:93], v[38:41], v[146:149], v[126:129]
	v_mfma_f32_16x16x32_bf16 v[126:129], v[46:49], v[150:153], v[90:93]
	v_mfma_f32_16x16x32_bf16 v[90:93], v[66:69], v[146:149], v[122:125]
	v_mfma_f32_16x16x32_bf16 v[122:125], v[70:73], v[150:153], v[90:93]
	v_mfma_f32_16x16x32_bf16 v[90:93], v[38:41], v[154:157], v[118:121]
	v_mfma_f32_16x16x32_bf16 v[118:121], v[46:49], v[158:161], v[90:93]
	v_mfma_f32_16x16x32_bf16 v[90:93], v[66:69], v[154:157], v[114:117]
	v_mfma_f32_16x16x32_bf16 v[114:117], v[70:73], v[158:161], v[90:93]
	v_mfma_f32_16x16x32_bf16 v[90:93], v[38:41], v[162:165], v[110:113]
	v_mfma_f32_16x16x32_bf16 v[2:5], v[38:41], v[170:173], v[2:5]
	v_mfma_f32_16x16x32_bf16 v[110:113], v[46:49], v[166:169], v[90:93]
	v_mfma_f32_16x16x32_bf16 v[90:93], v[66:69], v[162:165], v[106:109]
	v_mfma_f32_16x16x32_bf16 v[102:105], v[46:49], v[174:177], v[2:5]
	v_mfma_f32_16x16x32_bf16 v[2:5], v[66:69], v[170:173], v[6:9]
	v_mfma_f32_16x16x32_bf16 v[106:109], v[70:73], v[166:169], v[90:93]
	v_mfma_f32_16x16x32_bf16 v[98:101], v[70:73], v[174:177], v[2:5]
	s_setprio 0
	s_setprio 1
	v_mfma_f32_16x16x32_bf16 v[2:5], v[130:133], v[146:149], v[10:13]
	v_mfma_f32_16x16x32_bf16 v[94:97], v[134:137], v[150:153], v[2:5]
	v_mfma_f32_16x16x32_bf16 v[2:5], v[138:141], v[146:149], v[18:21]
	v_mfma_f32_16x16x32_bf16 v[90:93], v[142:145], v[150:153], v[2:5]
	v_mfma_f32_16x16x32_bf16 v[2:5], v[130:133], v[154:157], v[86:89]
	v_mfma_f32_16x16x32_bf16 v[86:89], v[134:137], v[158:161], v[2:5]
	v_mfma_f32_16x16x32_bf16 v[2:5], v[138:141], v[154:157], v[82:85]
	v_mfma_f32_16x16x32_bf16 v[82:85], v[142:145], v[158:161], v[2:5]
	v_mfma_f32_16x16x32_bf16 v[2:5], v[130:133], v[162:165], v[78:81]
	v_mfma_f32_16x16x32_bf16 v[78:81], v[134:137], v[166:169], v[2:5]
	v_mfma_f32_16x16x32_bf16 v[2:5], v[138:141], v[162:165], v[74:77]
	v_mfma_f32_16x16x32_bf16 v[74:77], v[142:145], v[166:169], v[2:5]
	v_mfma_f32_16x16x32_bf16 v[2:5], v[130:133], v[170:173], v[26:29]
	v_mfma_f32_16x16x32_bf16 v[70:73], v[134:137], v[174:177], v[2:5]
	v_mfma_f32_16x16x32_bf16 v[2:5], v[138:141], v[170:173], v[30:33]
	v_mfma_f32_16x16x32_bf16 v[66:69], v[142:145], v[174:177], v[2:5]
	s_setprio 0
	s_barrier
	s_add_i32 s67, s67, s70
	v_lshl_add_u64 v[26:27], v[178:179], 0, s[38:39]
	s_mov_b32 m0, s67
	s_nop 1
	ds_read_b128 v[2:5], v246 offset:49152
	ds_read_b128 v[6:9], v246 offset:50176
	ds_read_b128 v[10:13], v246 offset:51200
	ds_read_b128 v[18:21], v246 offset:52224
	global_load_lds_dwordx4 v[26:27], off
	s_add_i32 m0, s67, 0x2000
	s_add_u32 s62, s62, 0x40080
	v_lshl_add_u64 v[26:27], v[180:181], 0, s[38:39]
	s_addc_u32 s63, s63, 0
	s_add_i32 s67, s72, s70
	global_load_lds_dwordx4 v[26:27], off
	v_lshl_add_u64 v[26:27], s[62:63], 0, v[184:185]
	s_mov_b32 m0, s67
	s_nop 0
	global_load_lds_dwordx4 v[26:27], off
	v_lshl_add_u64 v[26:27], s[62:63], 0, v[188:189]
	s_add_i32 m0, s67, 0x2000
	s_nop 0
	global_load_lds_dwordx4 v[26:27], off
	v_lshl_add_u64 v[26:27], v[198:199], 0, s[38:39]
	s_mov_b32 m0, s79
	s_nop 0
	global_load_lds_dwordx4 v[26:27], off
	v_lshl_add_u64 v[26:27], v[200:201], 0, s[38:39]
	s_mov_b32 m0, s80
	s_nop 0
	global_load_lds_dwordx4 v[26:27], off
	s_waitcnt vmcnt(8)
	s_waitcnt lgkmcnt(0)
	s_setprio 1
	s_barrier
	s_waitcnt lgkmcnt(0)
	v_mfma_f32_16x16x32_bf16 v[26:29], v[2:5], v[146:149], v[62:65]
	v_mfma_f32_16x16x32_bf16 v[62:65], v[6:9], v[150:153], v[26:29]
	v_mfma_f32_16x16x32_bf16 v[26:29], v[10:13], v[146:149], v[58:61]
	v_mfma_f32_16x16x32_bf16 v[58:61], v[18:21], v[150:153], v[26:29]
	v_mfma_f32_16x16x32_bf16 v[26:29], v[2:5], v[154:157], v[54:57]
	v_mfma_f32_16x16x32_bf16 v[54:57], v[6:9], v[158:161], v[26:29]
	v_mfma_f32_16x16x32_bf16 v[26:29], v[10:13], v[154:157], v[50:53]
	v_mfma_f32_16x16x32_bf16 v[50:53], v[18:21], v[158:161], v[26:29]
	v_mfma_f32_16x16x32_bf16 v[26:29], v[2:5], v[162:165], v[42:45]
	v_mfma_f32_16x16x32_bf16 v[2:5], v[2:5], v[170:173], v[22:25]
	v_mfma_f32_16x16x32_bf16 v[42:45], v[6:9], v[166:169], v[26:29]
	v_mfma_f32_16x16x32_bf16 v[26:29], v[10:13], v[162:165], v[34:37]
	v_mfma_f32_16x16x32_bf16 v[22:25], v[6:9], v[174:177], v[2:5]
	v_mfma_f32_16x16x32_bf16 v[2:5], v[10:13], v[170:173], v[14:17]
	v_mfma_f32_16x16x32_bf16 v[34:37], v[18:21], v[166:169], v[26:29]
	v_mfma_f32_16x16x32_bf16 v[14:17], v[18:21], v[174:177], v[2:5]
	s_setprio 0
	s_barrier
	s_add_i32 s66, s66, 2
	s_add_u32 s64, s64, 0x100
	s_addc_u32 s65, s65, 0
	s_add_u32 s60, s60, 0x100
	s_addc_u32 s61, s61, 0
	s_cmp_gt_u32 s66, 13
	s_cbranch_scc0 .LBB0_1749
	s_branch .LBB0_1801

.LBB0_1752:
	ds_read_b128 v[130:133], v243
	ds_read_b128 v[134:137], v243 offset:1024
	ds_read_b128 v[138:141], v243 offset:2048
	ds_read_b128 v[142:145], v243 offset:3072
	ds_read_b128 v[146:149], v244
	ds_read_b128 v[150:153], v244 offset:1024
	ds_read_b128 v[154:157], v244 offset:2048
	ds_read_b128 v[158:161], v244 offset:3072
	s_add_u32 s66, s8, 0xfffc0080
	s_addc_u32 s67, s9, -1
	s_cmp_eq_u32 s72, 12
	s_cselect_b64 s[64:65], -1, 0
	s_and_b64 s[62:63], s[64:65], exec
	s_cselect_b32 s63, s49, s55
	s_cselect_b32 s62, s52, s53
	s_cselect_b32 s67, s3, s67
	s_cselect_b32 s66, s5, s66
	v_lshl_add_u64 v[210:211], s[8:9], 0, v[196:197]
	s_add_i32 m0, s71, 0xc000
	ds_read_b128 v[162:165], v245
	ds_read_b128 v[166:169], v245 offset:1024
	ds_read_b128 v[170:173], v245 offset:2048
	ds_read_b128 v[174:177], v245 offset:3072
	ds_read_b128 v[178:181], v245 offset:4096
	ds_read_b128 v[198:201], v245 offset:5120
	ds_read_b128 v[202:205], v245 offset:6144
	ds_read_b128 v[206:209], v245 offset:7168
	global_load_lds_dwordx4 v[210:211], off
	v_lshl_add_u64 v[210:211], s[8:9], 0, v[186:187]
	s_add_i32 m0, s71, 0xe000
	s_nop 0
	global_load_lds_dwordx4 v[210:211], off
	s_waitcnt vmcnt(8)
	s_waitcnt lgkmcnt(0)
	s_setprio 1
	s_barrier
	s_waitcnt lgkmcnt(0)
	v_mfma_f32_16x16x32_bf16 v[126:129], v[130:133], v[162:165], v[126:129]
	v_mfma_f32_16x16x32_bf16 v[122:125], v[138:141], v[162:165], v[122:125]
	v_mfma_f32_16x16x32_bf16 v[118:121], v[130:133], v[170:173], v[118:121]
	v_mfma_f32_16x16x32_bf16 v[114:117], v[138:141], v[170:173], v[114:117]
	v_mfma_f32_16x16x32_bf16 v[110:113], v[130:133], v[178:181], v[110:113]
	v_mfma_f32_16x16x32_bf16 v[106:109], v[138:141], v[178:181], v[106:109]
	v_mfma_f32_16x16x32_bf16 v[102:105], v[130:133], v[202:205], v[102:105]
	v_mfma_f32_16x16x32_bf16 v[98:101], v[138:141], v[202:205], v[98:101]
	v_mfma_f32_16x16x32_bf16 v[126:129], v[134:137], v[166:169], v[126:129]
	v_mfma_f32_16x16x32_bf16 v[122:125], v[142:145], v[166:169], v[122:125]
	v_mfma_f32_16x16x32_bf16 v[118:121], v[134:137], v[174:177], v[118:121]
	v_mfma_f32_16x16x32_bf16 v[114:117], v[142:145], v[174:177], v[114:117]
	v_mfma_f32_16x16x32_bf16 v[110:113], v[134:137], v[198:201], v[110:113]
	v_mfma_f32_16x16x32_bf16 v[106:109], v[142:145], v[198:201], v[106:109]
	v_mfma_f32_16x16x32_bf16 v[102:105], v[134:137], v[206:209], v[102:105]
	v_mfma_f32_16x16x32_bf16 v[98:101], v[142:145], v[206:209], v[98:101]
	s_setprio 0
	s_setprio 1
	v_mfma_f32_16x16x32_bf16 v[94:97], v[146:149], v[162:165], v[94:97]
	v_mfma_f32_16x16x32_bf16 v[90:93], v[154:157], v[162:165], v[90:93]
	v_mfma_f32_16x16x32_bf16 v[86:89], v[146:149], v[170:173], v[86:89]
	v_mfma_f32_16x16x32_bf16 v[82:85], v[154:157], v[170:173], v[82:85]
	v_mfma_f32_16x16x32_bf16 v[78:81], v[146:149], v[178:181], v[78:81]
	v_mfma_f32_16x16x32_bf16 v[74:77], v[154:157], v[178:181], v[74:77]
	v_mfma_f32_16x16x32_bf16 v[70:73], v[146:149], v[202:205], v[70:73]
	v_mfma_f32_16x16x32_bf16 v[66:69], v[154:157], v[202:205], v[66:69]
	v_mfma_f32_16x16x32_bf16 v[94:97], v[150:153], v[166:169], v[94:97]
	v_mfma_f32_16x16x32_bf16 v[90:93], v[158:161], v[166:169], v[90:93]
	v_mfma_f32_16x16x32_bf16 v[86:89], v[150:153], v[174:177], v[86:89]
	v_mfma_f32_16x16x32_bf16 v[82:85], v[158:161], v[174:177], v[82:85]
	v_mfma_f32_16x16x32_bf16 v[78:81], v[150:153], v[198:201], v[78:81]
	v_mfma_f32_16x16x32_bf16 v[74:77], v[158:161], v[198:201], v[74:77]
	v_mfma_f32_16x16x32_bf16 v[70:73], v[150:153], v[206:209], v[70:73]
	v_mfma_f32_16x16x32_bf16 v[66:69], v[158:161], v[206:209], v[66:69]
	s_setprio 0
	s_barrier
	s_add_i32 s73, s74, s70
	v_lshl_add_u64 v[210:211], s[62:63], 0, v[184:185]
	s_mov_b32 m0, s73
	ds_read_b128 v[162:165], v245 offset:16384
	ds_read_b128 v[166:169], v245 offset:17408
	ds_read_b128 v[170:173], v245 offset:18432
	ds_read_b128 v[174:177], v245 offset:19456
	ds_read_b128 v[178:181], v245 offset:20480
	ds_read_b128 v[198:201], v245 offset:21504
	ds_read_b128 v[202:205], v245 offset:22528
	ds_read_b128 v[206:209], v245 offset:23552
	global_load_lds_dwordx4 v[210:211], off
	s_add_i32 m0, s73, 0x2000
	s_add_u32 vcc_lo, s62, 0x40000
	v_lshl_add_u64 v[212:213], s[62:63], 0, v[188:189]
	s_addc_u32 vcc_hi, s63, 0
	s_add_i32 s73, s75, s70
	global_load_lds_dwordx4 v[212:213], off
	v_lshl_add_u64 v[214:215], vcc, 0, v[184:185]
	s_mov_b32 m0, s73
	v_lshl_add_u64 v[216:217], s[66:67], 0, v[186:187]
	global_load_lds_dwordx4 v[214:215], off
	v_lshl_add_u64 v[214:215], vcc, 0, v[188:189]
	s_add_i32 m0, s73, 0x2000
	s_nop 0
	global_load_lds_dwordx4 v[214:215], off
	v_lshl_add_u64 v[214:215], s[66:67], 0, v[182:183]
	s_mov_b32 m0, s71
	s_nop 0
	global_load_lds_dwordx4 v[214:215], off
	s_mov_b32 m0, s76
	s_nop 0
	global_load_lds_dwordx4 v[216:217], off
	s_waitcnt vmcnt(8)
	s_waitcnt lgkmcnt(0)
	s_setprio 1
	s_barrier
	s_waitcnt lgkmcnt(0)
	v_mfma_f32_16x16x32_bf16 v[62:65], v[130:133], v[162:165], v[62:65]
	v_mfma_f32_16x16x32_bf16 v[58:61], v[138:141], v[162:165], v[58:61]
	v_mfma_f32_16x16x32_bf16 v[54:57], v[130:133], v[170:173], v[54:57]
	v_mfma_f32_16x16x32_bf16 v[50:53], v[138:141], v[170:173], v[50:53]
	v_mfma_f32_16x16x32_bf16 v[42:45], v[130:133], v[178:181], v[42:45]
	v_mfma_f32_16x16x32_bf16 v[34:37], v[138:141], v[178:181], v[34:37]
	v_mfma_f32_16x16x32_bf16 v[22:25], v[130:133], v[202:205], v[22:25]
	v_mfma_f32_16x16x32_bf16 v[14:17], v[138:141], v[202:205], v[14:17]
	v_mfma_f32_16x16x32_bf16 v[62:65], v[134:137], v[166:169], v[62:65]
	v_mfma_f32_16x16x32_bf16 v[58:61], v[142:145], v[166:169], v[58:61]
	v_mfma_f32_16x16x32_bf16 v[54:57], v[134:137], v[174:177], v[54:57]
	v_mfma_f32_16x16x32_bf16 v[50:53], v[142:145], v[174:177], v[50:53]
	v_mfma_f32_16x16x32_bf16 v[42:45], v[134:137], v[198:201], v[42:45]
	v_mfma_f32_16x16x32_bf16 v[34:37], v[142:145], v[198:201], v[34:37]
	v_mfma_f32_16x16x32_bf16 v[22:25], v[134:137], v[206:209], v[22:25]
	v_mfma_f32_16x16x32_bf16 v[14:17], v[142:145], v[206:209], v[14:17]
	s_setprio 0
	s_setprio 1
	v_mfma_f32_16x16x32_bf16 v[46:49], v[146:149], v[162:165], v[46:49]
	v_mfma_f32_16x16x32_bf16 v[38:41], v[154:157], v[162:165], v[38:41]
	v_mfma_f32_16x16x32_bf16 v[30:33], v[146:149], v[170:173], v[30:33]
	v_mfma_f32_16x16x32_bf16 v[26:29], v[154:157], v[170:173], v[26:29]
	v_mfma_f32_16x16x32_bf16 v[18:21], v[146:149], v[178:181], v[18:21]
	v_mfma_f32_16x16x32_bf16 v[10:13], v[154:157], v[178:181], v[10:13]
	v_mfma_f32_16x16x32_bf16 v[6:9], v[146:149], v[202:205], v[6:9]
	v_mfma_f32_16x16x32_bf16 v[2:5], v[154:157], v[202:205], v[2:5]
	v_mfma_f32_16x16x32_bf16 v[46:49], v[150:153], v[166:169], v[46:49]
	v_mfma_f32_16x16x32_bf16 v[38:41], v[158:161], v[166:169], v[38:41]
	v_mfma_f32_16x16x32_bf16 v[30:33], v[150:153], v[174:177], v[30:33]
	v_mfma_f32_16x16x32_bf16 v[26:29], v[158:161], v[174:177], v[26:29]
	v_mfma_f32_16x16x32_bf16 v[18:21], v[150:153], v[198:201], v[18:21]
	v_mfma_f32_16x16x32_bf16 v[10:13], v[158:161], v[198:201], v[10:13]
	v_mfma_f32_16x16x32_bf16 v[6:9], v[150:153], v[206:209], v[6:9]
	v_mfma_f32_16x16x32_bf16 v[2:5], v[158:161], v[206:209], v[2:5]
	s_setprio 0
	s_barrier
	s_add_i32 s73, 0, 0x18000
	v_add_u32_e32 v1, s73, v241
	s_add_i32 s96, 0, 0x1c000
	ds_read_b128 v[130:133], v1
	ds_read_b128 v[134:137], v1 offset:1024
	ds_read_b128 v[138:141], v1 offset:2048
	ds_read_b128 v[142:145], v1 offset:3072
	v_add_u32_e32 v1, s96, v241
	ds_read_b128 v[146:149], v1
	ds_read_b128 v[150:153], v1 offset:1024
	ds_read_b128 v[154:157], v1 offset:2048
	ds_read_b128 v[158:161], v1 offset:3072
	s_and_b64 s[64:65], s[50:51], s[64:65]
	s_and_b64 vcc, s[64:65], s[60:61]
	s_add_u32 s66, s66, 0x40000
	s_addc_u32 s67, s67, 0
	s_and_b64 s[64:65], vcc, exec
	s_mov_b32 m0, s77
	v_cndmask_b32_e32 v1, v182, v184, vcc
	s_cselect_b32 s65, s69, s67
	s_cselect_b32 s64, s68, s66
	ds_read_b128 v[162:165], v245 offset:32768
	ds_read_b128 v[166:169], v245 offset:33792
	ds_read_b128 v[170:173], v245 offset:34816
	ds_read_b128 v[174:177], v245 offset:35840
	ds_read_b128 v[178:181], v245 offset:36864
	ds_read_b128 v[198:201], v245 offset:37888
	ds_read_b128 v[202:205], v245 offset:38912
	ds_read_b128 v[206:209], v245 offset:39936
	v_cndmask_b32_e32 v218, v186, v188, vcc
	global_load_lds_dwordx4 v1, s[64:65]
	s_mov_b32 m0, s78
	s_nop 0
	global_load_lds_dwordx4 v218, s[64:65]
	s_waitcnt vmcnt(8)
	s_waitcnt lgkmcnt(0)
	s_setprio 1
	s_barrier
	s_waitcnt lgkmcnt(0)
	v_mfma_f32_16x16x32_bf16 v[126:129], v[130:133], v[162:165], v[126:129]
	v_mfma_f32_16x16x32_bf16 v[122:125], v[138:141], v[162:165], v[122:125]
	v_mfma_f32_16x16x32_bf16 v[118:121], v[130:133], v[170:173], v[118:121]
	v_mfma_f32_16x16x32_bf16 v[114:117], v[138:141], v[170:173], v[114:117]
	v_mfma_f32_16x16x32_bf16 v[110:113], v[130:133], v[178:181], v[110:113]
	v_mfma_f32_16x16x32_bf16 v[106:109], v[138:141], v[178:181], v[106:109]
	v_mfma_f32_16x16x32_bf16 v[102:105], v[130:133], v[202:205], v[102:105]
	v_mfma_f32_16x16x32_bf16 v[98:101], v[138:141], v[202:205], v[98:101]
	v_mfma_f32_16x16x32_bf16 v[126:129], v[134:137], v[166:169], v[126:129]
	v_mfma_f32_16x16x32_bf16 v[122:125], v[142:145], v[166:169], v[122:125]
	v_mfma_f32_16x16x32_bf16 v[118:121], v[134:137], v[174:177], v[118:121]
	v_mfma_f32_16x16x32_bf16 v[114:117], v[142:145], v[174:177], v[114:117]
	v_mfma_f32_16x16x32_bf16 v[110:113], v[134:137], v[198:201], v[110:113]
	v_mfma_f32_16x16x32_bf16 v[106:109], v[142:145], v[198:201], v[106:109]
	v_mfma_f32_16x16x32_bf16 v[102:105], v[134:137], v[206:209], v[102:105]
	v_mfma_f32_16x16x32_bf16 v[98:101], v[142:145], v[206:209], v[98:101]
	s_setprio 0
	s_setprio 1
	v_mfma_f32_16x16x32_bf16 v[94:97], v[146:149], v[162:165], v[94:97]
	v_mfma_f32_16x16x32_bf16 v[90:93], v[154:157], v[162:165], v[90:93]
	v_mfma_f32_16x16x32_bf16 v[86:89], v[146:149], v[170:173], v[86:89]
	v_mfma_f32_16x16x32_bf16 v[82:85], v[154:157], v[170:173], v[82:85]
	v_mfma_f32_16x16x32_bf16 v[78:81], v[146:149], v[178:181], v[78:81]
	v_mfma_f32_16x16x32_bf16 v[74:77], v[154:157], v[178:181], v[74:77]
	v_mfma_f32_16x16x32_bf16 v[70:73], v[146:149], v[202:205], v[70:73]
	v_mfma_f32_16x16x32_bf16 v[66:69], v[154:157], v[202:205], v[66:69]
	v_mfma_f32_16x16x32_bf16 v[94:97], v[150:153], v[166:169], v[94:97]
	v_mfma_f32_16x16x32_bf16 v[90:93], v[158:161], v[166:169], v[90:93]
	v_mfma_f32_16x16x32_bf16 v[86:89], v[150:153], v[174:177], v[86:89]
	v_mfma_f32_16x16x32_bf16 v[82:85], v[158:161], v[174:177], v[82:85]
	v_mfma_f32_16x16x32_bf16 v[78:81], v[150:153], v[198:201], v[78:81]
	v_mfma_f32_16x16x32_bf16 v[74:77], v[158:161], v[198:201], v[74:77]
	v_mfma_f32_16x16x32_bf16 v[70:73], v[150:153], v[206:209], v[70:73]
	v_mfma_f32_16x16x32_bf16 v[66:69], v[158:161], v[206:209], v[66:69]
	s_setprio 0
	s_barrier
	s_add_i32 s64, s73, s70
	v_lshl_add_u64 v[210:211], v[210:211], 0, s[38:39]
	s_mov_b32 m0, s64
	ds_read_b128 v[162:165], v245 offset:49152
	ds_read_b128 v[166:169], v245 offset:50176
	ds_read_b128 v[170:173], v245 offset:51200
	ds_read_b128 v[174:177], v245 offset:52224
	ds_read_b128 v[178:181], v245 offset:53248
	ds_read_b128 v[198:201], v245 offset:54272
	ds_read_b128 v[202:205], v245 offset:55296
	ds_read_b128 v[206:209], v245 offset:56320
	global_load_lds_dwordx4 v[210:211], off
	s_add_i32 m0, s64, 0x2000
	s_add_u32 s62, s62, 0x40080
	v_lshl_add_u64 v[210:211], v[212:213], 0, s[38:39]
	s_addc_u32 s63, s63, 0
	s_add_i32 s64, s96, s70
	global_load_lds_dwordx4 v[210:211], off
	v_lshl_add_u64 v[210:211], s[62:63], 0, v[184:185]
	s_mov_b32 m0, s64
	s_nop 0
	global_load_lds_dwordx4 v[210:211], off
	v_lshl_add_u64 v[210:211], s[62:63], 0, v[188:189]
	s_add_i32 m0, s64, 0x2000
	s_nop 0
	global_load_lds_dwordx4 v[210:211], off
	v_lshl_add_u64 v[210:211], v[214:215], 0, s[38:39]
	s_mov_b32 m0, s79
	s_nop 0
	global_load_lds_dwordx4 v[210:211], off
	v_lshl_add_u64 v[210:211], v[216:217], 0, s[38:39]
	s_mov_b32 m0, s80
	s_nop 0
	global_load_lds_dwordx4 v[210:211], off
	s_waitcnt vmcnt(8)
	s_waitcnt lgkmcnt(0)
	s_setprio 1
	s_barrier
	s_waitcnt lgkmcnt(0)
	v_mfma_f32_16x16x32_bf16 v[62:65], v[130:133], v[162:165], v[62:65]
	v_mfma_f32_16x16x32_bf16 v[58:61], v[138:141], v[162:165], v[58:61]
	v_mfma_f32_16x16x32_bf16 v[54:57], v[130:133], v[170:173], v[54:57]
	v_mfma_f32_16x16x32_bf16 v[50:53], v[138:141], v[170:173], v[50:53]
	v_mfma_f32_16x16x32_bf16 v[42:45], v[130:133], v[178:181], v[42:45]
	v_mfma_f32_16x16x32_bf16 v[34:37], v[138:141], v[178:181], v[34:37]
	v_mfma_f32_16x16x32_bf16 v[22:25], v[130:133], v[202:205], v[22:25]
	v_mfma_f32_16x16x32_bf16 v[14:17], v[138:141], v[202:205], v[14:17]
	v_mfma_f32_16x16x32_bf16 v[62:65], v[134:137], v[166:169], v[62:65]
	v_mfma_f32_16x16x32_bf16 v[58:61], v[142:145], v[166:169], v[58:61]
	v_mfma_f32_16x16x32_bf16 v[54:57], v[134:137], v[174:177], v[54:57]
	v_mfma_f32_16x16x32_bf16 v[50:53], v[142:145], v[174:177], v[50:53]
	v_mfma_f32_16x16x32_bf16 v[42:45], v[134:137], v[198:201], v[42:45]
	v_mfma_f32_16x16x32_bf16 v[34:37], v[142:145], v[198:201], v[34:37]
	v_mfma_f32_16x16x32_bf16 v[22:25], v[134:137], v[206:209], v[22:25]
	v_mfma_f32_16x16x32_bf16 v[14:17], v[142:145], v[206:209], v[14:17]
	s_setprio 0
	s_setprio 1
	v_mfma_f32_16x16x32_bf16 v[46:49], v[146:149], v[162:165], v[46:49]
	v_mfma_f32_16x16x32_bf16 v[38:41], v[154:157], v[162:165], v[38:41]
	v_mfma_f32_16x16x32_bf16 v[30:33], v[146:149], v[170:173], v[30:33]
	v_mfma_f32_16x16x32_bf16 v[26:29], v[154:157], v[170:173], v[26:29]
	v_mfma_f32_16x16x32_bf16 v[18:21], v[146:149], v[178:181], v[18:21]
	v_mfma_f32_16x16x32_bf16 v[10:13], v[154:157], v[178:181], v[10:13]
	v_mfma_f32_16x16x32_bf16 v[6:9], v[146:149], v[202:205], v[6:9]
	v_mfma_f32_16x16x32_bf16 v[2:5], v[154:157], v[202:205], v[2:5]
	v_mfma_f32_16x16x32_bf16 v[46:49], v[150:153], v[166:169], v[46:49]
	v_mfma_f32_16x16x32_bf16 v[38:41], v[158:161], v[166:169], v[38:41]
	v_mfma_f32_16x16x32_bf16 v[30:33], v[150:153], v[174:177], v[30:33]
	v_mfma_f32_16x16x32_bf16 v[26:29], v[158:161], v[174:177], v[26:29]
	v_mfma_f32_16x16x32_bf16 v[18:21], v[150:153], v[198:201], v[18:21]
	v_mfma_f32_16x16x32_bf16 v[10:13], v[158:161], v[198:201], v[10:13]
	v_mfma_f32_16x16x32_bf16 v[6:9], v[150:153], v[206:209], v[6:9]
	v_mfma_f32_16x16x32_bf16 v[2:5], v[158:161], v[206:209], v[2:5]
	s_setprio 0
	s_barrier
	s_add_i32 s72, s72, 2
	s_add_u32 s8, s8, 0x100
	s_addc_u32 s9, s9, 0
	s_add_u32 s53, s53, 0x100
	s_addc_u32 s55, s55, 0
	s_cmp_gt_u32 s72, 13
	s_cbranch_scc0 .LBB0_1752
	s_andn2_b64 vcc, exec, s[40:41]
	s_cbranch_vccnz .LBB0_1755

.LBB0_1882:
	ds_read_b128 v[128:131], v203
	ds_read_b128 v[132:135], v203 offset:1024
	ds_read_b128 v[136:139], v203 offset:2048
	ds_read_b128 v[140:143], v203 offset:3072
	ds_read_b128 v[144:147], v204
	ds_read_b128 v[148:151], v204 offset:1024
	ds_read_b128 v[152:155], v204 offset:2048
	ds_read_b128 v[172:175], v204 offset:3072
	s_add_u32 s2, s22, 0x100
	s_addc_u32 s3, s23, 0
	s_cmp_eq_u32 s58, 40
	s_cselect_b32 s29, s21, s3
	s_cselect_b32 s28, s20, s2
	s_cselect_b32 s25, s5, s57
	s_cselect_b32 s24, s4, s56
	v_lshl_add_u64 v[214:215], s[22:23], 0, v[164:165]
	s_add_i32 m0, s39, 0xc000
	ds_read_b128 v[176:179], v205
	ds_read_b128 v[180:183], v205 offset:1024
	ds_read_b128 v[184:187], v205 offset:2048
	ds_read_b128 v[188:191], v205 offset:3072
	ds_read_b128 v[192:195], v205 offset:4096
	ds_read_b128 v[196:199], v205 offset:5120
	ds_read_b128 v[206:209], v205 offset:6144
	ds_read_b128 v[210:213], v205 offset:7168
	global_load_lds_dwordx4 v[214:215], off
	v_lshl_add_u64 v[214:215], s[22:23], 0, v[166:167]
	s_add_i32 m0, s39, 0xe000
	s_nop 0
	global_load_lds_dwordx4 v[214:215], off
	s_waitcnt vmcnt(8)
	s_waitcnt lgkmcnt(0)
	s_setprio 1
	s_barrier
	s_waitcnt lgkmcnt(0)
	v_mfma_f32_16x16x32_bf16 v[124:127], v[128:131], v[176:179], v[124:127]
	v_mfma_f32_16x16x32_bf16 v[120:123], v[136:139], v[176:179], v[120:123]
	v_mfma_f32_16x16x32_bf16 v[108:111], v[128:131], v[184:187], v[108:111]
	v_mfma_f32_16x16x32_bf16 v[104:107], v[136:139], v[184:187], v[104:107]
	v_mfma_f32_16x16x32_bf16 v[92:95], v[128:131], v[192:195], v[92:95]
	v_mfma_f32_16x16x32_bf16 v[88:91], v[136:139], v[192:195], v[88:91]
	v_mfma_f32_16x16x32_bf16 v[76:79], v[128:131], v[206:209], v[76:79]
	v_mfma_f32_16x16x32_bf16 v[72:75], v[136:139], v[206:209], v[72:75]
	v_mfma_f32_16x16x32_bf16 v[124:127], v[132:135], v[180:183], v[124:127]
	v_mfma_f32_16x16x32_bf16 v[120:123], v[140:143], v[180:183], v[120:123]
	v_mfma_f32_16x16x32_bf16 v[108:111], v[132:135], v[188:191], v[108:111]
	v_mfma_f32_16x16x32_bf16 v[104:107], v[140:143], v[188:191], v[104:107]
	v_mfma_f32_16x16x32_bf16 v[92:95], v[132:135], v[196:199], v[92:95]
	v_mfma_f32_16x16x32_bf16 v[88:91], v[140:143], v[196:199], v[88:91]
	v_mfma_f32_16x16x32_bf16 v[76:79], v[132:135], v[210:213], v[76:79]
	v_mfma_f32_16x16x32_bf16 v[72:75], v[140:143], v[210:213], v[72:75]
	s_setprio 0
	s_setprio 1
	v_mfma_f32_16x16x32_bf16 v[116:119], v[144:147], v[176:179], v[116:119]
	v_mfma_f32_16x16x32_bf16 v[112:115], v[152:155], v[176:179], v[112:115]
	v_mfma_f32_16x16x32_bf16 v[100:103], v[144:147], v[184:187], v[100:103]
	v_mfma_f32_16x16x32_bf16 v[96:99], v[152:155], v[184:187], v[96:99]
	v_mfma_f32_16x16x32_bf16 v[84:87], v[144:147], v[192:195], v[84:87]
	v_mfma_f32_16x16x32_bf16 v[80:83], v[152:155], v[192:195], v[80:83]
	v_mfma_f32_16x16x32_bf16 v[68:71], v[144:147], v[206:209], v[68:71]
	v_mfma_f32_16x16x32_bf16 v[64:67], v[152:155], v[206:209], v[64:67]
	v_mfma_f32_16x16x32_bf16 v[116:119], v[148:151], v[180:183], v[116:119]
	v_mfma_f32_16x16x32_bf16 v[112:115], v[172:175], v[180:183], v[112:115]
	v_mfma_f32_16x16x32_bf16 v[100:103], v[148:151], v[188:191], v[100:103]
	v_mfma_f32_16x16x32_bf16 v[96:99], v[172:175], v[188:191], v[96:99]
	v_mfma_f32_16x16x32_bf16 v[84:87], v[148:151], v[196:199], v[84:87]
	v_mfma_f32_16x16x32_bf16 v[80:83], v[172:175], v[196:199], v[80:83]
	v_mfma_f32_16x16x32_bf16 v[68:71], v[148:151], v[210:213], v[68:71]
	v_mfma_f32_16x16x32_bf16 v[64:67], v[172:175], v[210:213], v[64:67]
	s_setprio 0
	s_barrier
	s_add_i32 s22, s48, s38
	v_lshl_add_u64 v[214:215], s[24:25], 0, v[158:159]
	s_mov_b32 m0, s22
	ds_read_b128 v[176:179], v205 offset:16384
	ds_read_b128 v[180:183], v205 offset:17408
	ds_read_b128 v[184:187], v205 offset:18432
	ds_read_b128 v[188:191], v205 offset:19456
	ds_read_b128 v[192:195], v205 offset:20480
	ds_read_b128 v[196:199], v205 offset:21504
	ds_read_b128 v[206:209], v205 offset:22528
	ds_read_b128 v[210:213], v205 offset:23552
	global_load_lds_dwordx4 v[214:215], off
	s_add_i32 m0, s22, 0x2000
	s_add_u32 s22, s24, 0xb0000
	v_lshl_add_u64 v[216:217], s[24:25], 0, v[162:163]
	s_addc_u32 s23, s25, 0
	s_add_i32 s59, s49, s38
	global_load_lds_dwordx4 v[216:217], off
	v_lshl_add_u64 v[218:219], s[22:23], 0, v[158:159]
	s_mov_b32 m0, s59
	v_lshl_add_u64 v[220:221], s[28:29], 0, v[160:161]
	global_load_lds_dwordx4 v[218:219], off
	v_lshl_add_u64 v[218:219], s[22:23], 0, v[162:163]
	s_add_i32 m0, s59, 0x2000
	s_nop 0
	global_load_lds_dwordx4 v[218:219], off
	v_lshl_add_u64 v[218:219], s[28:29], 0, v[156:157]
	s_mov_b32 m0, s39
	s_nop 0
	global_load_lds_dwordx4 v[218:219], off
	s_mov_b32 m0, s40
	s_nop 0
	global_load_lds_dwordx4 v[220:221], off
	s_waitcnt vmcnt(8)
	s_waitcnt lgkmcnt(0)
	s_setprio 1
	s_barrier
	s_waitcnt lgkmcnt(0)
	v_mfma_f32_16x16x32_bf16 v[60:63], v[128:131], v[176:179], v[60:63]
	v_mfma_f32_16x16x32_bf16 v[56:59], v[136:139], v[176:179], v[56:59]
	v_mfma_f32_16x16x32_bf16 v[44:47], v[128:131], v[184:187], v[44:47]
	v_mfma_f32_16x16x32_bf16 v[40:43], v[136:139], v[184:187], v[40:43]
	v_mfma_f32_16x16x32_bf16 v[28:31], v[128:131], v[192:195], v[28:31]
	v_mfma_f32_16x16x32_bf16 v[24:27], v[136:139], v[192:195], v[24:27]
	v_mfma_f32_16x16x32_bf16 v[12:15], v[128:131], v[206:209], v[12:15]
	v_mfma_f32_16x16x32_bf16 v[8:11], v[136:139], v[206:209], v[8:11]
	v_mfma_f32_16x16x32_bf16 v[60:63], v[132:135], v[180:183], v[60:63]
	v_mfma_f32_16x16x32_bf16 v[56:59], v[140:143], v[180:183], v[56:59]
	v_mfma_f32_16x16x32_bf16 v[44:47], v[132:135], v[188:191], v[44:47]
	v_mfma_f32_16x16x32_bf16 v[40:43], v[140:143], v[188:191], v[40:43]
	v_mfma_f32_16x16x32_bf16 v[28:31], v[132:135], v[196:199], v[28:31]
	v_mfma_f32_16x16x32_bf16 v[24:27], v[140:143], v[196:199], v[24:27]
	v_mfma_f32_16x16x32_bf16 v[12:15], v[132:135], v[210:213], v[12:15]
	v_mfma_f32_16x16x32_bf16 v[8:11], v[140:143], v[210:213], v[8:11]
	s_setprio 0
	s_setprio 1
	v_mfma_f32_16x16x32_bf16 v[52:55], v[144:147], v[176:179], v[52:55]
	v_mfma_f32_16x16x32_bf16 v[48:51], v[152:155], v[176:179], v[48:51]
	v_mfma_f32_16x16x32_bf16 v[36:39], v[144:147], v[184:187], v[36:39]
	v_mfma_f32_16x16x32_bf16 v[32:35], v[152:155], v[184:187], v[32:35]
	v_mfma_f32_16x16x32_bf16 v[20:23], v[144:147], v[192:195], v[20:23]
	v_mfma_f32_16x16x32_bf16 v[16:19], v[152:155], v[192:195], v[16:19]
	v_mfma_f32_16x16x32_bf16 v[4:7], v[144:147], v[206:209], v[4:7]
	v_mfma_f32_16x16x32_bf16 v[0:3], v[152:155], v[206:209], v[0:3]
	v_mfma_f32_16x16x32_bf16 v[52:55], v[148:151], v[180:183], v[52:55]
	v_mfma_f32_16x16x32_bf16 v[48:51], v[172:175], v[180:183], v[48:51]
	v_mfma_f32_16x16x32_bf16 v[36:39], v[148:151], v[188:191], v[36:39]
	v_mfma_f32_16x16x32_bf16 v[32:35], v[172:175], v[188:191], v[32:35]
	v_mfma_f32_16x16x32_bf16 v[20:23], v[148:151], v[196:199], v[20:23]
	v_mfma_f32_16x16x32_bf16 v[16:19], v[172:175], v[196:199], v[16:19]
	v_mfma_f32_16x16x32_bf16 v[4:7], v[148:151], v[210:213], v[4:7]
	v_mfma_f32_16x16x32_bf16 v[0:3], v[172:175], v[210:213], v[0:3]
	s_setprio 0
	s_barrier
	s_add_i32 s59, 0, 0x18000
	s_add_i32 s60, 0, 0x1c000
	v_add_u32_e32 v140, s59, v201
	v_add_u32_e32 v172, s60, v201
	ds_read_b128 v[128:131], v140
	ds_read_b128 v[132:135], v140 offset:1024
	ds_read_b128 v[136:139], v140 offset:2048
	ds_read_b128 v[140:143], v140 offset:3072
	ds_read_b128 v[144:147], v172
	ds_read_b128 v[148:151], v172 offset:1024
	ds_read_b128 v[152:155], v172 offset:2048
	ds_read_b128 v[172:175], v172 offset:3072
	s_add_u32 s22, s28, 0xb0000
	s_addc_u32 s23, s29, 0
	s_mov_b32 m0, s41
	v_lshl_add_u64 v[222:223], s[22:23], 0, v[156:157]
	ds_read_b128 v[176:179], v205 offset:32768
	ds_read_b128 v[180:183], v205 offset:33792
	ds_read_b128 v[184:187], v205 offset:34816
	ds_read_b128 v[188:191], v205 offset:35840
	ds_read_b128 v[192:195], v205 offset:36864
	ds_read_b128 v[196:199], v205 offset:37888
	ds_read_b128 v[206:209], v205 offset:38912
	ds_read_b128 v[210:213], v205 offset:39936
	global_load_lds_dwordx4 v[222:223], off
	v_lshl_add_u64 v[222:223], s[22:23], 0, v[160:161]
	s_mov_b32 m0, s42
	s_nop 0
	global_load_lds_dwordx4 v[222:223], off
	s_waitcnt vmcnt(8)
	s_waitcnt lgkmcnt(0)
	s_setprio 1
	s_barrier
	s_waitcnt lgkmcnt(0)
	v_mfma_f32_16x16x32_bf16 v[124:127], v[128:131], v[176:179], v[124:127]
	v_mfma_f32_16x16x32_bf16 v[120:123], v[136:139], v[176:179], v[120:123]
	v_mfma_f32_16x16x32_bf16 v[108:111], v[128:131], v[184:187], v[108:111]
	v_mfma_f32_16x16x32_bf16 v[104:107], v[136:139], v[184:187], v[104:107]
	v_mfma_f32_16x16x32_bf16 v[92:95], v[128:131], v[192:195], v[92:95]
	v_mfma_f32_16x16x32_bf16 v[88:91], v[136:139], v[192:195], v[88:91]
	v_mfma_f32_16x16x32_bf16 v[76:79], v[128:131], v[206:209], v[76:79]
	v_mfma_f32_16x16x32_bf16 v[72:75], v[136:139], v[206:209], v[72:75]
	v_mfma_f32_16x16x32_bf16 v[124:127], v[132:135], v[180:183], v[124:127]
	v_mfma_f32_16x16x32_bf16 v[120:123], v[140:143], v[180:183], v[120:123]
	v_mfma_f32_16x16x32_bf16 v[108:111], v[132:135], v[188:191], v[108:111]
	v_mfma_f32_16x16x32_bf16 v[104:107], v[140:143], v[188:191], v[104:107]
	v_mfma_f32_16x16x32_bf16 v[92:95], v[132:135], v[196:199], v[92:95]
	v_mfma_f32_16x16x32_bf16 v[88:91], v[140:143], v[196:199], v[88:91]
	v_mfma_f32_16x16x32_bf16 v[76:79], v[132:135], v[210:213], v[76:79]
	v_mfma_f32_16x16x32_bf16 v[72:75], v[140:143], v[210:213], v[72:75]
	s_setprio 0
	s_setprio 1
	v_mfma_f32_16x16x32_bf16 v[116:119], v[144:147], v[176:179], v[116:119]
	v_mfma_f32_16x16x32_bf16 v[112:115], v[152:155], v[176:179], v[112:115]
	v_mfma_f32_16x16x32_bf16 v[100:103], v[144:147], v[184:187], v[100:103]
	v_mfma_f32_16x16x32_bf16 v[96:99], v[152:155], v[184:187], v[96:99]
	v_mfma_f32_16x16x32_bf16 v[84:87], v[144:147], v[192:195], v[84:87]
	v_mfma_f32_16x16x32_bf16 v[80:83], v[152:155], v[192:195], v[80:83]
	v_mfma_f32_16x16x32_bf16 v[68:71], v[144:147], v[206:209], v[68:71]
	v_mfma_f32_16x16x32_bf16 v[64:67], v[152:155], v[206:209], v[64:67]
	v_mfma_f32_16x16x32_bf16 v[116:119], v[148:151], v[180:183], v[116:119]
	v_mfma_f32_16x16x32_bf16 v[112:115], v[172:175], v[180:183], v[112:115]
	v_mfma_f32_16x16x32_bf16 v[100:103], v[148:151], v[188:191], v[100:103]
	v_mfma_f32_16x16x32_bf16 v[96:99], v[172:175], v[188:191], v[96:99]
	v_mfma_f32_16x16x32_bf16 v[84:87], v[148:151], v[196:199], v[84:87]
	v_mfma_f32_16x16x32_bf16 v[80:83], v[172:175], v[196:199], v[80:83]
	v_mfma_f32_16x16x32_bf16 v[68:71], v[148:151], v[210:213], v[68:71]
	v_mfma_f32_16x16x32_bf16 v[64:67], v[172:175], v[210:213], v[64:67]
	s_setprio 0
	s_barrier
	s_add_i32 s22, s59, s38
	v_lshl_add_u64 v[214:215], v[214:215], 0, s[6:7]
	s_mov_b32 m0, s22
	ds_read_b128 v[176:179], v205 offset:49152
	ds_read_b128 v[180:183], v205 offset:50176
	ds_read_b128 v[184:187], v205 offset:51200
	ds_read_b128 v[188:191], v205 offset:52224
	ds_read_b128 v[192:195], v205 offset:53248
	ds_read_b128 v[196:199], v205 offset:54272
	ds_read_b128 v[206:209], v205 offset:55296
	ds_read_b128 v[210:213], v205 offset:56320
	global_load_lds_dwordx4 v[214:215], off
	s_add_i32 m0, s22, 0x2000
	s_add_u32 s22, s24, 0xb0080
	v_lshl_add_u64 v[214:215], v[216:217], 0, s[6:7]
	s_addc_u32 s23, s25, 0
	s_add_i32 s24, s60, s38
	global_load_lds_dwordx4 v[214:215], off
	v_lshl_add_u64 v[214:215], s[22:23], 0, v[158:159]
	s_mov_b32 m0, s24
	s_nop 0
	global_load_lds_dwordx4 v[214:215], off
	v_lshl_add_u64 v[214:215], s[22:23], 0, v[162:163]
	s_add_i32 m0, s24, 0x2000
	s_nop 0
	global_load_lds_dwordx4 v[214:215], off
	v_lshl_add_u64 v[214:215], v[218:219], 0, s[6:7]
	s_mov_b32 m0, s44
	s_nop 0
	global_load_lds_dwordx4 v[214:215], off
	v_lshl_add_u64 v[214:215], v[220:221], 0, s[6:7]
	s_mov_b32 m0, s45
	s_nop 0
	global_load_lds_dwordx4 v[214:215], off
	s_waitcnt vmcnt(8)
	s_waitcnt lgkmcnt(0)
	s_setprio 1
	s_barrier
	s_waitcnt lgkmcnt(0)
	v_mfma_f32_16x16x32_bf16 v[60:63], v[128:131], v[176:179], v[60:63]
	v_mfma_f32_16x16x32_bf16 v[56:59], v[136:139], v[176:179], v[56:59]
	v_mfma_f32_16x16x32_bf16 v[44:47], v[128:131], v[184:187], v[44:47]
	v_mfma_f32_16x16x32_bf16 v[40:43], v[136:139], v[184:187], v[40:43]
	v_mfma_f32_16x16x32_bf16 v[28:31], v[128:131], v[192:195], v[28:31]
	v_mfma_f32_16x16x32_bf16 v[24:27], v[136:139], v[192:195], v[24:27]
	v_mfma_f32_16x16x32_bf16 v[12:15], v[128:131], v[206:209], v[12:15]
	v_mfma_f32_16x16x32_bf16 v[8:11], v[136:139], v[206:209], v[8:11]
	v_mfma_f32_16x16x32_bf16 v[60:63], v[132:135], v[180:183], v[60:63]
	v_mfma_f32_16x16x32_bf16 v[56:59], v[140:143], v[180:183], v[56:59]
	v_mfma_f32_16x16x32_bf16 v[44:47], v[132:135], v[188:191], v[44:47]
	v_mfma_f32_16x16x32_bf16 v[40:43], v[140:143], v[188:191], v[40:43]
	v_mfma_f32_16x16x32_bf16 v[28:31], v[132:135], v[196:199], v[28:31]
	v_mfma_f32_16x16x32_bf16 v[24:27], v[140:143], v[196:199], v[24:27]
	v_mfma_f32_16x16x32_bf16 v[12:15], v[132:135], v[210:213], v[12:15]
	v_mfma_f32_16x16x32_bf16 v[8:11], v[140:143], v[210:213], v[8:11]
	s_setprio 0
	s_setprio 1
	v_mfma_f32_16x16x32_bf16 v[52:55], v[144:147], v[176:179], v[52:55]
	v_mfma_f32_16x16x32_bf16 v[48:51], v[152:155], v[176:179], v[48:51]
	v_mfma_f32_16x16x32_bf16 v[36:39], v[144:147], v[184:187], v[36:39]
	v_mfma_f32_16x16x32_bf16 v[32:35], v[152:155], v[184:187], v[32:35]
	v_mfma_f32_16x16x32_bf16 v[20:23], v[144:147], v[192:195], v[20:23]
	v_mfma_f32_16x16x32_bf16 v[16:19], v[152:155], v[192:195], v[16:19]
	v_mfma_f32_16x16x32_bf16 v[4:7], v[144:147], v[206:209], v[4:7]
	v_mfma_f32_16x16x32_bf16 v[0:3], v[152:155], v[206:209], v[0:3]
	v_mfma_f32_16x16x32_bf16 v[52:55], v[148:151], v[180:183], v[52:55]
	v_mfma_f32_16x16x32_bf16 v[48:51], v[172:175], v[180:183], v[48:51]
	v_mfma_f32_16x16x32_bf16 v[36:39], v[148:151], v[188:191], v[36:39]
	v_mfma_f32_16x16x32_bf16 v[32:35], v[172:175], v[188:191], v[32:35]
	v_mfma_f32_16x16x32_bf16 v[20:23], v[148:151], v[196:199], v[20:23]
	v_mfma_f32_16x16x32_bf16 v[16:19], v[172:175], v[196:199], v[16:19]
	v_mfma_f32_16x16x32_bf16 v[4:7], v[148:151], v[210:213], v[4:7]
	v_mfma_f32_16x16x32_bf16 v[0:3], v[172:175], v[210:213], v[0:3]
	s_setprio 0
	s_barrier
	s_add_i32 s58, s58, 2
	s_add_u32 s56, s56, 0x100
	s_addc_u32 s57, s57, 0
	s_cmp_gt_u32 s58, 41
	s_mov_b64 s[22:23], s[2:3]
	s_cbranch_scc0 .LBB0_1882
	v_lshl_add_u32 v174, s55, 8, v200
	v_lshl_or_b32 v172, s54, 8, v202
	v_ashrrev_i32_e32 v175, 31, v174
	v_ashrrev_i32_e32 v173, 31, v172
	v_lshlrev_b64 v[128:129], 10, v[174:175]
	v_lshl_add_u64 v[198:199], v[128:129], 0, v[172:173]
	v_lshlrev_b64 v[128:129], 1, v[198:199]
	v_lshl_add_u64 v[196:197], s[34:35], 0, v[128:129]
	v_or_b32_e32 v128, 0x100, v128
	v_lshl_add_u64 v[194:195], s[34:35], 0, v[128:129]
	v_or_b32_e32 v128, 16, v174
	v_ashrrev_i32_e32 v129, 31, v128
	v_lshlrev_b64 v[128:129], 10, v[128:129]
	v_lshl_add_u64 v[192:193], v[128:129], 0, v[172:173]
	v_lshlrev_b64 v[128:129], 1, v[192:193]
	v_lshl_add_u64 v[190:191], s[34:35], 0, v[128:129]
	v_or_b32_e32 v128, 0x100, v128
	v_lshl_add_u64 v[188:189], s[34:35], 0, v[128:129]
	v_or_b32_e32 v128, 32, v174
	v_ashrrev_i32_e32 v129, 31, v128
	v_lshlrev_b64 v[128:129], 10, v[128:129]
	v_lshl_add_u64 v[186:187], v[128:129], 0, v[172:173]
	v_lshlrev_b64 v[128:129], 1, v[186:187]
	v_lshl_add_u64 v[184:185], s[34:35], 0, v[128:129]
	v_or_b32_e32 v128, 0x100, v128
	v_lshl_add_u64 v[182:183], s[34:35], 0, v[128:129]
	v_or_b32_e32 v128, 48, v174
	v_ashrrev_i32_e32 v129, 31, v128
	v_lshlrev_b64 v[128:129], 10, v[128:129]
	v_lshl_add_u64 v[180:181], v[128:129], 0, v[172:173]
	v_lshlrev_b64 v[128:129], 1, v[180:181]
	global_load_dwordx4 v[206:209], v[196:197], off
	global_load_dwordx4 v[152:155], v[194:195], off
	v_lshl_add_u64 v[178:179], s[34:35], 0, v[128:129]
	v_or_b32_e32 v128, 0x100, v128
	global_load_dwordx4 v[148:151], v[190:191], off
	global_load_dwordx4 v[144:147], v[188:189], off
	global_load_dwordx4 v[140:143], v[184:185], off
	global_load_dwordx4 v[136:139], v[182:183], off
	v_lshl_add_u64 v[176:177], s[34:35], 0, v[128:129]
	global_load_dwordx4 v[132:135], v[178:179], off
	global_load_dwordx4 v[128:131], v[176:177], off
	v_cndmask_b32_e64 v210, 0, 1, s[8:9]
	v_cmp_ne_u32_e64 s[2:3], 1, v210
	s_andn2_b64 vcc, exec, s[8:9]
	v_lshl_add_u64 v[198:199], v[198:199], 2, s[26:27]
	s_waitcnt vmcnt(0)
	v_lshlrev_b32_e32 v210, 16, v206
	v_and_b32_e32 v211, 0xffff0000, v206
	v_lshlrev_b32_e32 v206, 16, v207
	v_and_b32_e32 v207, 0xffff0000, v207
	v_lshlrev_b32_e32 v212, 16, v208
	v_and_b32_e32 v213, 0xffff0000, v208
	v_lshlrev_b32_e32 v208, 16, v209
	v_and_b32_e32 v209, 0xffff0000, v209
	v_pk_add_f32 v[126:127], v[126:127], v[206:207]
	v_pk_add_f32 v[124:125], v[124:125], v[210:211]
	v_pk_add_f32 v[122:123], v[122:123], v[208:209]
	v_pk_add_f32 v[120:121], v[120:121], v[212:213]
	s_cbranch_vccnz .LBB0_1930
	global_store_dwordx4 v[198:199], v[124:127], off nt
	global_store_dwordx4 v[198:199], v[120:123], off offset:16 nt
	s_cbranch_execnz .LBB0_1886
